# f32 weight reads of the per-call weight copies: nt loads
# speedup vs baseline: 1.0210x; 1.0210x over previous
.LBB0_5:
	s_or_b64 exec, exec, s[0:1]
	s_ashr_i32 s1, s33, 6
	s_lshl_b32 s0, s18, 3
	s_add_i32 s0, s0, s1
	v_writelane_b32 v249, s1, 0
	s_lshl_b32 s1, s1, 14
	s_add_i32 s20, s1, 0
	v_and_b32_e32 v108, 63, v1
	s_cmpk_gt_i32 s0, 0x5ff
	s_waitcnt lgkmcnt(0)
	s_barrier
	s_cbranch_scc1 .LBB0_12
	s_load_dwordx4 s[4:7], s[16:17], 0x8
	s_mul_hi_i32 s1, s0, 0x2aaaaaab
	s_lshr_b32 s2, s1, 31
	s_ashr_i32 s1, s1, 4
	s_add_i32 s1, s1, s2
	s_lshl_b32 s2, s1, 6
	s_waitcnt lgkmcnt(0)
	s_cmp_eq_u64 s[4:5], 0
	s_cbranch_scc1 .LBB0_8
	v_or_b32_e32 v2, s2, v108
	v_ashrrev_i32_e32 v3, 31, v2
	v_lshl_add_u64 v[2:3], v[2:3], 2, s[4:5]
	global_load_dword v4, v[2:3], off nt
	s_branch .LBB0_9

.LBB0_9:
	s_mulk_i32 s1, 0x60
	s_sub_i32 s3, s0, s1
	s_lshl_b32 s0, s3, 5
	s_ashr_i32 s1, s0, 31
	s_lshl_b64 s[4:5], s[0:1], 2
	s_add_u32 s4, s6, s4
	v_lshlrev_b32_e32 v2, 2, v1
	v_lshrrev_b32_e32 v5, 5, v108
	s_addc_u32 s5, s7, s5
	v_and_b32_e32 v2, 0x7c, v2
	v_mov_b32_e32 v3, 0
	v_or_b32_e32 v24, s2, v5
	v_lshl_add_u64 v[6:7], s[4:5], 0, v[2:3]
	s_movk_i32 s1, 0x3000
	v_mad_i64_i32 v[8:9], s[4:5], v24, s1, v[6:7]
	v_or_b32_e32 v10, 2, v24
	v_or_b32_e32 v12, 4, v24
	v_or_b32_e32 v14, 6, v24
	v_or_b32_e32 v16, 8, v24
	v_or_b32_e32 v18, 10, v24
	v_or_b32_e32 v20, 12, v24
	v_or_b32_e32 v22, 14, v24
	v_mad_i64_i32 v[10:11], s[4:5], v10, s1, v[6:7]
	v_mad_i64_i32 v[12:13], s[4:5], v12, s1, v[6:7]
	v_mad_i64_i32 v[14:15], s[4:5], v14, s1, v[6:7]
	v_mad_i64_i32 v[16:17], s[4:5], v16, s1, v[6:7]
	v_mad_i64_i32 v[18:19], s[4:5], v18, s1, v[6:7]
	v_mad_i64_i32 v[20:21], s[4:5], v20, s1, v[6:7]
	v_mad_i64_i32 v[22:23], s[4:5], v22, s1, v[6:7]
	global_load_dword v25, v[8:9], off nt
	global_load_dword v26, v[10:11], off nt
	global_load_dword v27, v[12:13], off nt
	global_load_dword v28, v[14:15], off nt
	global_load_dword v29, v[16:17], off nt
	global_load_dword v30, v[18:19], off nt
	global_load_dword v31, v[20:21], off nt
	global_load_dword v32, v[22:23], off nt
	v_or_b32_e32 v8, 16, v24
	v_mad_i64_i32 v[8:9], s[4:5], v8, s1, v[6:7]
	v_or_b32_e32 v10, 18, v24
	v_or_b32_e32 v12, 20, v24
	v_or_b32_e32 v14, 22, v24
	v_or_b32_e32 v16, 24, v24
	v_or_b32_e32 v18, 26, v24
	v_or_b32_e32 v20, 28, v24
	v_or_b32_e32 v22, 30, v24
	v_mad_i64_i32 v[10:11], s[4:5], v10, s1, v[6:7]
	v_mad_i64_i32 v[12:13], s[4:5], v12, s1, v[6:7]
	v_mad_i64_i32 v[14:15], s[4:5], v14, s1, v[6:7]
	v_mad_i64_i32 v[16:17], s[4:5], v16, s1, v[6:7]
	v_mad_i64_i32 v[18:19], s[4:5], v18, s1, v[6:7]
	v_mad_i64_i32 v[20:21], s[4:5], v20, s1, v[6:7]
	v_mad_i64_i32 v[22:23], s[4:5], v22, s1, v[6:7]
	global_load_dword v33, v[8:9], off nt
	global_load_dword v34, v[10:11], off nt
	global_load_dword v35, v[12:13], off nt
	global_load_dword v36, v[14:15], off nt
	global_load_dword v37, v[16:17], off nt
	global_load_dword v38, v[18:19], off nt
	global_load_dword v39, v[20:21], off nt
	global_load_dword v40, v[22:23], off nt
	v_or_b32_e32 v8, 32, v24
	v_mad_i64_i32 v[8:9], s[4:5], v8, s1, v[6:7]
	v_or_b32_e32 v10, 34, v24
	v_or_b32_e32 v12, 36, v24
	v_or_b32_e32 v14, 38, v24
	v_or_b32_e32 v16, 40, v24
	v_or_b32_e32 v18, 42, v24
	v_or_b32_e32 v20, 44, v24
	v_or_b32_e32 v22, 46, v24
	v_mad_i64_i32 v[10:11], s[4:5], v10, s1, v[6:7]
	v_mad_i64_i32 v[12:13], s[4:5], v12, s1, v[6:7]
	v_mad_i64_i32 v[14:15], s[4:5], v14, s1, v[6:7]
	v_mad_i64_i32 v[16:17], s[4:5], v16, s1, v[6:7]
	v_mad_i64_i32 v[18:19], s[4:5], v18, s1, v[6:7]
	v_mad_i64_i32 v[20:21], s[4:5], v20, s1, v[6:7]
	v_mad_i64_i32 v[22:23], s[4:5], v22, s1, v[6:7]
	global_load_dword v41, v[8:9], off nt
	global_load_dword v42, v[10:11], off nt
	global_load_dword v43, v[12:13], off nt
	global_load_dword v44, v[14:15], off nt
	global_load_dword v45, v[16:17], off nt
	global_load_dword v46, v[18:19], off nt
	global_load_dword v47, v[20:21], off nt
	global_load_dword v48, v[22:23], off nt
	v_or_b32_e32 v8, 48, v24
	v_mad_i64_i32 v[8:9], s[4:5], v8, s1, v[6:7]
	v_or_b32_e32 v10, 50, v24
	v_mad_i64_i32 v[10:11], s[4:5], v10, s1, v[6:7]
	global_load_dword v18, v[8:9], off nt
	global_load_dword v19, v[10:11], off nt
	v_or_b32_e32 v8, 52, v24
	v_mad_i64_i32 v[8:9], s[4:5], v8, s1, v[6:7]
	v_or_b32_e32 v10, 54, v24
	v_or_b32_e32 v12, 56, v24
	v_or_b32_e32 v14, 58, v24
	v_or_b32_e32 v16, 60, v24
	v_or_b32_e32 v20, 62, v24
	v_mad_i64_i32 v[10:11], s[4:5], v10, s1, v[6:7]
	v_mad_i64_i32 v[12:13], s[4:5], v12, s1, v[6:7]
	v_mad_i64_i32 v[14:15], s[4:5], v14, s1, v[6:7]
	v_mad_i64_i32 v[16:17], s[4:5], v16, s1, v[6:7]
	v_mad_i64_i32 v[6:7], s[4:5], v20, s1, v[6:7]
	global_load_dword v23, v[8:9], off nt
	global_load_dword v24, v[10:11], off nt
	global_load_dword v49, v[12:13], off nt
	global_load_dword v50, v[14:15], off nt
	global_load_dword v51, v[16:17], off nt
	global_load_dword v52, v[6:7], off nt
	v_mbcnt_lo_u32_b32 v20, -1, 0
	v_mbcnt_hi_u32_b32 v20, -1, v20
	v_and_or_b32 v20, v20, 64, v5
	v_lshlrev_b32_e32 v20, 2, v20
	s_waitcnt vmcnt(32)
	ds_bpermute_b32 v21, v20, v4
	ds_bpermute_b32 v22, v20, v4 offset:8
	ds_bpermute_b32 v7, v20, v4 offset:16
	ds_bpermute_b32 v8, v20, v4 offset:24
	v_mul_u32_u24_e32 v5, 0x84, v5
	s_waitcnt vmcnt(31) lgkmcnt(3)
	v_mul_f32_e32 v6, v25, v21
	v_add3_u32 v2, s20, v2, v5
	s_waitcnt vmcnt(30) lgkmcnt(2)
	v_mul_f32_e32 v5, v26, v22
	ds_write2_b32 v2, v6, v5 offset1:66
	ds_bpermute_b32 v5, v20, v4 offset:32
	ds_bpermute_b32 v6, v20, v4 offset:40
	s_waitcnt vmcnt(29) lgkmcnt(4)
	v_mul_f32_e32 v7, v27, v7
	s_waitcnt vmcnt(28) lgkmcnt(3)
	v_mul_f32_e32 v8, v28, v8
	ds_write2_b32 v2, v7, v8 offset0:132 offset1:198
	ds_bpermute_b32 v8, v20, v4 offset:48
	ds_bpermute_b32 v9, v20, v4 offset:56
	s_waitcnt vmcnt(27) lgkmcnt(4)
	v_mul_f32_e32 v5, v29, v5
	s_waitcnt vmcnt(26) lgkmcnt(3)
	v_mul_f32_e32 v6, v30, v6
	v_add_u32_e32 v7, 0x400, v2
	ds_write2_b32 v7, v5, v6 offset0:8 offset1:74
	ds_bpermute_b32 v5, v20, v4 offset:64
	ds_bpermute_b32 v6, v20, v4 offset:72
	s_waitcnt vmcnt(25) lgkmcnt(4)
	v_mul_f32_e32 v8, v31, v8
	s_waitcnt vmcnt(24) lgkmcnt(3)
	v_mul_f32_e32 v9, v32, v9
	ds_write2_b32 v7, v8, v9 offset0:140 offset1:206
	ds_bpermute_b32 v8, v20, v4 offset:80
	ds_bpermute_b32 v9, v20, v4 offset:88
	s_waitcnt vmcnt(23) lgkmcnt(4)
	v_mul_f32_e32 v5, v33, v5
	s_waitcnt vmcnt(22) lgkmcnt(3)
	v_mul_f32_e32 v6, v34, v6
	v_add_u32_e32 v7, 0x800, v2
	ds_write2_b32 v7, v5, v6 offset0:16 offset1:82
	ds_bpermute_b32 v5, v20, v4 offset:96
	ds_bpermute_b32 v6, v20, v4 offset:104
	s_waitcnt vmcnt(21) lgkmcnt(4)
	v_mul_f32_e32 v8, v35, v8
	s_waitcnt vmcnt(20) lgkmcnt(3)
	v_mul_f32_e32 v9, v36, v9
	ds_write2_b32 v7, v8, v9 offset0:148 offset1:214
	ds_bpermute_b32 v8, v20, v4 offset:112
	ds_bpermute_b32 v9, v20, v4 offset:120
	s_waitcnt vmcnt(19) lgkmcnt(4)
	v_mul_f32_e32 v5, v37, v5
	s_waitcnt vmcnt(18) lgkmcnt(3)
	v_mul_f32_e32 v6, v38, v6
	v_add_u32_e32 v7, 0xc00, v2
	ds_write2_b32 v7, v5, v6 offset0:24 offset1:90
	ds_bpermute_b32 v5, v20, v4 offset:128
	ds_bpermute_b32 v6, v20, v4 offset:136
	s_waitcnt vmcnt(17) lgkmcnt(4)
	v_mul_f32_e32 v8, v39, v8
	s_waitcnt vmcnt(16) lgkmcnt(3)
	v_mul_f32_e32 v9, v40, v9
	ds_write2_b32 v7, v8, v9 offset0:156 offset1:222
	ds_bpermute_b32 v8, v20, v4 offset:144
	ds_bpermute_b32 v9, v20, v4 offset:152
	s_waitcnt vmcnt(15) lgkmcnt(4)
	v_mul_f32_e32 v5, v41, v5
	s_waitcnt vmcnt(14) lgkmcnt(3)
	v_mul_f32_e32 v6, v42, v6
	v_add_u32_e32 v7, 0x1000, v2
	ds_write2_b32 v7, v5, v6 offset0:32 offset1:98
	ds_bpermute_b32 v5, v20, v4 offset:160
	ds_bpermute_b32 v6, v20, v4 offset:168
	s_waitcnt vmcnt(13) lgkmcnt(4)
	v_mul_f32_e32 v8, v43, v8
	s_waitcnt vmcnt(12) lgkmcnt(3)
	v_mul_f32_e32 v9, v44, v9
	ds_write2_b32 v7, v8, v9 offset0:164 offset1:230
	ds_bpermute_b32 v8, v20, v4 offset:176
	ds_bpermute_b32 v9, v20, v4 offset:184
	s_waitcnt vmcnt(11) lgkmcnt(4)
	v_mul_f32_e32 v5, v45, v5
	s_waitcnt vmcnt(10) lgkmcnt(3)
	v_mul_f32_e32 v6, v46, v6
	v_add_u32_e32 v7, 0x1400, v2
	ds_write2_b32 v7, v5, v6 offset0:40 offset1:106
	ds_bpermute_b32 v5, v20, v4 offset:192
	ds_bpermute_b32 v6, v20, v4 offset:200
	s_waitcnt vmcnt(9) lgkmcnt(4)
	v_mul_f32_e32 v8, v47, v8
	s_waitcnt vmcnt(8) lgkmcnt(3)
	v_mul_f32_e32 v9, v48, v9
	ds_write2_b32 v7, v8, v9 offset0:172 offset1:238
	ds_bpermute_b32 v7, v20, v4 offset:208
	ds_bpermute_b32 v8, v20, v4 offset:216
	s_waitcnt vmcnt(7) lgkmcnt(4)
	v_mul_f32_e32 v5, v18, v5
	s_waitcnt vmcnt(6) lgkmcnt(3)
	v_mul_f32_e32 v6, v19, v6
	v_add_u32_e32 v9, 0x1800, v2
	ds_write2_b32 v9, v5, v6 offset0:48 offset1:114
	ds_bpermute_b32 v5, v20, v4 offset:224
	s_waitcnt vmcnt(5) lgkmcnt(3)
	v_mul_f32_e32 v6, v23, v7
	s_waitcnt vmcnt(4) lgkmcnt(2)
	v_mul_f32_e32 v7, v24, v8
	ds_bpermute_b32 v8, v20, v4 offset:232
	ds_write2_b32 v9, v6, v7 offset0:180 offset1:246
	ds_bpermute_b32 v6, v20, v4 offset:240
	ds_bpermute_b32 v4, v20, v4 offset:248
	s_waitcnt vmcnt(3) lgkmcnt(4)
	v_mul_f32_e32 v5, v49, v5
	s_waitcnt vmcnt(2) lgkmcnt(3)
	v_mul_f32_e32 v7, v50, v8
	v_add_u32_e32 v2, 0x1c00, v2
	ds_write2_b32 v2, v5, v7 offset0:56 offset1:122
	s_waitcnt vmcnt(1) lgkmcnt(2)
	v_mul_f32_e32 v5, v51, v6
	s_waitcnt vmcnt(0) lgkmcnt(1)
	v_mul_f32_e32 v4, v52, v4
	ds_write2_b32 v2, v5, v4 offset0:188 offset1:254
	s_waitcnt lgkmcnt(0)
	s_cmp_lt_i32 s3, 32
	s_cbranch_scc1 .LBB0_11
	s_cmpk_gt_u32 s0, 0x7ff
	s_cselect_b32 s1, 0xfffffc00, 0
	s_cselect_b32 s3, 0x80, 0
	s_add_i32 s1, s0, s1
	s_lshl_b32 s1, s1, 1
	s_addk_i32 s1, 0xf800
	s_and_b32 s1, s1, 0x7fffff00
	s_or_b32 s1, s1, s3
	s_and_b32 s0, s0, 0x60
	s_or_b32 s0, s1, s0
	s_addk_i32 s0, 0x400

.LBB0_41:
	s_or_b64 exec, exec, s[0:1]
	s_and_b32 s0, s18, 7
	s_ashr_i32 s1, s18, 3
	v_writelane_b32 v249, s1, 3
	s_cmp_lt_u32 s0, 4
	v_writelane_b32 v249, s0, 4
	s_cbranch_scc1 .LBB0_64
	s_load_dwordx4 s[12:15], s[16:17], 0x30
	v_writelane_b32 v249, s20, 5
	v_mov_b32_e32 v8, 1.0
	v_readlane_b32 s0, v249, 0
	s_lshl_b32 s20, s0, 7
	v_or_b32_e32 v2, s20, v108
	s_waitcnt lgkmcnt(0)
	s_cmp_lg_u64 s[12:13], 0
	s_cselect_b64 s[0:1], -1, 0
	s_cmp_eq_u64 s[12:13], 0
	v_ashrrev_i32_e32 v3, 31, v2
	v_mov_b32_e32 v9, 1.0
	s_cbranch_scc1 .LBB0_44
	v_lshl_add_u64 v[4:5], v[2:3], 2, s[12:13]
	global_load_dword v9, v[4:5], off nt
.LBB0_44:
	v_writelane_b32 v249, s68, 6
	v_lshrrev_b32_e32 v11, 5, v108
	v_mul_u32_u24_e32 v4, 0x1600, v11
	v_writelane_b32 v249, s69, 7
	v_and_b32_e32 v1, 31, v1
	v_readlane_b32 s2, v249, 3
	s_lshl_b32 s2, s2, 2
	v_readlane_b32 s3, v249, 4
	s_add_i32 s2, s3, s2
	s_add_i32 s70, s2, -4
	s_lshl_b32 s22, s70, 5
	s_ashr_i32 s23, s22, 31
	s_lshl_b64 s[2:3], s[22:23], 2
	v_or_b32_e32 v4, v4, v1
	s_add_u32 s2, s14, s2
	s_addc_u32 s3, s15, s3
	v_mov_b32_e32 v5, 0
	v_lshlrev_b32_e32 v4, 2, v4
	v_lshl_add_u64 v[6:7], s[2:3], 0, v[4:5]
	s_or_b32 s2, s20, 2
	s_mul_hi_i32 s79, s2, 0x1600
	s_mul_i32 s78, s2, 0x1600
	s_or_b32 s2, s20, 4
	s_mul_hi_i32 s75, s2, 0x1600
	s_mul_i32 s74, s2, 0x1600
	s_or_b32 s2, s20, 6
	s_mul_hi_i32 s81, s2, 0x1600
	s_mul_i32 s80, s2, 0x1600
	s_or_b32 s2, s20, 8
	s_mul_hi_i32 s83, s2, 0x1600
	s_mul_i32 s82, s2, 0x1600
	s_or_b32 s2, s20, 10
	s_mul_hi_i32 s85, s2, 0x1600
	s_mul_i32 s84, s2, 0x1600
	s_or_b32 s2, s20, 12
	s_mul_hi_i32 s87, s2, 0x1600
	s_mul_i32 s86, s2, 0x1600
	s_or_b32 s2, s20, 14
	s_mul_hi_i32 s89, s2, 0x1600
	s_mul_i32 s88, s2, 0x1600
	s_or_b32 s2, s20, 16
	s_mul_hi_i32 s91, s2, 0x1600
	s_mul_i32 s90, s2, 0x1600
	s_or_b32 s2, s20, 18
	s_mul_hi_i32 s93, s2, 0x1600
	s_mul_i32 s92, s2, 0x1600
	s_or_b32 s2, s20, 20
	s_mul_hi_i32 s95, s2, 0x1600
	s_mul_i32 s94, s2, 0x1600
	s_or_b32 s2, s20, 22
	s_mul_hi_i32 s97, s2, 0x1600
	s_mul_i32 s96, s2, 0x1600
	s_or_b32 s2, s20, 24
	s_mul_hi_i32 s5, s2, 0x1600
	s_mul_i32 s4, s2, 0x1600
	s_or_b32 s2, s20, 26
	s_mul_hi_i32 s9, s2, 0x1600
	s_mul_i32 s8, s2, 0x1600
	s_or_b32 s2, s20, 28
	s_mul_hi_i32 s77, s20, 0x1600
	s_mul_i32 s76, s20, 0x1600
	s_mul_hi_i32 s3, s2, 0x1600
	s_mulk_i32 s2, 0x1600
	v_lshl_add_u64 v[20:21], s[76:77], 2, v[6:7]
	v_lshl_add_u64 v[34:35], s[88:89], 2, v[6:7]
	v_writelane_b32 v249, s2, 8
	v_lshl_add_u64 v[22:23], s[78:79], 2, v[6:7]
	v_lshl_add_u64 v[24:25], s[74:75], 2, v[6:7]
	v_lshl_add_u64 v[26:27], s[80:81], 2, v[6:7]
	v_lshl_add_u64 v[28:29], s[82:83], 2, v[6:7]
	v_lshl_add_u64 v[30:31], s[84:85], 2, v[6:7]
	v_lshl_add_u64 v[32:33], s[86:87], 2, v[6:7]
	global_load_dword v14, v[20:21], off nt
	global_load_dword v16, v[22:23], off nt
	global_load_dword v17, v[24:25], off nt
	global_load_dword v18, v[26:27], off nt
	global_load_dword v5, v[28:29], off nt
	global_load_dword v10, v[30:31], off nt
	global_load_dword v12, v[32:33], off nt
	global_load_dword v13, v[34:35], off nt
	v_writelane_b32 v249, s3, 9
	v_lshl_add_u64 v[34:35], s[2:3], 2, v[6:7]
	s_or_b32 s2, s20, 30
	s_mul_hi_i32 s3, s2, 0x1600
	s_mulk_i32 s2, 0x1600
	v_writelane_b32 v249, s2, 10
	v_lshl_add_u64 v[20:21], s[90:91], 2, v[6:7]
	v_lshl_add_u64 v[22:23], s[92:93], 2, v[6:7]
	v_writelane_b32 v249, s3, 11
	v_lshl_add_u64 v[36:37], s[2:3], 2, v[6:7]
	s_or_b32 s2, s20, 32
	s_mul_hi_i32 s3, s2, 0x1600
	s_mulk_i32 s2, 0x1600
	v_lshl_add_u64 v[24:25], s[94:95], 2, v[6:7]
	v_lshl_add_u64 v[28:29], s[96:97], 2, v[6:7]
	v_writelane_b32 v249, s2, 12
	v_lshl_add_u64 v[30:31], s[4:5], 2, v[6:7]
	v_lshl_add_u64 v[32:33], s[8:9], 2, v[6:7]
	global_load_dword v26, v[20:21], off nt
	s_nop 0
	global_load_dword v21, v[22:23], off nt
	s_nop 0
	global_load_dword v22, v[24:25], off nt
	global_load_dword v23, v[28:29], off nt
	s_nop 0
	global_load_dword v24, v[30:31], off nt
	global_load_dword v25, v[32:33], off nt
	global_load_dword v19, v[34:35], off nt
	global_load_dword v20, v[36:37], off nt
	v_writelane_b32 v249, s3, 13
	v_lshl_add_u64 v[28:29], s[2:3], 2, v[6:7]
	s_or_b32 s2, s20, 34
	s_mul_hi_i32 s3, s2, 0x1600
	s_mulk_i32 s2, 0x1600
	v_writelane_b32 v249, s2, 14
	v_cndmask_b32_e64 v15, 0, 1, s[0:1]
	s_andn2_b64 vcc, exec, s[0:1]
	v_writelane_b32 v249, s3, 15
	v_lshl_add_u64 v[30:31], s[2:3], 2, v[6:7]
	s_or_b32 s2, s20, 36
	s_mul_hi_i32 s3, s2, 0x1600
	s_mulk_i32 s2, 0x1600
	v_writelane_b32 v249, s2, 16
	s_nop 1
	v_writelane_b32 v249, s3, 17
	v_lshl_add_u64 v[34:35], s[2:3], 2, v[6:7]
	s_or_b32 s2, s20, 38
	s_mul_hi_i32 s3, s2, 0x1600
	s_mulk_i32 s2, 0x1600
	v_writelane_b32 v249, s2, 18
	s_nop 1
	v_writelane_b32 v249, s3, 19
	v_lshl_add_u64 v[36:37], s[2:3], 2, v[6:7]
	s_or_b32 s2, s20, 40
	s_mul_hi_i32 s3, s2, 0x1600
	s_mulk_i32 s2, 0x1600
	v_writelane_b32 v249, s2, 20
	s_nop 1
	v_writelane_b32 v249, s3, 21
	v_lshl_add_u64 v[38:39], s[2:3], 2, v[6:7]
	s_or_b32 s2, s20, 42
	s_mul_hi_i32 s3, s2, 0x1600
	s_mulk_i32 s2, 0x1600
	v_writelane_b32 v249, s2, 22
	s_nop 1
	v_writelane_b32 v249, s3, 23
	v_lshl_add_u64 v[40:41], s[2:3], 2, v[6:7]
	s_or_b32 s2, s20, 44
	s_mul_hi_i32 s3, s2, 0x1600
	s_mulk_i32 s2, 0x1600
	v_writelane_b32 v249, s2, 24
	s_nop 1
	v_writelane_b32 v249, s3, 25
	v_lshl_add_u64 v[42:43], s[2:3], 2, v[6:7]
	s_or_b32 s2, s20, 46
	s_mul_hi_i32 s3, s2, 0x1600
	s_mulk_i32 s2, 0x1600
	v_writelane_b32 v249, s2, 26
	s_nop 1
	v_writelane_b32 v249, s3, 27
	v_lshl_add_u64 v[44:45], s[2:3], 2, v[6:7]
	s_or_b32 s2, s20, 48
	s_mul_hi_i32 s3, s2, 0x1600
	s_mulk_i32 s2, 0x1600
	v_writelane_b32 v249, s2, 28
	global_load_dword v32, v[28:29], off nt
	global_load_dword v33, v[30:31], off nt
	s_nop 0
	global_load_dword v34, v[34:35], off nt
	s_nop 0
	global_load_dword v27, v[36:37], off nt
	global_load_dword v28, v[38:39], off nt
	global_load_dword v29, v[40:41], off nt
	global_load_dword v30, v[42:43], off nt
	global_load_dword v31, v[44:45], off nt
	v_writelane_b32 v249, s3, 29
	v_lshl_add_u64 v[36:37], s[2:3], 2, v[6:7]
	s_or_b32 s2, s20, 50
	s_mul_hi_i32 s3, s2, 0x1600
	s_mulk_i32 s2, 0x1600
	v_writelane_b32 v249, s2, 30
	s_nop 1
	v_writelane_b32 v249, s3, 31
	v_lshl_add_u64 v[40:41], s[2:3], 2, v[6:7]
	s_or_b32 s2, s20, 52
	s_mul_hi_i32 s3, s2, 0x1600
	s_mulk_i32 s2, 0x1600
	v_writelane_b32 v249, s2, 32
	s_nop 1
	v_writelane_b32 v249, s3, 33
	v_lshl_add_u64 v[42:43], s[2:3], 2, v[6:7]
	s_or_b32 s2, s20, 54
	s_mul_hi_i32 s3, s2, 0x1600
	s_mulk_i32 s2, 0x1600
	v_writelane_b32 v249, s2, 34
	s_nop 1
	v_writelane_b32 v249, s3, 35
	v_lshl_add_u64 v[44:45], s[2:3], 2, v[6:7]
	s_or_b32 s2, s20, 56
	s_mul_hi_i32 s3, s2, 0x1600
	s_mulk_i32 s2, 0x1600
	v_writelane_b32 v249, s2, 36
	s_nop 1
	v_writelane_b32 v249, s3, 37
	v_lshl_add_u64 v[46:47], s[2:3], 2, v[6:7]
	s_or_b32 s2, s20, 58
	s_mul_hi_i32 s3, s2, 0x1600
	s_mulk_i32 s2, 0x1600
	v_writelane_b32 v249, s2, 38
	s_nop 1
	v_writelane_b32 v249, s3, 39
	v_lshl_add_u64 v[48:49], s[2:3], 2, v[6:7]
	s_or_b32 s2, s20, 60
	s_mul_hi_i32 s3, s2, 0x1600
	s_mulk_i32 s2, 0x1600
	v_writelane_b32 v249, s2, 40
	s_nop 1
	v_writelane_b32 v249, s3, 41
	v_lshl_add_u64 v[50:51], s[2:3], 2, v[6:7]
	s_or_b32 s2, s20, 62
	s_mul_hi_i32 s3, s2, 0x1600
	s_mulk_i32 s2, 0x1600
	v_writelane_b32 v249, s2, 42
	s_nop 1
	v_lshl_add_u64 v[52:53], s[2:3], 2, v[6:7]
	global_load_dword v38, v[36:37], off nt
	global_load_dword v39, v[40:41], off nt
	s_nop 0
	global_load_dword v40, v[42:43], off nt
	global_load_dword v41, v[44:45], off nt
	s_nop 0
	global_load_dword v42, v[46:47], off nt
	global_load_dword v35, v[48:49], off nt
	global_load_dword v36, v[50:51], off nt
	global_load_dword v37, v[52:53], off nt
	v_writelane_b32 v249, s3, 43
	v_cmp_ne_u32_e64 s[2:3], 1, v15
	s_nop 1
	v_writelane_b32 v249, s2, 44
	s_nop 1
	v_writelane_b32 v249, s3, 45
	s_cbranch_vccnz .LBB0_46
	v_lshl_add_u64 v[44:45], v[2:3], 2, s[12:13]
	global_load_dword v8, v[44:45], off offset:256 nt
.LBB0_46:
	s_or_b32 s0, s20, 64
	s_mul_hi_i32 s1, s0, 0x1600
	s_mulk_i32 s0, 0x1600
	v_writelane_b32 v249, s0, 46
	s_or_b32 s2, s20, 0x4e
	s_mul_hi_i32 s13, s2, 0x1600
	v_writelane_b32 v249, s1, 47
	v_lshl_add_u64 v[44:45], s[0:1], 2, v[6:7]
	s_or_b32 s0, s20, 0x42
	s_mul_hi_i32 s1, s0, 0x1600
	s_mulk_i32 s0, 0x1600
	v_writelane_b32 v249, s0, 48
	s_mul_i32 s12, s2, 0x1600
	v_lshl_add_u64 v[58:59], s[12:13], 2, v[6:7]
	v_writelane_b32 v249, s1, 49
	v_lshl_add_u64 v[46:47], s[0:1], 2, v[6:7]
	s_or_b32 s0, s20, 0x44
	s_mul_hi_i32 s1, s0, 0x1600
	s_mulk_i32 s0, 0x1600
	v_writelane_b32 v249, s0, 50
	s_or_b32 s2, s20, 0x50
	s_or_b32 s21, s20, 0x56
	v_writelane_b32 v249, s1, 51
	v_lshl_add_u64 v[48:49], s[0:1], 2, v[6:7]
	s_or_b32 s0, s20, 0x46
	s_mul_hi_i32 s1, s0, 0x1600
	s_mulk_i32 s0, 0x1600
	v_writelane_b32 v249, s0, 52
	s_mul_hi_i32 s15, s2, 0x1600
	s_mul_i32 s14, s2, 0x1600
	v_writelane_b32 v249, s1, 53
	v_lshl_add_u64 v[50:51], s[0:1], 2, v[6:7]
	s_or_b32 s0, s20, 0x48
	s_mul_hi_i32 s1, s0, 0x1600
	s_mulk_i32 s0, 0x1600
	v_writelane_b32 v249, s0, 54
	s_or_b32 s2, s20, 0x52
	s_mul_hi_i32 s25, s21, 0x1600
	v_writelane_b32 v249, s1, 55
	v_lshl_add_u64 v[52:53], s[0:1], 2, v[6:7]
	s_or_b32 s0, s20, 0x4a
	s_mul_hi_i32 s1, s0, 0x1600
	s_mulk_i32 s0, 0x1600
	v_writelane_b32 v249, s0, 56
	s_mul_i32 s24, s21, 0x1600
	s_or_b32 s21, s20, 0x58
	v_writelane_b32 v249, s1, 57
	v_lshl_add_u64 v[54:55], s[0:1], 2, v[6:7]
	s_or_b32 s0, s20, 0x4c
	s_mul_hi_i32 s1, s0, 0x1600
	s_mulk_i32 s0, 0x1600
	v_writelane_b32 v249, s0, 58
	s_mul_hi_i32 s7, s2, 0x1600
	s_mul_i32 s6, s2, 0x1600
	v_lshl_add_u64 v[56:57], s[0:1], 2, v[6:7]
	global_load_dword v43, v[44:45], off nt
	global_load_dword v74, v[46:47], off nt
	global_load_dword v75, v[48:49], off nt
	global_load_dword v76, v[50:51], off nt
	global_load_dword v77, v[52:53], off nt
	global_load_dword v78, v[54:55], off nt
	global_load_dword v79, v[56:57], off nt
	global_load_dword v80, v[58:59], off nt
	v_lshl_add_u64 v[44:45], s[14:15], 2, v[6:7]
	s_mul_hi_i32 s27, s21, 0x1600
	s_mul_i32 s26, s21, 0x1600
	s_or_b32 s21, s20, 0x5a
	v_lshl_add_u64 v[46:47], s[6:7], 2, v[6:7]
	global_load_dword v81, v[44:45], off nt
	global_load_dword v82, v[46:47], off nt
	s_mul_hi_i32 s29, s21, 0x1600
	s_mul_i32 s28, s21, 0x1600
	s_or_b32 s21, s20, 0x5c
	s_or_b32 s2, s20, 0x54
	s_mul_hi_i32 s31, s21, 0x1600
	s_mul_i32 s30, s21, 0x1600
	s_or_b32 s21, s20, 0x5e
	s_mul_hi_i32 s3, s2, 0x1600
	s_mulk_i32 s2, 0x1600
	s_mul_hi_i32 s35, s21, 0x1600
	s_mul_i32 s34, s21, 0x1600
	s_or_b32 s21, s20, 0x60
	v_lshl_add_u64 v[44:45], s[2:3], 2, v[6:7]
	s_mul_hi_i32 s37, s21, 0x1600
	s_mul_i32 s36, s21, 0x1600
	s_or_b32 s21, s20, 0x62
	v_lshl_add_u64 v[46:47], s[24:25], 2, v[6:7]
	v_lshl_add_u64 v[48:49], s[26:27], 2, v[6:7]
	v_lshl_add_u64 v[50:51], s[28:29], 2, v[6:7]
	v_lshl_add_u64 v[52:53], s[30:31], 2, v[6:7]
	v_lshl_add_u64 v[54:55], s[34:35], 2, v[6:7]
	global_load_dword v83, v[44:45], off nt
	global_load_dword v84, v[46:47], off nt
	global_load_dword v85, v[48:49], off nt
	global_load_dword v86, v[50:51], off nt
	global_load_dword v87, v[52:53], off nt
	global_load_dword v88, v[54:55], off nt
	s_mul_hi_i32 s39, s21, 0x1600
	s_mul_i32 s38, s21, 0x1600
	s_or_b32 s21, s20, 0x64
	v_lshl_add_u64 v[44:45], s[36:37], 2, v[6:7]
	s_mul_hi_i32 s41, s21, 0x1600
	s_mul_i32 s40, s21, 0x1600
	s_or_b32 s21, s20, 0x66
	v_lshl_add_u64 v[46:47], s[38:39], 2, v[6:7]
	global_load_dword v89, v[44:45], off nt
	global_load_dword v90, v[46:47], off nt
	s_mul_hi_i32 s43, s21, 0x1600
	s_mul_i32 s42, s21, 0x1600
	s_or_b32 s21, s20, 0x68
	v_lshl_add_u64 v[44:45], s[40:41], 2, v[6:7]
	v_lshl_add_u64 v[46:47], s[42:43], 2, v[6:7]
	s_mul_hi_i32 s45, s21, 0x1600
	s_mul_i32 s44, s21, 0x1600
	s_or_b32 s21, s20, 0x6a
	global_load_dword v91, v[44:45], off nt
	s_nop 0
	global_load_dword v46, v[46:47], off nt
	v_lshl_add_u64 v[44:45], s[44:45], 2, v[6:7]
	s_mul_hi_i32 s47, s21, 0x1600
	s_mul_i32 s46, s21, 0x1600
	s_or_b32 s21, s20, 0x6c
	global_load_dword v47, v[44:45], off nt
	v_lshl_add_u64 v[44:45], s[46:47], 2, v[6:7]
	s_mul_hi_i32 s49, s21, 0x1600
	s_mul_i32 s48, s21, 0x1600
	s_or_b32 s21, s20, 0x6e
	global_load_dword v92, v[44:45], off nt
	v_lshl_add_u64 v[44:45], s[48:49], 2, v[6:7]
	s_mul_hi_i32 s53, s21, 0x1600
	s_mul_i32 s52, s21, 0x1600
	s_or_b32 s21, s20, 0x70
	global_load_dword v93, v[44:45], off nt
	v_lshl_add_u64 v[44:45], s[52:53], 2, v[6:7]
	s_mul_hi_i32 s51, s21, 0x1600
	s_mul_i32 s50, s21, 0x1600
	s_or_b32 s21, s20, 0x72
	global_load_dword v94, v[44:45], off nt
	v_lshl_add_u64 v[44:45], s[50:51], 2, v[6:7]
	s_mul_hi_i32 s55, s21, 0x1600
	s_mul_i32 s54, s21, 0x1600
	s_or_b32 s21, s20, 0x74
	global_load_dword v95, v[44:45], off nt
	v_lshl_add_u64 v[44:45], s[54:55], 2, v[6:7]
	s_mul_hi_i32 s57, s21, 0x1600
	s_mul_i32 s56, s21, 0x1600
	s_or_b32 s21, s20, 0x76
	global_load_dword v96, v[44:45], off nt
	v_lshl_add_u64 v[44:45], s[56:57], 2, v[6:7]
	s_mul_hi_i32 s59, s21, 0x1600
	s_mul_i32 s58, s21, 0x1600
	s_or_b32 s21, s20, 0x78
	global_load_dword v97, v[44:45], off nt
	s_mul_hi_i32 s61, s21, 0x1600
	s_mul_i32 s60, s21, 0x1600
	s_or_b32 s21, s20, 0x7a
	v_lshl_add_u64 v[44:45], s[58:59], 2, v[6:7]
	s_mul_hi_i32 s63, s21, 0x1600
	s_mul_i32 s62, s21, 0x1600
	s_or_b32 s21, s20, 0x7c
	global_load_dword v98, v[44:45], off nt
	v_lshl_add_u64 v[44:45], s[60:61], 2, v[6:7]
	s_mul_hi_i32 s65, s21, 0x1600
	s_mul_i32 s64, s21, 0x1600
	s_or_b32 s21, s20, 0x7e
	global_load_dword v99, v[44:45], off nt
	v_lshl_add_u64 v[44:45], s[62:63], 2, v[6:7]
	s_mul_hi_i32 s67, s21, 0x1600
	s_mul_i32 s66, s21, 0x1600
	global_load_dword v100, v[44:45], off nt
	v_lshl_add_u64 v[44:45], s[64:65], 2, v[6:7]
	v_lshl_add_u64 v[6:7], s[66:67], 2, v[6:7]
	global_load_dword v101, v[44:45], off nt
	global_load_dword v102, v[6:7], off nt
	v_lshlrev_b32_e32 v15, 2, v11
	s_waitcnt vmcnt(62)
	ds_bpermute_b32 v45, v15, v9 offset:8
	ds_bpermute_b32 v48, v15, v9 offset:16
	ds_bpermute_b32 v49, v15, v9 offset:24
	ds_bpermute_b32 v50, v15, v9 offset:64
	ds_bpermute_b32 v44, v15, v9
	s_waitcnt lgkmcnt(4)
	v_mul_f32_e32 v16, v16, v45
	s_waitcnt vmcnt(61) lgkmcnt(3)
	v_mul_f32_e32 v7, v17, v48
	s_waitcnt vmcnt(60) lgkmcnt(2)
	v_mul_f32_e32 v6, v18, v49
	ds_bpermute_b32 v17, v15, v9 offset:32
	ds_bpermute_b32 v18, v15, v9 offset:40
	ds_bpermute_b32 v45, v15, v9 offset:56
	s_waitcnt lgkmcnt(3)
	v_mul_f32_e32 v14, v14, v44
	ds_bpermute_b32 v44, v15, v9 offset:48
	s_waitcnt vmcnt(59) lgkmcnt(3)
	v_mul_f32_e32 v55, v5, v17
	s_waitcnt vmcnt(58) lgkmcnt(2)
	v_mul_f32_e32 v53, v10, v18
	s_waitcnt vmcnt(56) lgkmcnt(1)
	v_mul_f32_e32 v48, v13, v45
	ds_bpermute_b32 v5, v15, v9 offset:72
	ds_bpermute_b32 v10, v15, v9 offset:80
	ds_bpermute_b32 v13, v15, v9 offset:96
	ds_bpermute_b32 v18, v15, v9 offset:104
	s_waitcnt vmcnt(55)
	v_mul_f32_e32 v17, v26, v50
	s_waitcnt vmcnt(54) lgkmcnt(3)
	v_mul_f32_e32 v61, v21, v5
	s_waitcnt vmcnt(53) lgkmcnt(2)
	v_mul_f32_e32 v56, v22, v10
	s_waitcnt vmcnt(51) lgkmcnt(1)
	v_mul_f32_e32 v51, v24, v13
	ds_bpermute_b32 v5, v15, v9 offset:112
	ds_bpermute_b32 v10, v15, v9 offset:120
	ds_bpermute_b32 v13, v15, v9 offset:136
	s_waitcnt vmcnt(50) lgkmcnt(3)
	v_mul_f32_e32 v50, v25, v18
	ds_bpermute_b32 v18, v15, v9 offset:144
	s_waitcnt vmcnt(49) lgkmcnt(3)
	v_mul_f32_e32 v64, v19, v5
	s_waitcnt vmcnt(48) lgkmcnt(2)
	v_mul_f32_e32 v62, v20, v10
	s_waitcnt vmcnt(46) lgkmcnt(1)
	v_mul_f32_e32 v57, v33, v13
	ds_bpermute_b32 v5, v15, v9 offset:152
	ds_bpermute_b32 v10, v15, v9 offset:160
	ds_bpermute_b32 v13, v15, v9 offset:176
	s_waitcnt vmcnt(45) lgkmcnt(3)
	v_mul_f32_e32 v52, v34, v18
	ds_bpermute_b32 v18, v15, v9 offset:184
	s_waitcnt vmcnt(44) lgkmcnt(3)
	v_mul_f32_e32 v69, v27, v5
	s_waitcnt vmcnt(43) lgkmcnt(2)
	v_mul_f32_e32 v66, v28, v10
	s_waitcnt vmcnt(41) lgkmcnt(1)
	v_mul_f32_e32 v60, v30, v13
	ds_bpermute_b32 v5, v15, v9 offset:192
	ds_bpermute_b32 v10, v15, v9 offset:200
	ds_bpermute_b32 v13, v15, v9 offset:216
	v_mul_f32_e32 v49, v12, v44
	ds_bpermute_b32 v12, v15, v9 offset:88
	s_waitcnt vmcnt(40) lgkmcnt(4)
	v_mul_f32_e32 v58, v31, v18
	ds_bpermute_b32 v18, v15, v9 offset:224
	s_waitcnt vmcnt(39) lgkmcnt(4)
	v_mul_f32_e32 v71, v38, v5
	s_waitcnt vmcnt(38) lgkmcnt(3)
	v_mul_f32_e32 v70, v39, v10
	s_waitcnt vmcnt(36) lgkmcnt(2)
	v_mul_f32_e32 v67, v41, v13
	ds_bpermute_b32 v5, v15, v9 offset:232
	ds_bpermute_b32 v10, v15, v9 offset:240
	s_waitcnt vmcnt(32)
	ds_bpermute_b32 v13, v15, v8 offset:8
	s_waitcnt lgkmcnt(4)
	v_mul_f32_e32 v54, v23, v12
	ds_bpermute_b32 v12, v15, v9 offset:128
	s_waitcnt lgkmcnt(4)
	v_mul_f32_e32 v63, v42, v18
	s_waitcnt lgkmcnt(3)
	v_mul_f32_e32 v73, v35, v5
	s_waitcnt lgkmcnt(2)
	v_mul_f32_e32 v72, v36, v10
	s_waitcnt vmcnt(30) lgkmcnt(1)
	v_mul_f32_e32 v5, v74, v13
	ds_bpermute_b32 v10, v15, v8 offset:16
	ds_bpermute_b32 v13, v15, v8 offset:24
	ds_bpermute_b32 v18, v15, v8 offset:32
	ds_bpermute_b32 v21, v15, v8 offset:48
	s_waitcnt lgkmcnt(4)
	v_mul_f32_e32 v59, v32, v12
	ds_bpermute_b32 v12, v15, v9 offset:168
	s_waitcnt vmcnt(29) lgkmcnt(4)
	v_mul_f32_e32 v24, v75, v10
	s_waitcnt vmcnt(28) lgkmcnt(3)
	v_mul_f32_e32 v22, v76, v13
	s_waitcnt vmcnt(27) lgkmcnt(2)
	v_mul_f32_e32 v20, v77, v18
	s_waitcnt vmcnt(25) lgkmcnt(1)
	v_mul_f32_e32 v13, v79, v21
	ds_bpermute_b32 v10, v15, v8 offset:56
	ds_bpermute_b32 v18, v15, v8 offset:64
	ds_bpermute_b32 v21, v15, v8 offset:72
	ds_bpermute_b32 v27, v15, v8 offset:88
	s_waitcnt lgkmcnt(4)
	v_mul_f32_e32 v65, v29, v12
	ds_bpermute_b32 v12, v15, v9 offset:208
	ds_bpermute_b32 v9, v15, v9 offset:248
	s_waitcnt vmcnt(24) lgkmcnt(5)
	v_mul_f32_e32 v28, v80, v10
	s_waitcnt vmcnt(23) lgkmcnt(4)
	v_mul_f32_e32 v26, v81, v18
	s_waitcnt vmcnt(22) lgkmcnt(3)
	v_mul_f32_e32 v25, v82, v21
	s_waitcnt vmcnt(20) lgkmcnt(2)
	v_mul_f32_e32 v21, v84, v27
	ds_bpermute_b32 v10, v15, v8 offset:96
	ds_bpermute_b32 v18, v15, v8 offset:104
	ds_bpermute_b32 v27, v15, v8 offset:112
	ds_bpermute_b32 v31, v15, v8 offset:128
	s_waitcnt lgkmcnt(4)
	v_mul_f32_e32 v9, v37, v9
	s_waitcnt vmcnt(19) lgkmcnt(3)
	v_mul_f32_e32 v34, v85, v10
	s_waitcnt vmcnt(18) lgkmcnt(2)
	v_mul_f32_e32 v32, v86, v18
	s_waitcnt vmcnt(17) lgkmcnt(1)
	v_mul_f32_e32 v30, v87, v27
	s_waitcnt vmcnt(15) lgkmcnt(0)
	v_mul_f32_e32 v27, v89, v31
	ds_bpermute_b32 v10, v15, v8 offset:136
	ds_bpermute_b32 v18, v15, v8 offset:144
	ds_bpermute_b32 v31, v15, v8 offset:152
	ds_bpermute_b32 v37, v15, v8 offset:168
	v_mul_f32_e32 v68, v40, v12
	ds_bpermute_b32 v12, v15, v8
	s_waitcnt vmcnt(14) lgkmcnt(4)
	v_mul_f32_e32 v38, v90, v10
	s_waitcnt vmcnt(13) lgkmcnt(3)
	v_mul_f32_e32 v36, v91, v18
	s_waitcnt vmcnt(12) lgkmcnt(2)
	v_mul_f32_e32 v35, v46, v31
	s_waitcnt vmcnt(10) lgkmcnt(1)
	v_mul_f32_e32 v31, v92, v37
	ds_bpermute_b32 v10, v15, v8 offset:176
	ds_bpermute_b32 v18, v15, v8 offset:184
	ds_bpermute_b32 v37, v15, v8 offset:192
	ds_bpermute_b32 v41, v15, v8 offset:208
	s_waitcnt lgkmcnt(4)
	v_mul_f32_e32 v12, v43, v12
	ds_bpermute_b32 v19, v15, v8 offset:40
	ds_bpermute_b32 v23, v15, v8 offset:80
	ds_bpermute_b32 v29, v15, v8 offset:120
	ds_bpermute_b32 v33, v15, v8 offset:160
	ds_bpermute_b32 v39, v15, v8 offset:200
	s_waitcnt vmcnt(9) lgkmcnt(8)
	v_mul_f32_e32 v44, v93, v10
	s_waitcnt vmcnt(8) lgkmcnt(7)
	v_mul_f32_e32 v42, v94, v18
	s_waitcnt vmcnt(7) lgkmcnt(6)
	v_mul_f32_e32 v40, v95, v37
	s_waitcnt vmcnt(5) lgkmcnt(5)
	v_mul_f32_e32 v37, v97, v41
	ds_bpermute_b32 v10, v15, v8 offset:216
	ds_bpermute_b32 v18, v15, v8 offset:224
	ds_bpermute_b32 v41, v15, v8 offset:232
	ds_bpermute_b32 v43, v15, v8 offset:240
	ds_bpermute_b32 v8, v15, v8 offset:248
	s_waitcnt lgkmcnt(9)
	v_mul_f32_e32 v19, v78, v19
	s_waitcnt lgkmcnt(8)
	v_mul_f32_e32 v23, v83, v23
	s_waitcnt vmcnt(2) lgkmcnt(2)
	v_mul_f32_e32 v45, v100, v41
	v_mul_f32_e32 v29, v88, v29
	s_waitcnt vmcnt(0) lgkmcnt(0)
	v_mul_f32_e32 v41, v102, v8
	v_max3_f32 v8, |v14|, 0, |v16|
	v_max3_f32 v8, v8, |v7|, |v6|
	v_max3_f32 v8, v8, |v55|, |v53|
	v_max3_f32 v8, v8, |v49|, |v48|
	v_max3_f32 v8, v8, |v17|, |v61|
	v_max3_f32 v8, v8, |v56|, |v54|
	v_max3_f32 v8, v8, |v51|, |v50|
	v_max3_f32 v8, v8, |v64|, |v62|
	v_max3_f32 v8, v8, |v59|, |v57|
	v_max3_f32 v8, v8, |v52|, |v69|
	v_max3_f32 v8, v8, |v66|, |v65|
	v_max3_f32 v8, v8, |v60|, |v58|
	v_max3_f32 v8, v8, |v71|, |v70|
	v_max3_f32 v8, v8, |v68|, |v67|
	v_max3_f32 v8, v8, |v63|, |v73|
	v_max3_f32 v8, v8, |v72|, |v9|
	v_max3_f32 v8, v8, |v12|, |v5|
	v_max3_f32 v8, v8, |v24|, |v22|
	v_max3_f32 v8, v8, |v20|, |v19|
	v_max3_f32 v8, v8, |v13|, |v28|
	v_max3_f32 v8, v8, |v26|, |v25|
	v_max3_f32 v8, v8, |v23|, |v21|
	v_max3_f32 v8, v8, |v34|, |v32|
	v_max3_f32 v8, v8, |v30|, |v29|
	v_max3_f32 v8, v8, |v27|, |v38|
	v_mul_f32_e32 v33, v47, v33
	v_max3_f32 v8, v8, |v36|, |v35|
	v_max3_f32 v8, v8, |v33|, |v31|
	v_mul_f32_e32 v39, v96, v39
	v_max3_f32 v8, v8, |v44|, |v42|
	v_mul_f32_e32 v47, v98, v10
	v_max3_f32 v8, v8, |v40|, |v39|
	v_mul_f32_e32 v46, v99, v18
	v_max3_f32 v8, v8, |v37|, |v47|
	v_mul_f32_e32 v43, v101, v43
	v_max3_f32 v8, v8, |v46|, |v45|
	v_max3_f32 v8, v8, |v43|, |v41|
	v_writelane_b32 v249, s1, 59
	v_mov_b32_e32 v10, v8
	v_cmp_gt_u32_e64 s[0:1], 32, v108
	s_ashr_i32 s21, s20, 31
	v_permlane32_swap_b32_e32 v8, v10
	v_writelane_b32 v249, s0, 60
	s_nop 1
	v_writelane_b32 v249, s1, 61
	s_and_saveexec_b64 s[68:69], s[0:1]
	s_cbranch_execz .LBB0_48
	v_max_f32_e32 v8, v8, v8
	v_max_f32_e32 v10, v10, v10
	s_add_i32 s23, s20, 0
	v_max_f32_e32 v8, v8, v10
	v_lshl_add_u32 v10, v108, 2, s23
	v_add_u32_e32 v10, 0x20000, v10
	ds_write_b32 v10, v8

.LBB0_50:
	s_or_b64 exec, exec, vcc
	s_mov_b32 s23, 0x42fe0000
	v_div_scale_f32 v10, s[70:71], v8, v8, s23
	v_rcp_f32_e32 v74, v10
	v_div_scale_f32 v75, vcc, s23, v8, s23
	s_mov_b64 s[70:71], 0xa00000
	v_fma_f32 v76, -v10, v74, 1.0
	v_fmac_f32_e32 v74, v76, v74
	v_mul_f32_e32 v76, v75, v74
	v_fma_f32 v77, -v10, v76, v75
	v_fmac_f32_e32 v76, v77, v74
	v_fma_f32 v10, -v10, v76, v75
	v_div_fmas_f32 v10, v10, v74, v76
	v_div_fixup_f32 v10, v10, v8, s23
	v_cmp_lt_f32_e32 vcc, 0, v8
	v_readlane_b32 s23, v249, 5
	s_mov_b32 s33, s19
	v_cndmask_b32_e32 v74, 0, v10, vcc
	v_mul_f32_e32 v14, v14, v74
	v_lshlrev_b32_e32 v10, 2, v1
	v_rndne_f32_e32 v75, v14
	v_mul_u32_u24_e32 v14, 0x84, v11
	v_mul_f32_e32 v7, v7, v74
	v_mul_f32_e32 v6, v6, v74
	v_add3_u32 v14, s23, v10, v14
	v_mul_f32_e32 v16, v16, v74
	v_rndne_f32_e32 v7, v7
	v_rndne_f32_e32 v6, v6
	v_rndne_f32_e32 v16, v16
	ds_write2_b32 v14, v7, v6 offset0:132 offset1:198
	v_mul_f32_e32 v6, v55, v74
	v_mul_f32_e32 v7, v53, v74
	ds_write2_b32 v14, v75, v16 offset1:66
	v_rndne_f32_e32 v6, v6
	v_rndne_f32_e32 v7, v7
	v_add_u32_e32 v75, 0x400, v14
	ds_write2_b32 v75, v6, v7 offset0:8 offset1:74
	v_mul_f32_e32 v6, v49, v74
	v_mul_f32_e32 v7, v48, v74
	v_rndne_f32_e32 v6, v6
	v_rndne_f32_e32 v7, v7
	ds_write2_b32 v75, v6, v7 offset0:140 offset1:206
	v_mul_f32_e32 v6, v17, v74
	v_mul_f32_e32 v7, v61, v74
	v_rndne_f32_e32 v6, v6
	v_rndne_f32_e32 v7, v7
	v_add_u32_e32 v61, 0x800, v14
	ds_write2_b32 v61, v6, v7 offset0:16 offset1:82
	v_mul_f32_e32 v6, v56, v74
	v_mul_f32_e32 v7, v54, v74
	v_rndne_f32_e32 v6, v6
	v_rndne_f32_e32 v7, v7
	ds_write2_b32 v61, v6, v7 offset0:148 offset1:214
	v_mul_f32_e32 v6, v51, v74
	v_mul_f32_e32 v7, v50, v74
	v_rndne_f32_e32 v6, v6
	v_rndne_f32_e32 v7, v7
	v_add_u32_e32 v76, 0xc00, v14
	ds_write2_b32 v76, v6, v7 offset0:24 offset1:90
	v_mul_f32_e32 v6, v64, v74
	v_mul_f32_e32 v7, v62, v74
	v_rndne_f32_e32 v6, v6
	v_rndne_f32_e32 v7, v7
	ds_write2_b32 v76, v6, v7 offset0:156 offset1:222
	v_mul_f32_e32 v6, v59, v74
	v_mul_f32_e32 v7, v57, v74
	v_rndne_f32_e32 v6, v6
	v_rndne_f32_e32 v7, v7
	v_add_u32_e32 v59, 0x1000, v14
	ds_write2_b32 v59, v6, v7 offset0:32 offset1:98
	v_mul_f32_e32 v6, v52, v74
	v_mul_f32_e32 v7, v69, v74
	v_rndne_f32_e32 v6, v6
	v_rndne_f32_e32 v7, v7
	ds_write2_b32 v59, v6, v7 offset0:164 offset1:230
	v_mul_f32_e32 v6, v66, v74
	v_mul_f32_e32 v7, v65, v74
	v_rndne_f32_e32 v6, v6
	v_rndne_f32_e32 v7, v7
	v_add_u32_e32 v62, 0x1400, v14
	ds_write2_b32 v62, v6, v7 offset0:40 offset1:106
	v_mul_f32_e32 v6, v60, v74
	v_mul_f32_e32 v7, v58, v74
	v_rndne_f32_e32 v6, v6
	v_rndne_f32_e32 v7, v7
	ds_write2_b32 v62, v6, v7 offset0:172 offset1:238
	v_mul_f32_e32 v6, v71, v74
	v_mul_f32_e32 v7, v70, v74
	v_rndne_f32_e32 v6, v6
	v_rndne_f32_e32 v7, v7
	v_add_u32_e32 v58, 0x1800, v14
	ds_write2_b32 v58, v6, v7 offset0:48 offset1:114
	v_mul_f32_e32 v6, v68, v74
	v_mul_f32_e32 v7, v67, v74
	v_rndne_f32_e32 v6, v6
	v_rndne_f32_e32 v7, v7
	ds_write2_b32 v58, v6, v7 offset0:180 offset1:246
	v_mul_f32_e32 v6, v63, v74
	v_mul_f32_e32 v7, v73, v74
	v_rndne_f32_e32 v6, v6
	v_rndne_f32_e32 v7, v7
	v_add_u32_e32 v60, 0x1c00, v14
	ds_write2_b32 v60, v6, v7 offset0:56 offset1:122
	v_mul_f32_e32 v6, v72, v74
	v_mul_f32_e32 v7, v9, v74
	v_lshlrev_b32_e32 v1, 4, v108
	v_rndne_f32_e32 v6, v6
	v_rndne_f32_e32 v7, v7
	v_and_b32_e32 v8, 48, v1
	ds_write2_b32 v60, v6, v7 offset0:188 offset1:254
	v_mul_u32_u24_e32 v1, 0x84, v8
	s_waitcnt lgkmcnt(0)
	v_and_b32_e32 v6, 60, v108
	v_add3_u32 v1, s23, v1, v6
	ds_read2_b32 v[48:49], v1 offset1:33
	ds_read2_b32 v[50:51], v1 offset0:66 offset1:99
	v_mov_b32_e32 v9, 0
	v_lshl_add_u64 v[6:7], s[10:11], 0, v[8:9]
	v_lshl_add_u64 v[8:9], v[6:7], 0, s[20:21]
	s_waitcnt lgkmcnt(1)
	v_cvt_i32_f32_e32 v17, v49
	v_cvt_i32_f32_e32 v48, v48
	s_waitcnt lgkmcnt(0)
	v_cvt_i32_f32_sdwa v49, v50 dst_sel:WORD_1 dst_unused:UNUSED_PAD src0_sel:DWORD
	v_cvt_i32_f32_sdwa v52, v51 dst_sel:BYTE_3 dst_unused:UNUSED_PAD src0_sel:DWORD
	ds_read2_b32 v[50:51], v1 offset0:132 offset1:165
	v_lshlrev_b32_e32 v17, 8, v17
	s_mov_b32 s21, 0xc0c0500
	v_perm_b32 v17, v17, v48, s21
	v_and_b32_e32 v48, 0xff0000, v49
	v_or3_b32 v48, v17, v48, v52
	s_waitcnt lgkmcnt(0)
	v_cvt_i32_f32_e32 v17, v50
	v_cvt_i32_f32_e32 v49, v51
	ds_read2_b32 v[50:51], v1 offset0:198 offset1:231
	v_add_u32_e32 v63, 0x400, v1
	ds_read2_b32 v[52:53], v63 offset0:8 offset1:41
	v_lshlrev_b32_e32 v49, 8, v49
	v_perm_b32 v17, v49, v17, s21
	s_waitcnt lgkmcnt(1)
	v_cvt_i32_f32_sdwa v49, v50 dst_sel:WORD_1 dst_unused:UNUSED_PAD src0_sel:DWORD
	v_cvt_i32_f32_sdwa v54, v51 dst_sel:BYTE_3 dst_unused:UNUSED_PAD src0_sel:DWORD
	ds_read2_b32 v[50:51], v63 offset0:74 offset1:107
	s_waitcnt lgkmcnt(1)
	v_cvt_i32_f32_e32 v53, v53
	v_and_b32_e32 v49, 0xff0000, v49
	v_or3_b32 v49, v17, v49, v54
	v_cvt_i32_f32_e32 v17, v52
	v_lshlrev_b32_e32 v54, 8, v53
	s_waitcnt lgkmcnt(0)
	v_cvt_i32_f32_sdwa v50, v50 dst_sel:WORD_1 dst_unused:UNUSED_PAD src0_sel:DWORD
	ds_read2_b32 v[52:53], v63 offset0:140 offset1:173
	v_cvt_i32_f32_sdwa v51, v51 dst_sel:BYTE_3 dst_unused:UNUSED_PAD src0_sel:DWORD
	v_perm_b32 v17, v54, v17, s21
	ds_read2_b32 v[54:55], v63 offset0:206 offset1:239
	v_and_b32_e32 v50, 0xff0000, v50
	v_or3_b32 v50, v17, v50, v51
	s_waitcnt lgkmcnt(1)
	v_cvt_i32_f32_e32 v17, v53
	v_cvt_i32_f32_e32 v51, v52
	s_waitcnt lgkmcnt(0)
	v_cvt_i32_f32_sdwa v52, v54 dst_sel:WORD_1 dst_unused:UNUSED_PAD src0_sel:DWORD
	v_cvt_i32_f32_sdwa v53, v55 dst_sel:BYTE_3 dst_unused:UNUSED_PAD src0_sel:DWORD
	v_lshrrev_b32_e32 v16, 2, v108
	v_lshlrev_b32_e32 v17, 8, v17
	v_perm_b32 v17, v17, v51, s21
	v_and_b32_e32 v51, 0xff0000, v52
	v_or_b32_e32 v52, s68, v16
	v_or3_b32 v51, v17, v51, v53
	v_ashrrev_i32_e32 v53, 31, v52
	v_lshl_add_u64 v[6:7], v[8:9], 0, s[70:71]
	v_lshlrev_b64 v[52:53], 10, v[52:53]
	v_lshl_add_u64 v[54:55], v[6:7], 0, v[52:53]
	global_store_dwordx4 v[54:55], v[48:51], off sc1
	s_nop 1
	ds_read2_b32 v[48:49], v1 offset0:16 offset1:49
	ds_read2_b32 v[50:51], v1 offset0:82 offset1:115
	v_or_b32_e32 v17, 16, v16
	v_mul_f32_e32 v12, v12, v74
	v_mul_f32_e32 v5, v5, v74
	s_waitcnt lgkmcnt(1)
	v_cvt_i32_f32_e32 v54, v49
	v_cvt_i32_f32_e32 v55, v48
	s_waitcnt lgkmcnt(0)
	v_cvt_i32_f32_sdwa v50, v50 dst_sel:WORD_1 dst_unused:UNUSED_PAD src0_sel:DWORD
	ds_read2_b32 v[48:49], v1 offset0:148 offset1:181
	v_lshlrev_b32_e32 v54, 8, v54
	v_perm_b32 v54, v54, v55, s21
	v_and_b32_e32 v55, 0xff0000, v50
	v_cvt_i32_f32_sdwa v56, v51 dst_sel:BYTE_3 dst_unused:UNUSED_PAD src0_sel:DWORD
	ds_read2_b32 v[50:51], v1 offset0:214 offset1:247
	s_waitcnt lgkmcnt(1)
	v_cvt_i32_f32_e32 v49, v49
	v_cvt_i32_f32_e32 v57, v48
	v_or3_b32 v48, v54, v55, v56
	ds_read2_b32 v[54:55], v63 offset0:24 offset1:57
	v_lshlrev_b32_e32 v49, 8, v49
	s_waitcnt lgkmcnt(1)
	v_cvt_i32_f32_sdwa v56, v50 dst_sel:WORD_1 dst_unused:UNUSED_PAD src0_sel:DWORD
	v_perm_b32 v49, v49, v57, s21
	v_cvt_i32_f32_sdwa v57, v51 dst_sel:BYTE_3 dst_unused:UNUSED_PAD src0_sel:DWORD
	ds_read2_b32 v[50:51], v63 offset0:90 offset1:123
	s_waitcnt lgkmcnt(1)
	v_cvt_i32_f32_e32 v55, v55
	v_and_b32_e32 v56, 0xff0000, v56
	v_or3_b32 v49, v49, v56, v57
	v_cvt_i32_f32_e32 v56, v54
	v_lshlrev_b32_e32 v57, 8, v55
	s_waitcnt lgkmcnt(0)
	v_cvt_i32_f32_sdwa v50, v50 dst_sel:WORD_1 dst_unused:UNUSED_PAD src0_sel:DWORD
	ds_read2_b32 v[54:55], v63 offset0:156 offset1:189
	v_cvt_i32_f32_sdwa v51, v51 dst_sel:BYTE_3 dst_unused:UNUSED_PAD src0_sel:DWORD
	v_perm_b32 v64, v57, v56, s21
	ds_read2_b32 v[56:57], v63 offset0:222 offset1:255
	v_and_b32_e32 v50, 0xff0000, v50
	v_or3_b32 v50, v64, v50, v51
	s_waitcnt lgkmcnt(1)
	v_cvt_i32_f32_e32 v51, v55
	v_cvt_i32_f32_e32 v54, v54
	s_waitcnt lgkmcnt(0)
	v_cvt_i32_f32_sdwa v55, v56 dst_sel:WORD_1 dst_unused:UNUSED_PAD src0_sel:DWORD
	v_cvt_i32_f32_sdwa v56, v57 dst_sel:BYTE_3 dst_unused:UNUSED_PAD src0_sel:DWORD
	v_lshlrev_b32_e32 v51, 8, v51
	v_perm_b32 v51, v51, v54, s21
	v_and_b32_e32 v54, 0xff0000, v55
	v_or3_b32 v51, v51, v54, v56
	v_or_b32_e32 v54, s68, v17
	v_ashrrev_i32_e32 v55, 31, v54
	v_lshlrev_b64 v[54:55], 10, v[54:55]
	v_lshl_add_u64 v[56:57], v[6:7], 0, v[54:55]
	global_store_dwordx4 v[56:57], v[48:51], off sc1
	s_nop 1
	s_waitcnt lgkmcnt(0)
	v_rndne_f32_e32 v12, v12
	v_rndne_f32_e32 v5, v5
	ds_write2_b32 v14, v12, v5 offset1:66
	v_mul_f32_e32 v5, v24, v74
	v_mul_f32_e32 v12, v22, v74
	v_rndne_f32_e32 v5, v5
	v_rndne_f32_e32 v12, v12
	ds_write2_b32 v14, v5, v12 offset0:132 offset1:198
	v_mul_f32_e32 v5, v20, v74
	v_mul_f32_e32 v12, v19, v74
	v_rndne_f32_e32 v5, v5
	v_rndne_f32_e32 v12, v12
	ds_write2_b32 v75, v5, v12 offset0:8 offset1:74
	v_mul_f32_e32 v5, v13, v74
	v_mul_f32_e32 v12, v28, v74
	v_rndne_f32_e32 v5, v5
	v_rndne_f32_e32 v12, v12
	ds_write2_b32 v75, v5, v12 offset0:140 offset1:206
	v_mul_f32_e32 v5, v26, v74
	v_mul_f32_e32 v12, v25, v74
	v_rndne_f32_e32 v5, v5
	v_rndne_f32_e32 v12, v12
	ds_write2_b32 v61, v5, v12 offset0:16 offset1:82
	v_mul_f32_e32 v5, v23, v74
	v_mul_f32_e32 v12, v21, v74
	v_rndne_f32_e32 v5, v5
	v_rndne_f32_e32 v12, v12
	ds_write2_b32 v61, v5, v12 offset0:148 offset1:214
	v_mul_f32_e32 v5, v34, v74
	v_mul_f32_e32 v12, v32, v74
	v_rndne_f32_e32 v5, v5
	v_rndne_f32_e32 v12, v12
	ds_write2_b32 v76, v5, v12 offset0:24 offset1:90
	v_mul_f32_e32 v5, v30, v74
	v_mul_f32_e32 v12, v29, v74
	v_rndne_f32_e32 v5, v5
	v_rndne_f32_e32 v12, v12
	ds_write2_b32 v76, v5, v12 offset0:156 offset1:222
	v_mul_f32_e32 v5, v27, v74
	v_mul_f32_e32 v12, v38, v74
	v_rndne_f32_e32 v5, v5
	v_rndne_f32_e32 v12, v12
	ds_write2_b32 v59, v5, v12 offset0:32 offset1:98
	v_mul_f32_e32 v5, v36, v74
	v_mul_f32_e32 v12, v35, v74
	v_rndne_f32_e32 v5, v5
	v_rndne_f32_e32 v12, v12
	ds_write2_b32 v59, v5, v12 offset0:164 offset1:230
	v_mul_f32_e32 v5, v33, v74
	v_mul_f32_e32 v12, v31, v74
	v_rndne_f32_e32 v5, v5
	v_rndne_f32_e32 v12, v12
	ds_write2_b32 v62, v5, v12 offset0:40 offset1:106
	v_mul_f32_e32 v5, v44, v74
	v_mul_f32_e32 v12, v42, v74
	v_rndne_f32_e32 v5, v5
	v_rndne_f32_e32 v12, v12
	ds_write2_b32 v62, v5, v12 offset0:172 offset1:238
	v_mul_f32_e32 v5, v40, v74
	v_mul_f32_e32 v12, v39, v74
	v_rndne_f32_e32 v5, v5
	v_rndne_f32_e32 v12, v12
	ds_write2_b32 v58, v5, v12 offset0:48 offset1:114
	v_mul_f32_e32 v5, v37, v74
	v_mul_f32_e32 v12, v47, v74
	v_rndne_f32_e32 v5, v5
	v_rndne_f32_e32 v12, v12
	ds_write2_b32 v58, v5, v12 offset0:180 offset1:246
	v_mul_f32_e32 v5, v46, v74
	v_mul_f32_e32 v12, v45, v74
	v_rndne_f32_e32 v5, v5
	v_rndne_f32_e32 v12, v12
	ds_write2_b32 v60, v5, v12 offset0:56 offset1:122
	v_mul_f32_e32 v5, v43, v74
	v_mul_f32_e32 v12, v41, v74
	v_rndne_f32_e32 v5, v5
	v_rndne_f32_e32 v12, v12
	ds_write2_b32 v60, v5, v12 offset0:188 offset1:254
	s_waitcnt lgkmcnt(0)
	ds_read2_b32 v[12:13], v1 offset1:33
	ds_read2_b32 v[20:21], v1 offset0:66 offset1:99
	ds_read2_b32 v[22:23], v63 offset0:8 offset1:41
	s_mov_b64 s[68:69], 0xa00040
	v_lshl_add_u64 v[8:9], v[8:9], 0, s[68:69]
	s_waitcnt lgkmcnt(2)
	v_cvt_i32_f32_e32 v5, v13
	v_cvt_i32_f32_e32 v19, v12
	ds_read2_b32 v[12:13], v1 offset0:132 offset1:165
	s_waitcnt lgkmcnt(2)
	v_cvt_i32_f32_sdwa v20, v20 dst_sel:WORD_1 dst_unused:UNUSED_PAD src0_sel:DWORD
	v_lshlrev_b32_e32 v5, 8, v5
	v_perm_b32 v5, v5, v19, s21
	s_waitcnt lgkmcnt(1)
	v_cvt_i32_f32_e32 v23, v23
	v_and_b32_e32 v19, 0xff0000, v20
	v_cvt_i32_f32_sdwa v20, v21 dst_sel:BYTE_3 dst_unused:UNUSED_PAD src0_sel:DWORD
	s_waitcnt lgkmcnt(0)
	v_cvt_i32_f32_e32 v21, v12
	v_cvt_i32_f32_e32 v24, v13
	ds_read2_b32 v[12:13], v1 offset0:198 offset1:231
	v_or3_b32 v20, v5, v19, v20
	s_cmp_gt_i32 s19, 47
	v_lshlrev_b32_e32 v5, 8, v24
	v_perm_b32 v5, v5, v21, s21
	s_waitcnt lgkmcnt(0)
	v_cvt_i32_f32_sdwa v19, v12 dst_sel:WORD_1 dst_unused:UNUSED_PAD src0_sel:DWORD
	v_cvt_i32_f32_sdwa v21, v13 dst_sel:BYTE_3 dst_unused:UNUSED_PAD src0_sel:DWORD
	ds_read2_b32 v[12:13], v63 offset0:74 offset1:107
	ds_read2_b32 v[24:25], v63 offset0:206 offset1:239
	v_and_b32_e32 v19, 0xff0000, v19
	v_or3_b32 v21, v5, v19, v21
	v_cvt_i32_f32_e32 v5, v22
	v_lshlrev_b32_e32 v19, 8, v23
	s_waitcnt lgkmcnt(1)
	v_cvt_i32_f32_sdwa v22, v12 dst_sel:WORD_1 dst_unused:UNUSED_PAD src0_sel:DWORD
	v_cvt_i32_f32_sdwa v23, v13 dst_sel:BYTE_3 dst_unused:UNUSED_PAD src0_sel:DWORD
	ds_read2_b32 v[12:13], v63 offset0:140 offset1:173
	v_perm_b32 v5, v19, v5, s21
	v_and_b32_e32 v19, 0xff0000, v22
	v_or3_b32 v22, v5, v19, v23
	s_waitcnt lgkmcnt(1)
	v_cvt_i32_f32_sdwa v19, v25 dst_sel:BYTE_3 dst_unused:UNUSED_PAD src0_sel:DWORD
	s_waitcnt lgkmcnt(0)
	v_cvt_i32_f32_e32 v5, v13
	v_cvt_i32_f32_e32 v12, v12
	v_cvt_i32_f32_sdwa v13, v24 dst_sel:WORD_1 dst_unused:UNUSED_PAD src0_sel:DWORD
	s_mov_b64 s[68:69], -1
	v_lshlrev_b32_e32 v5, 8, v5
	v_perm_b32 v5, v5, v12, s21
	v_and_b32_e32 v12, 0xff0000, v13
	v_or3_b32 v23, v5, v12, v19
	v_lshl_add_u64 v[12:13], v[8:9], 0, v[52:53]
	global_store_dwordx4 v[12:13], v[20:23], off sc1
	s_nop 1
	ds_read2_b32 v[12:13], v1 offset0:16 offset1:49
	ds_read2_b32 v[20:21], v1 offset0:82 offset1:115
	ds_read2_b32 v[22:23], v63 offset0:24 offset1:57
	s_waitcnt lgkmcnt(2)
	v_cvt_i32_f32_e32 v5, v13
	v_cvt_i32_f32_e32 v19, v12
	ds_read2_b32 v[12:13], v1 offset0:148 offset1:181
	s_waitcnt lgkmcnt(2)
	v_cvt_i32_f32_sdwa v20, v20 dst_sel:WORD_1 dst_unused:UNUSED_PAD src0_sel:DWORD
	v_lshlrev_b32_e32 v5, 8, v5
	v_perm_b32 v5, v5, v19, s21
	s_waitcnt lgkmcnt(1)
	v_cvt_i32_f32_e32 v23, v23
	v_and_b32_e32 v19, 0xff0000, v20
	v_cvt_i32_f32_sdwa v20, v21 dst_sel:BYTE_3 dst_unused:UNUSED_PAD src0_sel:DWORD
	s_waitcnt lgkmcnt(0)
	v_cvt_i32_f32_e32 v21, v12
	v_cvt_i32_f32_e32 v24, v13
	ds_read2_b32 v[12:13], v1 offset0:214 offset1:247
	v_or3_b32 v20, v5, v19, v20
	v_lshlrev_b32_e32 v5, 8, v24
	v_perm_b32 v5, v5, v21, s21
	s_waitcnt lgkmcnt(0)
	v_cvt_i32_f32_sdwa v19, v12 dst_sel:WORD_1 dst_unused:UNUSED_PAD src0_sel:DWORD
	v_cvt_i32_f32_sdwa v21, v13 dst_sel:BYTE_3 dst_unused:UNUSED_PAD src0_sel:DWORD
	ds_read2_b32 v[12:13], v63 offset0:90 offset1:123
	ds_read2_b32 v[24:25], v63 offset0:222 offset1:255
	v_and_b32_e32 v19, 0xff0000, v19
	v_or3_b32 v21, v5, v19, v21
	v_cvt_i32_f32_e32 v5, v22
	v_lshlrev_b32_e32 v19, 8, v23
	s_waitcnt lgkmcnt(1)
	v_cvt_i32_f32_sdwa v22, v12 dst_sel:WORD_1 dst_unused:UNUSED_PAD src0_sel:DWORD
	v_cvt_i32_f32_sdwa v23, v13 dst_sel:BYTE_3 dst_unused:UNUSED_PAD src0_sel:DWORD
	ds_read2_b32 v[12:13], v63 offset0:156 offset1:189
	v_perm_b32 v5, v19, v5, s21
	v_and_b32_e32 v19, 0xff0000, v22
	v_or3_b32 v22, v5, v19, v23
	s_waitcnt lgkmcnt(1)
	v_cvt_i32_f32_sdwa v19, v25 dst_sel:BYTE_3 dst_unused:UNUSED_PAD src0_sel:DWORD
	s_waitcnt lgkmcnt(0)
	v_cvt_i32_f32_e32 v5, v13
	v_cvt_i32_f32_e32 v12, v12
	v_cvt_i32_f32_sdwa v13, v24 dst_sel:WORD_1 dst_unused:UNUSED_PAD src0_sel:DWORD
	v_lshlrev_b32_e32 v5, 8, v5
	v_perm_b32 v5, v5, v12, s21
	v_and_b32_e32 v12, 0xff0000, v13
	v_or3_b32 v23, v5, v12, v19
	v_lshl_add_u64 v[12:13], v[8:9], 0, v[54:55]
	global_store_dwordx4 v[12:13], v[20:23], off sc1
	s_nop 1
	s_waitcnt lgkmcnt(0)
	s_barrier
	s_cbranch_scc0 .LBB0_54
	s_lshl_b32 s21, s33, 3
	v_readlane_b32 s23, v249, 0
	s_add_i32 s21, s23, s21
	s_addk_i32 s21, 0xfe80
	s_cmpk_gt_i32 s21, 0x1ff
	s_cbranch_scc1 .LBB0_53
	s_ashr_i32 s23, s21, 31
	s_lshr_b32 s23, s23, 27
	s_add_i32 s23, s21, s23
	s_load_dwordx2 s[70:71], s[16:17], 0x20
	s_and_b32 s33, s23, 0x7ffffe0
	s_sub_i32 s21, s21, s33
	s_lshl_b32 s23, s23, 1
	s_lshl_b32 vcc_lo, s21, 5
	s_and_b32 s68, s23, 0xffffffc0
	s_ashr_i32 vcc_hi, vcc_lo, 31
	v_or_b32_e32 v12, s68, v11
	s_mov_b32 s21, s72
	s_mov_b32 s23, s73
	s_lshl_b64 s[72:73], vcc, 2
	s_waitcnt lgkmcnt(0)
	s_add_u32 s70, s70, s72
	v_or_b32_e32 v24, 2, v12
	v_or_b32_e32 v26, 4, v12
	v_or_b32_e32 v28, 6, v12
	v_or_b32_e32 v30, 8, v12
	v_or_b32_e32 v32, 10, v12
	v_or_b32_e32 v34, 12, v12
	v_or_b32_e32 v36, 14, v12
	s_addc_u32 s71, s71, s73
	v_mov_b32_e32 v11, 0
	v_ashrrev_i32_e32 v13, 31, v12
	v_ashrrev_i32_e32 v25, 31, v24
	v_ashrrev_i32_e32 v27, 31, v26
	v_ashrrev_i32_e32 v29, 31, v28
	v_ashrrev_i32_e32 v31, 31, v30
	v_ashrrev_i32_e32 v33, 31, v32
	v_ashrrev_i32_e32 v35, 31, v34
	v_ashrrev_i32_e32 v37, 31, v36
	v_lshl_add_u64 v[20:21], s[70:71], 0, v[10:11]
	v_lshlrev_b64 v[22:23], 12, v[12:13]
	v_lshlrev_b64 v[24:25], 12, v[24:25]
	v_lshlrev_b64 v[26:27], 12, v[26:27]
	v_lshlrev_b64 v[28:29], 12, v[28:29]
	v_lshlrev_b64 v[30:31], 12, v[30:31]
	v_lshlrev_b64 v[32:33], 12, v[32:33]
	v_lshlrev_b64 v[34:35], 12, v[34:35]
	v_lshlrev_b64 v[36:37], 12, v[36:37]
	v_lshl_add_u64 v[22:23], v[20:21], 0, v[22:23]
	v_lshl_add_u64 v[24:25], v[20:21], 0, v[24:25]
	v_lshl_add_u64 v[26:27], v[20:21], 0, v[26:27]
	v_lshl_add_u64 v[28:29], v[20:21], 0, v[28:29]
	v_lshl_add_u64 v[30:31], v[20:21], 0, v[30:31]
	v_lshl_add_u64 v[32:33], v[20:21], 0, v[32:33]
	v_lshl_add_u64 v[34:35], v[20:21], 0, v[34:35]
	v_lshl_add_u64 v[36:37], v[20:21], 0, v[36:37]
	global_load_dword v5, v[22:23], off nt
	global_load_dword v10, v[24:25], off nt
	global_load_dword v19, v[26:27], off nt
	global_load_dword v38, v[28:29], off nt
	global_load_dword v39, v[30:31], off nt
	global_load_dword v40, v[32:33], off nt
	global_load_dword v41, v[34:35], off nt
	global_load_dword v42, v[36:37], off nt
	v_or_b32_e32 v22, 16, v12
	v_or_b32_e32 v24, 18, v12
	v_or_b32_e32 v26, 20, v12
	v_or_b32_e32 v28, 22, v12
	v_or_b32_e32 v30, 24, v12
	v_or_b32_e32 v32, 26, v12
	v_or_b32_e32 v34, 28, v12
	v_or_b32_e32 v36, 30, v12
	v_ashrrev_i32_e32 v23, 31, v22
	v_ashrrev_i32_e32 v25, 31, v24
	v_ashrrev_i32_e32 v27, 31, v26
	v_ashrrev_i32_e32 v29, 31, v28
	v_ashrrev_i32_e32 v31, 31, v30
	v_ashrrev_i32_e32 v33, 31, v32
	v_ashrrev_i32_e32 v35, 31, v34
	v_ashrrev_i32_e32 v37, 31, v36
	v_lshlrev_b64 v[22:23], 12, v[22:23]
	v_lshlrev_b64 v[24:25], 12, v[24:25]
	v_lshlrev_b64 v[26:27], 12, v[26:27]
	v_lshlrev_b64 v[28:29], 12, v[28:29]
	v_lshlrev_b64 v[30:31], 12, v[30:31]
	v_lshlrev_b64 v[32:33], 12, v[32:33]
	v_lshlrev_b64 v[34:35], 12, v[34:35]
	v_lshlrev_b64 v[36:37], 12, v[36:37]
	v_lshl_add_u64 v[22:23], v[20:21], 0, v[22:23]
	v_lshl_add_u64 v[24:25], v[20:21], 0, v[24:25]
	v_lshl_add_u64 v[26:27], v[20:21], 0, v[26:27]
	v_lshl_add_u64 v[28:29], v[20:21], 0, v[28:29]
	v_lshl_add_u64 v[30:31], v[20:21], 0, v[30:31]
	v_lshl_add_u64 v[32:33], v[20:21], 0, v[32:33]
	v_lshl_add_u64 v[34:35], v[20:21], 0, v[34:35]
	v_lshl_add_u64 v[36:37], v[20:21], 0, v[36:37]
	global_load_dword v43, v[22:23], off nt
	global_load_dword v44, v[24:25], off nt
	global_load_dword v45, v[26:27], off nt
	global_load_dword v46, v[28:29], off nt
	global_load_dword v47, v[30:31], off nt
	global_load_dword v48, v[32:33], off nt
	global_load_dword v49, v[34:35], off nt
	global_load_dword v50, v[36:37], off nt
	v_or_b32_e32 v22, 32, v12
	v_or_b32_e32 v24, 34, v12
	v_or_b32_e32 v26, 36, v12
	v_or_b32_e32 v28, 38, v12
	v_or_b32_e32 v30, 40, v12
	v_or_b32_e32 v32, 42, v12
	v_or_b32_e32 v34, 44, v12
	v_or_b32_e32 v36, 46, v12
	v_ashrrev_i32_e32 v23, 31, v22
	v_ashrrev_i32_e32 v25, 31, v24
	v_ashrrev_i32_e32 v27, 31, v26
	v_ashrrev_i32_e32 v29, 31, v28
	v_ashrrev_i32_e32 v31, 31, v30
	v_ashrrev_i32_e32 v33, 31, v32
	v_ashrrev_i32_e32 v35, 31, v34
	v_ashrrev_i32_e32 v37, 31, v36
	v_lshlrev_b64 v[22:23], 12, v[22:23]
	v_lshlrev_b64 v[24:25], 12, v[24:25]
	v_lshlrev_b64 v[26:27], 12, v[26:27]
	v_lshlrev_b64 v[28:29], 12, v[28:29]
	v_lshlrev_b64 v[30:31], 12, v[30:31]
	v_lshlrev_b64 v[32:33], 12, v[32:33]
	v_lshlrev_b64 v[34:35], 12, v[34:35]
	v_lshlrev_b64 v[36:37], 12, v[36:37]
	v_lshl_add_u64 v[22:23], v[20:21], 0, v[22:23]
	v_lshl_add_u64 v[24:25], v[20:21], 0, v[24:25]
	v_lshl_add_u64 v[26:27], v[20:21], 0, v[26:27]
	v_lshl_add_u64 v[28:29], v[20:21], 0, v[28:29]
	v_lshl_add_u64 v[30:31], v[20:21], 0, v[30:31]
	v_lshl_add_u64 v[32:33], v[20:21], 0, v[32:33]
	v_lshl_add_u64 v[34:35], v[20:21], 0, v[34:35]
	v_lshl_add_u64 v[36:37], v[20:21], 0, v[36:37]
	global_load_dword v51, v[22:23], off nt
	global_load_dword v52, v[24:25], off nt
	global_load_dword v53, v[26:27], off nt
	global_load_dword v54, v[28:29], off nt
	global_load_dword v55, v[30:31], off nt
	global_load_dword v56, v[32:33], off nt
	global_load_dword v57, v[34:35], off nt
	s_nop 0
	global_load_dword v36, v[36:37], off nt
	v_or_b32_e32 v22, 48, v12
	v_or_b32_e32 v24, 50, v12
	v_or_b32_e32 v26, 52, v12
	v_or_b32_e32 v28, 54, v12
	v_or_b32_e32 v30, 56, v12
	v_or_b32_e32 v32, 58, v12
	v_or_b32_e32 v34, 60, v12
	v_or_b32_e32 v12, 62, v12
	v_ashrrev_i32_e32 v23, 31, v22
	v_ashrrev_i32_e32 v25, 31, v24
	v_ashrrev_i32_e32 v27, 31, v26
	v_ashrrev_i32_e32 v13, 31, v12
	v_lshlrev_b64 v[22:23], 12, v[22:23]
	v_lshlrev_b64 v[24:25], 12, v[24:25]
	v_lshlrev_b64 v[26:27], 12, v[26:27]
	v_ashrrev_i32_e32 v29, 31, v28
	v_ashrrev_i32_e32 v31, 31, v30
	v_ashrrev_i32_e32 v33, 31, v32
	v_ashrrev_i32_e32 v35, 31, v34
	v_lshlrev_b64 v[12:13], 12, v[12:13]
	v_lshl_add_u64 v[22:23], v[20:21], 0, v[22:23]
	v_lshl_add_u64 v[24:25], v[20:21], 0, v[24:25]
	v_lshl_add_u64 v[26:27], v[20:21], 0, v[26:27]
	v_lshlrev_b64 v[28:29], 12, v[28:29]
	v_lshlrev_b64 v[30:31], 12, v[30:31]
	v_lshlrev_b64 v[32:33], 12, v[32:33]
	v_lshlrev_b64 v[34:35], 12, v[34:35]
	v_lshl_add_u64 v[12:13], v[20:21], 0, v[12:13]
	v_lshl_add_u64 v[28:29], v[20:21], 0, v[28:29]
	v_lshl_add_u64 v[30:31], v[20:21], 0, v[30:31]
	v_lshl_add_u64 v[32:33], v[20:21], 0, v[32:33]
	v_lshl_add_u64 v[34:35], v[20:21], 0, v[34:35]
	global_load_dword v20, v[22:23], off nt
	global_load_dword v21, v[24:25], off nt
	s_nop 0
	global_load_dword v22, v[26:27], off nt
	global_load_dword v23, v[28:29], off nt
	global_load_dword v24, v[30:31], off nt
	global_load_dword v25, v[32:33], off nt
	s_nop 0
	global_load_dword v26, v[34:35], off nt
	s_nop 0
	global_load_dword v12, v[12:13], off nt
	s_waitcnt vmcnt(30)
	ds_write2_b32 v14, v5, v10 offset1:66
	s_waitcnt vmcnt(28)
	ds_write2_b32 v14, v19, v38 offset0:132 offset1:198
	v_add_u32_e32 v5, 0x400, v14
	s_waitcnt vmcnt(26)
	ds_write2_b32 v5, v39, v40 offset0:8 offset1:74
	s_waitcnt vmcnt(24)
	ds_write2_b32 v5, v41, v42 offset0:140 offset1:206
	v_add_u32_e32 v5, 0x800, v14
	s_waitcnt vmcnt(22)
	ds_write2_b32 v5, v43, v44 offset0:16 offset1:82
	s_waitcnt vmcnt(20)
	ds_write2_b32 v5, v45, v46 offset0:148 offset1:214
	v_add_u32_e32 v5, 0xc00, v14
	s_waitcnt vmcnt(18)
	ds_write2_b32 v5, v47, v48 offset0:24 offset1:90
	s_waitcnt vmcnt(16)
	ds_write2_b32 v5, v49, v50 offset0:156 offset1:222
	v_add_u32_e32 v5, 0x1000, v14
	s_waitcnt vmcnt(14)
	ds_write2_b32 v5, v51, v52 offset0:32 offset1:98
	s_waitcnt vmcnt(12)
	ds_write2_b32 v5, v53, v54 offset0:164 offset1:230
	v_add_u32_e32 v5, 0x1400, v14
	s_waitcnt vmcnt(10)
	ds_write2_b32 v5, v55, v56 offset0:40 offset1:106
	s_waitcnt vmcnt(8)
	ds_write2_b32 v5, v57, v36 offset0:172 offset1:238
	v_add_u32_e32 v5, 0x1800, v14
	s_waitcnt vmcnt(6)
	ds_write2_b32 v5, v20, v21 offset0:48 offset1:114
	s_waitcnt vmcnt(4)
	ds_write2_b32 v5, v22, v23 offset0:180 offset1:246
	v_add_u32_e32 v5, 0x1c00, v14
	v_lshlrev_b32_e32 v10, 3, v108
	s_waitcnt vmcnt(2)
	ds_write2_b32 v5, v24, v25 offset0:56 offset1:122
	s_waitcnt vmcnt(0)
	ds_write2_b32 v5, v26, v12 offset0:188 offset1:254
	v_lshrrev_b32_e32 v5, 3, v108
	v_and_b32_e32 v10, 56, v10
	s_mov_b32 s72, s21
	s_waitcnt lgkmcnt(0)
	v_mul_u32_u24_e32 v12, 0x84, v10
	v_lshlrev_b32_e32 v13, 2, v5
	v_readlane_b32 s21, v249, 5
	s_ashr_i32 s69, s68, 31
	s_lshl_b64 s[68:69], s[68:69], 1
	v_add3_u32 v19, s21, v12, v13
	ds_read2_b32 v[12:13], v19 offset1:33
	s_add_u32 s68, s10, s68
	s_addc_u32 s69, s11, s69
	v_lshlrev_b32_e32 v10, 1, v10
	ds_read2_b32 v[22:23], v19 offset0:66 offset1:99
	v_lshl_add_u64 v[10:11], s[68:69], 0, v[10:11]
	s_mov_b64 s[68:69], 0x800000
	v_lshl_add_u64 v[20:21], v[10:11], 0, s[68:69]
	s_waitcnt lgkmcnt(1)
	v_bfe_u32 v10, v12, 16, 1
	s_movk_i32 s21, 0x7fff
	v_bfe_u32 v11, v13, 16, 1
	v_add3_u32 v10, v12, v10, s21
	v_add3_u32 v11, v13, v11, s21
	ds_read2_b32 v[12:13], v19 offset0:132 offset1:165
	s_mov_b32 s73, s23
	v_lshrrev_b32_e32 v10, 16, v10
	s_mov_b32 s23, 0xffff0000
	v_and_or_b32 v10, v11, s23, v10
	s_waitcnt lgkmcnt(1)
	v_bfe_u32 v11, v22, 16, 1
	v_add3_u32 v11, v22, v11, s21
	v_bfe_u32 v22, v23, 16, 1
	v_lshrrev_b32_e32 v11, 16, v11
	v_add3_u32 v22, v23, v22, s21
	v_and_or_b32 v11, v22, s23, v11
	s_waitcnt lgkmcnt(0)
	v_bfe_u32 v22, v12, 16, 1
	v_add3_u32 v12, v12, v22, s21
	ds_read2_b32 v[22:23], v19 offset0:198 offset1:231
	v_bfe_u32 v24, v13, 16, 1
	v_lshrrev_b32_e32 v12, 16, v12
	v_add3_u32 v13, v13, v24, s21
	v_and_or_b32 v12, v13, s23, v12
	s_waitcnt lgkmcnt(0)
	v_bfe_u32 v13, v22, 16, 1
	v_add3_u32 v13, v22, v13, s21
	v_bfe_u32 v22, v23, 16, 1
	v_lshrrev_b32_e32 v13, 16, v13
	v_add3_u32 v22, v23, v22, s21
	v_and_or_b32 v13, v22, s23, v13
	v_or_b32_e32 v22, vcc_lo, v5
	v_ashrrev_i32_e32 v23, 31, v22
	v_lshlrev_b64 v[24:25], 11, v[22:23]
	v_lshl_add_u64 v[24:25], v[20:21], 0, v[24:25]
	global_store_dwordx4 v[24:25], v[10:13], off sc1
	s_nop 1
	ds_read2_b32 v[10:11], v19 offset0:8 offset1:41
	ds_read2_b32 v[12:13], v19 offset0:74 offset1:107
	ds_read2_b32 v[24:25], v19 offset0:140 offset1:173
	ds_read2_b32 v[26:27], v19 offset0:206 offset1:239
	s_mov_b32 s33, s19
	s_waitcnt lgkmcnt(3)
	v_bfe_u32 v5, v10, 16, 1
	v_add3_u32 v5, v10, v5, s21
	v_bfe_u32 v10, v11, 16, 1
	v_lshrrev_b32_e32 v5, 16, v5
	v_add3_u32 v10, v11, v10, s21
	v_and_or_b32 v10, v10, s23, v5
	s_waitcnt lgkmcnt(2)
	v_bfe_u32 v5, v12, 16, 1
	v_add3_u32 v5, v12, v5, s21
	v_bfe_u32 v11, v13, 16, 1
	v_lshrrev_b32_e32 v5, 16, v5
	v_add3_u32 v11, v13, v11, s21
	v_and_or_b32 v11, v11, s23, v5
	s_waitcnt lgkmcnt(1)
	v_bfe_u32 v5, v24, 16, 1
	v_add3_u32 v5, v24, v5, s21
	v_bfe_u32 v12, v25, 16, 1
	v_lshrrev_b32_e32 v5, 16, v5
	v_add3_u32 v12, v25, v12, s21
	v_and_or_b32 v12, v12, s23, v5
	s_waitcnt lgkmcnt(0)
	v_bfe_u32 v5, v26, 16, 1
	v_or_b32_e32 v24, 8, v22
	v_add3_u32 v5, v26, v5, s21
	v_bfe_u32 v13, v27, 16, 1
	v_ashrrev_i32_e32 v25, 31, v24
	v_lshrrev_b32_e32 v5, 16, v5
	v_add3_u32 v13, v27, v13, s21
	v_lshlrev_b64 v[24:25], 11, v[24:25]
	v_and_or_b32 v13, v13, s23, v5
	v_lshl_add_u64 v[24:25], v[20:21], 0, v[24:25]
	global_store_dwordx4 v[24:25], v[10:13], off sc1
	s_nop 1
	ds_read2_b32 v[10:11], v19 offset0:16 offset1:49
	ds_read2_b32 v[12:13], v19 offset0:82 offset1:115
	ds_read2_b32 v[24:25], v19 offset0:148 offset1:181
	ds_read2_b32 v[26:27], v19 offset0:214 offset1:247
	s_waitcnt lgkmcnt(3)
	v_bfe_u32 v5, v10, 16, 1
	v_add3_u32 v5, v10, v5, s21
	v_bfe_u32 v10, v11, 16, 1
	v_lshrrev_b32_e32 v5, 16, v5
	v_add3_u32 v10, v11, v10, s21
	v_and_or_b32 v10, v10, s23, v5
	s_waitcnt lgkmcnt(2)
	v_bfe_u32 v5, v12, 16, 1
	v_add3_u32 v5, v12, v5, s21
	v_bfe_u32 v11, v13, 16, 1
	v_lshrrev_b32_e32 v5, 16, v5
	v_add3_u32 v11, v13, v11, s21
	v_and_or_b32 v11, v11, s23, v5
	s_waitcnt lgkmcnt(1)
	v_bfe_u32 v5, v24, 16, 1
	v_add3_u32 v5, v24, v5, s21
	v_bfe_u32 v12, v25, 16, 1
	v_lshrrev_b32_e32 v5, 16, v5
	v_add3_u32 v12, v25, v12, s21
	v_and_or_b32 v12, v12, s23, v5
	s_waitcnt lgkmcnt(0)
	v_bfe_u32 v5, v26, 16, 1
	v_or_b32_e32 v24, 16, v22
	v_add3_u32 v5, v26, v5, s21
	v_bfe_u32 v13, v27, 16, 1
	v_ashrrev_i32_e32 v25, 31, v24
	v_lshrrev_b32_e32 v5, 16, v5
	v_add3_u32 v13, v27, v13, s21
	v_lshlrev_b64 v[24:25], 11, v[24:25]
	v_and_or_b32 v13, v13, s23, v5
	v_lshl_add_u64 v[24:25], v[20:21], 0, v[24:25]
	global_store_dwordx4 v[24:25], v[10:13], off sc1
	s_nop 1
	ds_read2_b32 v[10:11], v19 offset0:24 offset1:57
	ds_read2_b32 v[12:13], v19 offset0:90 offset1:123
	ds_read2_b32 v[24:25], v19 offset0:156 offset1:189
	ds_read2_b32 v[26:27], v19 offset0:222 offset1:255
	v_or_b32_e32 v22, 24, v22
	s_waitcnt lgkmcnt(3)
	v_bfe_u32 v5, v10, 16, 1
	v_add3_u32 v5, v10, v5, s21
	v_bfe_u32 v10, v11, 16, 1
	v_lshrrev_b32_e32 v5, 16, v5
	v_add3_u32 v10, v11, v10, s21
	v_and_or_b32 v10, v10, s23, v5
	s_waitcnt lgkmcnt(2)
	v_bfe_u32 v5, v12, 16, 1
	v_add3_u32 v5, v12, v5, s21
	v_bfe_u32 v11, v13, 16, 1
	v_lshrrev_b32_e32 v5, 16, v5
	v_add3_u32 v11, v13, v11, s21
	v_and_or_b32 v11, v11, s23, v5
	s_waitcnt lgkmcnt(1)
	v_bfe_u32 v5, v24, 16, 1
	v_add3_u32 v5, v24, v5, s21
	v_bfe_u32 v12, v25, 16, 1
	v_lshrrev_b32_e32 v5, 16, v5
	v_add3_u32 v12, v25, v12, s21
	v_and_or_b32 v12, v12, s23, v5
	s_waitcnt lgkmcnt(0)
	v_bfe_u32 v5, v26, 16, 1
	v_add3_u32 v5, v26, v5, s21
	v_bfe_u32 v13, v27, 16, 1
	v_ashrrev_i32_e32 v23, 31, v22
	v_lshrrev_b32_e32 v5, 16, v5
	v_add3_u32 v13, v27, v13, s21
	v_lshlrev_b64 v[22:23], 11, v[22:23]
	v_and_or_b32 v13, v13, s23, v5
	v_lshl_add_u64 v[20:21], v[20:21], 0, v[22:23]
	global_store_dwordx4 v[20:21], v[10:13], off sc1
	s_nop 1
	s_waitcnt lgkmcnt(0)

.LBB0_54:
	s_andn2_b64 vcc, exec, s[68:69]
	v_readlane_b32 s68, v249, 6
	v_readlane_b32 s69, v249, 7
	s_cbranch_vccnz .LBB0_64
	s_mov_b32 s21, s1
	s_mov_b32 s19, s0
	s_mov_b64 s[0:1], s[8:9]
	s_mov_b64 s[8:9], s[4:5]
	s_mov_b64 s[4:5], s[96:97]
	s_mov_b64 s[96:97], s[94:95]
	s_mov_b64 s[94:95], s[92:93]
	s_mov_b64 s[92:93], s[90:91]
	s_mov_b64 s[90:91], s[88:89]
	s_mov_b64 s[88:89], s[86:87]
	s_mov_b64 s[86:87], s[84:85]
	s_mov_b64 s[84:85], s[82:83]
	s_mov_b64 s[82:83], s[80:81]
	s_mov_b64 s[80:81], s[74:75]
	s_mov_b64 s[74:75], s[78:79]
	s_mov_b64 s[70:71], s[76:77]
	s_load_dwordx4 s[76:79], s[16:17], 0x30
	v_readlane_b32 s68, v249, 44
	v_readlane_b32 s69, v249, 45
	v_mov_b32_e32 v10, 1.0
	s_and_b64 vcc, exec, s[68:69]
	v_mov_b32_e32 v11, 1.0
	s_cbranch_vccnz .LBB0_57
	s_waitcnt lgkmcnt(0)
	v_lshl_add_u64 v[12:13], v[2:3], 2, s[76:77]
	global_load_dword v11, v[12:13], off nt
.LBB0_57:
	s_addk_i32 s22, 0x1000
	s_ashr_i32 s23, s22, 31
	s_lshl_b64 s[68:69], s[22:23], 2
	s_waitcnt lgkmcnt(0)
	s_add_u32 s68, s78, s68
	s_addc_u32 s69, s79, s69
	v_mov_b32_e32 v5, 0
	v_lshl_add_u64 v[4:5], s[68:69], 0, v[4:5]
	v_lshl_add_u64 v[12:13], s[70:71], 2, v[4:5]
	v_lshl_add_u64 v[28:29], s[86:87], 2, v[4:5]
	v_lshl_add_u64 v[20:21], s[74:75], 2, v[4:5]
	v_lshl_add_u64 v[22:23], s[80:81], 2, v[4:5]
	v_lshl_add_u64 v[24:25], s[82:83], 2, v[4:5]
	v_lshl_add_u64 v[26:27], s[84:85], 2, v[4:5]
	v_lshl_add_u64 v[30:31], s[88:89], 2, v[4:5]
	v_lshl_add_u64 v[32:33], s[90:91], 2, v[4:5]
	global_load_dword v43, v[12:13], off nt
	global_load_dword v44, v[20:21], off nt
	global_load_dword v49, v[22:23], off nt
	global_load_dword v46, v[24:25], off nt
	global_load_dword v47, v[26:27], off nt
	global_load_dword v48, v[28:29], off nt
	global_load_dword v51, v[30:31], off nt
	global_load_dword v52, v[32:33], off nt
	v_lshl_add_u64 v[28:29], s[0:1], 2, v[4:5]
	v_readlane_b32 s0, v249, 8
	v_readlane_b32 s1, v249, 9
	v_lshl_add_u64 v[12:13], s[92:93], 2, v[4:5]
	v_lshl_add_u64 v[20:21], s[94:95], 2, v[4:5]
	v_lshl_add_u64 v[30:31], s[0:1], 2, v[4:5]
	v_readlane_b32 s0, v249, 10
	v_readlane_b32 s1, v249, 11
	v_lshl_add_u64 v[22:23], s[96:97], 2, v[4:5]
	v_lshl_add_u64 v[24:25], s[4:5], 2, v[4:5]
	v_lshl_add_u64 v[32:33], s[0:1], 2, v[4:5]
	v_readlane_b32 s0, v249, 12
	v_readlane_b32 s1, v249, 13
	v_lshl_add_u64 v[26:27], s[8:9], 2, v[4:5]
	global_load_dword v56, v[12:13], off nt
	global_load_dword v57, v[20:21], off nt
	global_load_dword v58, v[22:23], off nt
	global_load_dword v60, v[24:25], off nt
	global_load_dword v61, v[26:27], off nt
	s_nop 0
	global_load_dword v12, v[28:29], off nt
	global_load_dword v53, v[30:31], off nt
	global_load_dword v55, v[32:33], off nt
	v_lshl_add_u64 v[20:21], s[0:1], 2, v[4:5]
	v_readlane_b32 s0, v249, 14
	v_readlane_b32 s1, v249, 15
	v_or_b32_e32 v80, 8, v15
	v_or_b32_e32 v79, 16, v15
	v_lshl_add_u64 v[22:23], s[0:1], 2, v[4:5]
	v_readlane_b32 s0, v249, 16
	v_readlane_b32 s1, v249, 17
	v_or_b32_e32 v78, 24, v15
	v_or_b32_e32 v77, 32, v15
	v_lshl_add_u64 v[24:25], s[0:1], 2, v[4:5]
	v_readlane_b32 s0, v249, 18
	v_readlane_b32 s1, v249, 19
	v_or_b32_e32 v76, 40, v15
	v_or_b32_e32 v67, 48, v15
	v_lshl_add_u64 v[26:27], s[0:1], 2, v[4:5]
	v_readlane_b32 s0, v249, 20
	v_readlane_b32 s1, v249, 21
	v_or_b32_e32 v13, 56, v15
	v_or_b32_e32 v19, 0x58, v15
	v_lshl_add_u64 v[28:29], s[0:1], 2, v[4:5]
	v_readlane_b32 s0, v249, 22
	v_readlane_b32 s1, v249, 23
	v_or_b32_e32 v38, 0xc0, v15
	v_or_b32_e32 v37, 0xc8, v15
	v_lshl_add_u64 v[30:31], s[0:1], 2, v[4:5]
	v_readlane_b32 s0, v249, 24
	v_readlane_b32 s1, v249, 25
	v_or_b32_e32 v36, 0xd0, v15
	v_or_b32_e32 v42, 0xe0, v15
	v_lshl_add_u64 v[32:33], s[0:1], 2, v[4:5]
	v_readlane_b32 s0, v249, 26
	v_readlane_b32 s1, v249, 27
	v_or_b32_e32 v41, 0xe8, v15
	v_or_b32_e32 v39, 0xf0, v15
	v_lshl_add_u64 v[34:35], s[0:1], 2, v[4:5]
	v_readlane_b32 s0, v249, 28
	v_readlane_b32 s1, v249, 29
	global_load_dword v66, v[20:21], off nt
	global_load_dword v68, v[22:23], off nt
	global_load_dword v63, v[24:25], off nt
	global_load_dword v64, v[26:27], off nt
	global_load_dword v69, v[28:29], off nt
	global_load_dword v70, v[30:31], off nt
	global_load_dword v71, v[32:33], off nt
	global_load_dword v62, v[34:35], off nt
	v_lshl_add_u64 v[20:21], s[0:1], 2, v[4:5]
	v_readlane_b32 s0, v249, 30
	v_readlane_b32 s1, v249, 31
	v_or_b32_e32 v40, 0xf8, v15
	s_nop 0
	v_lshl_add_u64 v[22:23], s[0:1], 2, v[4:5]
	v_readlane_b32 s0, v249, 32
	v_readlane_b32 s1, v249, 33
	s_nop 1
	v_lshl_add_u64 v[24:25], s[0:1], 2, v[4:5]
	v_readlane_b32 s0, v249, 34
	v_readlane_b32 s1, v249, 35
	s_nop 1
	v_lshl_add_u64 v[26:27], s[0:1], 2, v[4:5]
	v_readlane_b32 s0, v249, 36
	v_readlane_b32 s1, v249, 37
	s_nop 1
	v_lshl_add_u64 v[28:29], s[0:1], 2, v[4:5]
	v_readlane_b32 s0, v249, 38
	v_readlane_b32 s1, v249, 39
	s_nop 1
	v_lshl_add_u64 v[30:31], s[0:1], 2, v[4:5]
	v_readlane_b32 s0, v249, 40
	v_readlane_b32 s1, v249, 41
	s_nop 1
	v_lshl_add_u64 v[32:33], s[0:1], 2, v[4:5]
	v_readlane_b32 s0, v249, 42
	v_readlane_b32 s1, v249, 43
	s_nop 1
	v_lshl_add_u64 v[34:35], s[0:1], 2, v[4:5]
	global_load_dword v75, v[20:21], off nt
	global_load_dword v83, v[22:23], off nt
	global_load_dword v84, v[24:25], off nt
	global_load_dword v85, v[26:27], off nt
	global_load_dword v73, v[28:29], off nt
	global_load_dword v74, v[30:31], off nt
	global_load_dword v81, v[32:33], off nt
	global_load_dword v82, v[34:35], off nt
	v_readlane_b32 s0, v249, 44
	v_readlane_b32 s1, v249, 45
	v_or_b32_e32 v22, 64, v15
	v_or_b32_e32 v21, 0x48, v15
	v_or_b32_e32 v20, 0x50, v15
	v_or_b32_e32 v26, 0x60, v15
	v_or_b32_e32 v25, 0x68, v15
	v_or_b32_e32 v24, 0x70, v15
	v_or_b32_e32 v23, 0x78, v15
	v_or_b32_e32 v30, 0x80, v15
	v_or_b32_e32 v29, 0x88, v15
	v_or_b32_e32 v28, 0x90, v15
	v_or_b32_e32 v27, 0x98, v15
	v_or_b32_e32 v34, 0xa0, v15
	v_or_b32_e32 v33, 0xa8, v15
	v_or_b32_e32 v32, 0xb0, v15
	v_or_b32_e32 v31, 0xb8, v15
	v_or_b32_e32 v35, 0xd8, v15
	s_and_b64 vcc, exec, s[0:1]
	s_cbranch_vccnz .LBB0_59
	v_lshl_add_u64 v[2:3], v[2:3], 2, s[76:77]
	global_load_dword v10, v[2:3], off offset:256 nt
.LBB0_59:
	v_readlane_b32 s0, v249, 46
	v_readlane_b32 s1, v249, 47
	v_lshl_add_u64 v[98:99], s[12:13], 2, v[4:5]
	s_waitcnt vmcnt(32)
	ds_bpermute_b32 v45, v15, v11
	v_lshl_add_u64 v[2:3], s[0:1], 2, v[4:5]
	v_readlane_b32 s0, v249, 48
	v_readlane_b32 s1, v249, 49
	ds_bpermute_b32 v54, v79, v11
	ds_bpermute_b32 v50, v80, v11
	v_lshl_add_u64 v[86:87], s[0:1], 2, v[4:5]
	v_readlane_b32 s0, v249, 50
	v_readlane_b32 s1, v249, 51
	s_waitcnt vmcnt(31) lgkmcnt(2)
	v_mul_f32_e32 v45, v43, v45
	s_waitcnt vmcnt(29) lgkmcnt(1)
	v_mul_f32_e32 v43, v49, v54
	v_lshl_add_u64 v[88:89], s[0:1], 2, v[4:5]
	v_readlane_b32 s0, v249, 52
	v_readlane_b32 s1, v249, 53
	ds_bpermute_b32 v59, v13, v11
	s_waitcnt lgkmcnt(1)
	v_mul_f32_e32 v44, v44, v50
	v_lshl_add_u64 v[90:91], s[0:1], 2, v[4:5]
	v_readlane_b32 s0, v249, 54
	v_readlane_b32 s1, v249, 55
	s_waitcnt vmcnt(0)
	ds_bpermute_b32 v13, v13, v10
	v_lshl_add_u64 v[92:93], s[0:1], 2, v[4:5]
	v_readlane_b32 s0, v249, 56
	v_readlane_b32 s1, v249, 57
	s_nop 1
	v_lshl_add_u64 v[94:95], s[0:1], 2, v[4:5]
	v_readlane_b32 s0, v249, 58
	v_readlane_b32 s1, v249, 59
	s_nop 1
	v_lshl_add_u64 v[96:97], s[0:1], 2, v[4:5]
	global_load_dword v100, v[2:3], off nt
	global_load_dword v101, v[86:87], off nt
	global_load_dword v102, v[88:89], off nt
	global_load_dword v103, v[90:91], off nt
	global_load_dword v104, v[92:93], off nt
	global_load_dword v105, v[94:95], off nt
	global_load_dword v106, v[96:97], off nt
	global_load_dword v107, v[98:99], off nt
	v_lshl_add_u64 v[2:3], s[14:15], 2, v[4:5]
	v_lshl_add_u64 v[86:87], s[6:7], 2, v[4:5]
	v_lshl_add_u64 v[88:89], s[2:3], 2, v[4:5]
	v_lshl_add_u64 v[90:91], s[24:25], 2, v[4:5]
	v_lshl_add_u64 v[92:93], s[26:27], 2, v[4:5]
	v_lshl_add_u64 v[94:95], s[28:29], 2, v[4:5]
	v_lshl_add_u64 v[96:97], s[30:31], 2, v[4:5]
	v_lshl_add_u64 v[98:99], s[34:35], 2, v[4:5]
	global_load_dword v109, v[2:3], off nt
	global_load_dword v110, v[86:87], off nt
	global_load_dword v111, v[88:89], off nt
	global_load_dword v112, v[90:91], off nt
	global_load_dword v113, v[92:93], off nt
	global_load_dword v114, v[94:95], off nt
	global_load_dword v115, v[96:97], off nt
	global_load_dword v116, v[98:99], off nt
	v_lshl_add_u64 v[2:3], s[36:37], 2, v[4:5]
	v_lshl_add_u64 v[86:87], s[38:39], 2, v[4:5]
	v_lshl_add_u64 v[88:89], s[40:41], 2, v[4:5]
	v_lshl_add_u64 v[90:91], s[42:43], 2, v[4:5]
	v_lshl_add_u64 v[92:93], s[44:45], 2, v[4:5]
	v_lshl_add_u64 v[94:95], s[46:47], 2, v[4:5]
	v_lshl_add_u64 v[96:97], s[48:49], 2, v[4:5]
	v_lshl_add_u64 v[98:99], s[52:53], 2, v[4:5]
	global_load_dword v117, v[2:3], off nt
	global_load_dword v118, v[86:87], off nt
	global_load_dword v119, v[88:89], off nt
	global_load_dword v120, v[90:91], off nt
	global_load_dword v121, v[92:93], off nt
	global_load_dword v122, v[94:95], off nt
	global_load_dword v123, v[96:97], off nt
	global_load_dword v124, v[98:99], off nt
	v_lshl_add_u64 v[2:3], s[50:51], 2, v[4:5]
	v_lshl_add_u64 v[86:87], s[54:55], 2, v[4:5]
	v_lshl_add_u64 v[88:89], s[56:57], 2, v[4:5]
	v_lshl_add_u64 v[90:91], s[58:59], 2, v[4:5]
	v_lshl_add_u64 v[92:93], s[60:61], 2, v[4:5]
	v_lshl_add_u64 v[94:95], s[62:63], 2, v[4:5]
	v_lshl_add_u64 v[96:97], s[64:65], 2, v[4:5]
	v_lshl_add_u64 v[4:5], s[66:67], 2, v[4:5]
	global_load_dword v98, v[2:3], off nt
	global_load_dword v99, v[86:87], off nt
	global_load_dword v125, v[88:89], off nt
	global_load_dword v126, v[90:91], off nt
	global_load_dword v127, v[92:93], off nt
	global_load_dword v128, v[94:95], off nt
	global_load_dword v129, v[96:97], off nt
	global_load_dword v130, v[4:5], off nt
	ds_bpermute_b32 v2, v78, v11
	ds_bpermute_b32 v4, v76, v11
	ds_bpermute_b32 v3, v77, v11
	ds_bpermute_b32 v5, v67, v11
	ds_bpermute_b32 v76, v76, v10
	s_waitcnt lgkmcnt(4)
	v_mul_f32_e32 v54, v46, v2
	s_waitcnt lgkmcnt(3)
	v_mul_f32_e32 v49, v48, v4
	ds_bpermute_b32 v2, v22, v11
	ds_bpermute_b32 v4, v20, v11
	s_waitcnt lgkmcnt(4)
	v_mul_f32_e32 v50, v47, v3
	s_waitcnt lgkmcnt(3)
	v_mul_f32_e32 v47, v51, v5
	v_mul_f32_e32 v46, v52, v59
	ds_bpermute_b32 v3, v21, v11
	ds_bpermute_b32 v5, v19, v11
	s_waitcnt lgkmcnt(3)
	v_mul_f32_e32 v59, v56, v2
	s_waitcnt lgkmcnt(2)
	v_mul_f32_e32 v52, v58, v4
	ds_bpermute_b32 v2, v25, v11
	ds_bpermute_b32 v4, v23, v11
	s_waitcnt lgkmcnt(3)
	v_mul_f32_e32 v57, v57, v3
	s_waitcnt lgkmcnt(2)
	v_mul_f32_e32 v51, v60, v5
	ds_bpermute_b32 v3, v24, v11
	ds_bpermute_b32 v5, v30, v11
	ds_bpermute_b32 v56, v29, v11
	s_waitcnt lgkmcnt(4)
	v_mul_f32_e32 v65, v12, v2
	s_waitcnt lgkmcnt(3)
	v_mul_f32_e32 v58, v55, v4
	ds_bpermute_b32 v2, v28, v11
	ds_bpermute_b32 v4, v34, v11
	ds_bpermute_b32 v48, v26, v11
	s_waitcnt lgkmcnt(5)
	v_mul_f32_e32 v60, v53, v3
	s_waitcnt lgkmcnt(4)
	v_mul_f32_e32 v55, v66, v5
	s_waitcnt lgkmcnt(3)
	v_mul_f32_e32 v53, v68, v56
	ds_bpermute_b32 v3, v27, v11
	ds_bpermute_b32 v5, v33, v11
	s_waitcnt lgkmcnt(4)
	v_mul_f32_e32 v68, v63, v2
	s_waitcnt lgkmcnt(3)
	v_mul_f32_e32 v63, v69, v4
	ds_bpermute_b32 v2, v31, v11
	ds_bpermute_b32 v4, v37, v11
	s_waitcnt lgkmcnt(4)
	v_mul_f32_e32 v48, v61, v48
	ds_bpermute_b32 v12, v32, v11
	s_waitcnt lgkmcnt(4)
	v_mul_f32_e32 v66, v64, v3
	s_waitcnt lgkmcnt(3)
	v_mul_f32_e32 v61, v70, v5
	ds_bpermute_b32 v3, v38, v11
	ds_bpermute_b32 v5, v36, v11
	s_waitcnt lgkmcnt(4)
	v_mul_f32_e32 v72, v62, v2
	s_waitcnt lgkmcnt(3)
	v_mul_f32_e32 v69, v83, v4
	ds_bpermute_b32 v2, v42, v11
	ds_bpermute_b32 v4, v39, v11
	s_waitcnt lgkmcnt(4)
	v_mul_f32_e32 v56, v71, v12
	ds_bpermute_b32 v12, v35, v11
	s_waitcnt lgkmcnt(4)
	v_mul_f32_e32 v70, v75, v3
	s_waitcnt lgkmcnt(3)
	v_mul_f32_e32 v64, v84, v5
	ds_bpermute_b32 v3, v41, v11
	ds_bpermute_b32 v5, v40, v11
	ds_bpermute_b32 v11, v15, v10
	s_waitcnt lgkmcnt(5)
	v_mul_f32_e32 v75, v73, v2
	s_waitcnt lgkmcnt(4)
	v_mul_f32_e32 v73, v81, v4
	ds_bpermute_b32 v4, v79, v10
	ds_bpermute_b32 v15, v77, v10
	s_waitcnt vmcnt(31) lgkmcnt(2)
	v_mul_f32_e32 v2, v100, v11
	v_mul_f32_e32 v74, v74, v3
	ds_bpermute_b32 v3, v80, v10
	s_waitcnt vmcnt(29) lgkmcnt(2)
	v_mul_f32_e32 v11, v102, v4
	s_waitcnt vmcnt(27) lgkmcnt(1)
	v_mul_f32_e32 v4, v104, v15
	v_max3_f32 v15, |v45|, 0, |v44|
	v_max3_f32 v15, v15, |v43|, |v54|
	v_max3_f32 v15, v15, |v50|, |v49|
	v_max3_f32 v15, v15, |v47|, |v46|
	v_max3_f32 v15, v15, |v59|, |v57|
	v_max3_f32 v15, v15, |v52|, |v51|
	v_max3_f32 v15, v15, |v48|, |v65|
	v_max3_f32 v15, v15, |v60|, |v58|
	v_max3_f32 v15, v15, |v55|, |v53|
	v_max3_f32 v15, v15, |v68|, |v66|
	v_max3_f32 v15, v15, |v63|, |v61|
	v_mul_f32_e32 v71, v82, v5
	ds_bpermute_b32 v5, v78, v10
	v_max3_f32 v15, v15, |v56|, |v72|
	v_mul_f32_e32 v62, v85, v12
	v_max3_f32 v15, v15, |v70|, |v69|
	v_max3_f32 v15, v15, |v64|, |v62|
	ds_bpermute_b32 v67, v67, v10
	v_max3_f32 v15, v15, |v75|, |v74|
	ds_bpermute_b32 v22, v22, v10
	ds_bpermute_b32 v21, v21, v10
	s_waitcnt lgkmcnt(4)
	v_mul_f32_e32 v12, v101, v3
	v_max3_f32 v15, v15, |v73|, |v71|
	ds_bpermute_b32 v20, v20, v10
	ds_bpermute_b32 v19, v19, v10
	s_waitcnt lgkmcnt(5)
	v_mul_f32_e32 v5, v103, v5
	v_max3_f32 v15, v15, |v2|, |v12|
	ds_bpermute_b32 v26, v26, v10
	ds_bpermute_b32 v25, v25, v10
	s_waitcnt vmcnt(26)
	v_mul_f32_e32 v3, v105, v76
	v_max3_f32 v15, v15, |v11|, |v5|
	ds_bpermute_b32 v24, v24, v10
	ds_bpermute_b32 v23, v23, v10
	v_max3_f32 v76, v15, |v4|, |v3|
	s_waitcnt vmcnt(25) lgkmcnt(8)
	v_mul_f32_e32 v15, v106, v67
	s_waitcnt vmcnt(24)
	v_mul_f32_e32 v13, v107, v13
	ds_bpermute_b32 v30, v30, v10
	ds_bpermute_b32 v29, v29, v10
	v_max3_f32 v67, v76, |v15|, |v13|
	s_waitcnt vmcnt(23) lgkmcnt(9)
	v_mul_f32_e32 v22, v109, v22
	s_waitcnt vmcnt(22) lgkmcnt(8)
	v_mul_f32_e32 v21, v110, v21
	ds_bpermute_b32 v28, v28, v10
	ds_bpermute_b32 v27, v27, v10
	v_max3_f32 v67, v67, |v22|, |v21|
	s_waitcnt vmcnt(21) lgkmcnt(9)
	v_mul_f32_e32 v20, v111, v20
	s_waitcnt vmcnt(20) lgkmcnt(8)
	v_mul_f32_e32 v19, v112, v19
	ds_bpermute_b32 v34, v34, v10
	ds_bpermute_b32 v33, v33, v10
	v_max3_f32 v67, v67, |v20|, |v19|
	s_waitcnt vmcnt(19) lgkmcnt(9)
	v_mul_f32_e32 v26, v113, v26
	s_waitcnt vmcnt(18) lgkmcnt(8)
	v_mul_f32_e32 v25, v114, v25
	ds_bpermute_b32 v32, v32, v10
	ds_bpermute_b32 v31, v31, v10
	v_max3_f32 v67, v67, |v26|, |v25|
	s_waitcnt vmcnt(17) lgkmcnt(9)
	v_mul_f32_e32 v24, v115, v24
	s_waitcnt vmcnt(16) lgkmcnt(8)
	v_mul_f32_e32 v23, v116, v23
	ds_bpermute_b32 v38, v38, v10
	ds_bpermute_b32 v37, v37, v10
	v_max3_f32 v67, v67, |v24|, |v23|
	s_waitcnt vmcnt(15) lgkmcnt(9)
	v_mul_f32_e32 v30, v117, v30
	s_waitcnt vmcnt(14) lgkmcnt(8)
	v_mul_f32_e32 v29, v118, v29
	ds_bpermute_b32 v36, v36, v10
	ds_bpermute_b32 v35, v35, v10
	v_max3_f32 v67, v67, |v30|, |v29|
	s_waitcnt vmcnt(13) lgkmcnt(9)
	v_mul_f32_e32 v28, v119, v28
	s_waitcnt vmcnt(12) lgkmcnt(8)
	v_mul_f32_e32 v27, v120, v27
	ds_bpermute_b32 v42, v42, v10
	ds_bpermute_b32 v76, v41, v10
	v_max3_f32 v67, v67, |v28|, |v27|
	s_waitcnt vmcnt(11) lgkmcnt(9)
	v_mul_f32_e32 v34, v121, v34
	s_waitcnt vmcnt(10) lgkmcnt(8)
	v_mul_f32_e32 v33, v122, v33
	ds_bpermute_b32 v39, v39, v10
	ds_bpermute_b32 v10, v40, v10
	v_max3_f32 v67, v67, |v34|, |v33|
	s_waitcnt vmcnt(9) lgkmcnt(9)
	v_mul_f32_e32 v32, v123, v32
	s_waitcnt vmcnt(8) lgkmcnt(8)
	v_mul_f32_e32 v31, v124, v31
	v_max3_f32 v67, v67, |v32|, |v31|
	s_waitcnt vmcnt(7) lgkmcnt(7)
	v_mul_f32_e32 v38, v98, v38
	s_waitcnt vmcnt(6) lgkmcnt(6)
	v_mul_f32_e32 v37, v99, v37
	v_max3_f32 v67, v67, |v38|, |v37|
	s_waitcnt vmcnt(5) lgkmcnt(5)
	v_mul_f32_e32 v36, v125, v36
	s_waitcnt vmcnt(4) lgkmcnt(4)
	v_mul_f32_e32 v35, v126, v35
	v_max3_f32 v67, v67, |v36|, |v35|
	s_waitcnt vmcnt(3) lgkmcnt(3)
	v_mul_f32_e32 v41, v127, v42
	s_waitcnt vmcnt(2) lgkmcnt(2)
	v_mul_f32_e32 v40, v128, v76
	v_max3_f32 v42, v67, |v41|, |v40|
	s_waitcnt vmcnt(1) lgkmcnt(1)
	v_mul_f32_e32 v39, v129, v39
	s_waitcnt vmcnt(0) lgkmcnt(0)
	v_mul_f32_e32 v10, v130, v10
	v_max3_f32 v42, v42, |v39|, |v10|
	v_mov_b32_e32 v67, v42
	s_nop 1
	v_permlane32_swap_b32_e32 v42, v67
	s_mov_b64 s[0:1], exec
	v_readlane_b32 s2, v249, 60
	v_readlane_b32 s3, v249, 61
	s_and_b64 s[2:3], s[0:1], s[2:3]
	s_mov_b64 exec, s[2:3]
	s_cbranch_execz .LBB0_61
	v_max_f32_e32 v42, v42, v42
	v_max_f32_e32 v67, v67, v67
	s_add_i32 s2, s20, 0
	v_max_f32_e32 v42, v42, v67
	v_lshl_add_u32 v67, v108, 2, s2
	v_add_u32_e32 v67, 0x20000, v67
	ds_write_b32 v67, v42

.LBB0_360:
	s_ashr_i32 s11, s27, 6
	s_lshl_b32 s1, s11, 14
	s_add_i32 s10, s1, 0
	s_lshl_b32 s1, s29, 1
	s_add_i32 s12, s0, s1
	s_add_i32 s12, s12, -2
	s_cmp_gt_u32 s12, 63
	v_and_b32_e32 v6, 63, v144
	s_cbranch_scc0 .LBB0_383
	s_and_b32 s13, s12, 63
	s_cmp_gt_u32 s13, 31
	s_cbranch_scc0 .LBB0_384
	s_mov_b64 s[0:1], 0
	s_cmp_lt_u32 s13, 48
	s_mov_b64 s[2:3], 0
	s_cbranch_scc0 .LBB0_372
	s_load_dwordx4 s[4:7], s[18:19], 0x50
	s_lshl_b32 s2, s11, 7
	v_or_b32_e32 v4, s2, v6
	v_mov_b32_e32 v10, 1.0
	v_ashrrev_i32_e32 v5, 31, v4
	s_waitcnt lgkmcnt(0)
	s_cmp_lg_u64 s[4:5], 0
	s_cselect_b64 s[8:9], -1, 0
	s_cmp_eq_u64 s[4:5], 0
	v_mov_b32_e32 v11, 1.0
	s_cbranch_scc1 .LBB0_365
	v_lshl_add_u64 v[2:3], v[4:5], 2, s[4:5]
	global_load_dword v11, v[2:3], off nt
.LBB0_365:
	v_and_b32_e32 v9, 31, v144
	s_lshl_b32 s3, s13, 7
	v_lshrrev_b32_e32 v7, 5, v6
	s_add_u32 s6, s6, s3
	v_lshlrev_b32_e32 v8, 2, v9
	s_addc_u32 s7, s7, 0
	v_lshl_or_b32 v2, v7, 11, v8
	v_mov_b32_e32 v3, 0
	s_ashr_i32 s3, s2, 31
	v_lshl_add_u64 v[2:3], s[6:7], 0, v[2:3]
	s_lshl_b64 s[6:7], s[2:3], 11
	v_lshl_add_u64 v[20:21], v[2:3], 0, s[6:7]
	s_or_b32 s6, s2, 2
	s_ashr_i32 s7, s6, 31
	s_lshl_b64 s[6:7], s[6:7], 11
	v_lshl_add_u64 v[22:23], v[2:3], 0, s[6:7]
	s_or_b32 s6, s2, 4
	s_ashr_i32 s7, s6, 31
	s_lshl_b64 s[6:7], s[6:7], 11
	v_lshl_add_u64 v[24:25], v[2:3], 0, s[6:7]
	s_or_b32 s6, s2, 6
	s_ashr_i32 s7, s6, 31
	s_lshl_b64 s[6:7], s[6:7], 11
	v_lshl_add_u64 v[26:27], v[2:3], 0, s[6:7]
	s_or_b32 s6, s2, 8
	s_ashr_i32 s7, s6, 31
	s_lshl_b64 s[6:7], s[6:7], 11
	v_lshl_add_u64 v[28:29], v[2:3], 0, s[6:7]
	s_or_b32 s6, s2, 10
	s_ashr_i32 s7, s6, 31
	s_lshl_b64 s[6:7], s[6:7], 11
	v_lshl_add_u64 v[30:31], v[2:3], 0, s[6:7]
	s_or_b32 s6, s2, 12
	s_ashr_i32 s7, s6, 31
	s_lshl_b64 s[6:7], s[6:7], 11
	v_lshl_add_u64 v[32:33], v[2:3], 0, s[6:7]
	s_or_b32 s6, s2, 14
	s_ashr_i32 s7, s6, 31
	s_lshl_b64 s[6:7], s[6:7], 11
	v_lshl_add_u64 v[34:35], v[2:3], 0, s[6:7]
	s_or_b32 s6, s2, 16
	s_ashr_i32 s7, s6, 31
	s_lshl_b64 s[6:7], s[6:7], 11
	global_load_dword v18, v[20:21], off offset:-4096 nt
	global_load_dword v19, v[22:23], off offset:-4096 nt
	global_load_dword v16, v[24:25], off offset:-4096 nt
	global_load_dword v17, v[26:27], off offset:-4096 nt
	global_load_dword v14, v[28:29], off offset:-4096 nt
	global_load_dword v15, v[30:31], off offset:-4096 nt
	global_load_dword v12, v[32:33], off offset:-4096 nt
	global_load_dword v13, v[34:35], off offset:-4096 nt
	v_lshl_add_u64 v[28:29], v[2:3], 0, s[6:7]
	s_or_b32 s6, s2, 18
	s_ashr_i32 s7, s6, 31
	s_lshl_b64 s[6:7], s[6:7], 11
	v_lshl_add_u64 v[30:31], v[2:3], 0, s[6:7]
	s_or_b32 s6, s2, 20
	s_ashr_i32 s7, s6, 31
	s_lshl_b64 s[6:7], s[6:7], 11
	v_lshl_add_u64 v[32:33], v[2:3], 0, s[6:7]
	s_or_b32 s6, s2, 22
	s_ashr_i32 s7, s6, 31
	s_lshl_b64 s[6:7], s[6:7], 11
	v_lshl_add_u64 v[34:35], v[2:3], 0, s[6:7]
	s_or_b32 s6, s2, 24
	s_ashr_i32 s7, s6, 31
	s_lshl_b64 s[6:7], s[6:7], 11
	v_lshl_add_u64 v[36:37], v[2:3], 0, s[6:7]
	s_or_b32 s6, s2, 26
	s_ashr_i32 s7, s6, 31
	s_lshl_b64 s[6:7], s[6:7], 11
	v_lshl_add_u64 v[38:39], v[2:3], 0, s[6:7]
	s_or_b32 s6, s2, 28
	s_ashr_i32 s7, s6, 31
	s_lshl_b64 s[6:7], s[6:7], 11
	v_lshl_add_u64 v[40:41], v[2:3], 0, s[6:7]
	s_or_b32 s6, s2, 30
	s_ashr_i32 s7, s6, 31
	s_lshl_b64 s[6:7], s[6:7], 11
	v_lshl_add_u64 v[42:43], v[2:3], 0, s[6:7]
	s_or_b32 s6, s2, 32
	s_ashr_i32 s7, s6, 31
	s_lshl_b64 s[6:7], s[6:7], 11
	global_load_dword v26, v[28:29], off offset:-4096 nt
	global_load_dword v27, v[30:31], off offset:-4096 nt
	global_load_dword v24, v[32:33], off offset:-4096 nt
	global_load_dword v25, v[34:35], off offset:-4096 nt
	global_load_dword v22, v[36:37], off offset:-4096 nt
	global_load_dword v23, v[38:39], off offset:-4096 nt
	global_load_dword v20, v[40:41], off offset:-4096 nt
	global_load_dword v21, v[42:43], off offset:-4096 nt
	v_lshl_add_u64 v[36:37], v[2:3], 0, s[6:7]
	s_or_b32 s6, s2, 34
	s_ashr_i32 s7, s6, 31
	s_lshl_b64 s[6:7], s[6:7], 11
	v_lshl_add_u64 v[38:39], v[2:3], 0, s[6:7]
	s_or_b32 s6, s2, 36
	s_ashr_i32 s7, s6, 31
	s_lshl_b64 s[6:7], s[6:7], 11
	v_lshl_add_u64 v[40:41], v[2:3], 0, s[6:7]
	s_or_b32 s6, s2, 38
	s_ashr_i32 s7, s6, 31
	s_lshl_b64 s[6:7], s[6:7], 11
	v_lshl_add_u64 v[42:43], v[2:3], 0, s[6:7]
	s_or_b32 s6, s2, 40
	s_ashr_i32 s7, s6, 31
	s_lshl_b64 s[6:7], s[6:7], 11
	v_lshl_add_u64 v[44:45], v[2:3], 0, s[6:7]
	s_or_b32 s6, s2, 42
	s_ashr_i32 s7, s6, 31
	s_lshl_b64 s[6:7], s[6:7], 11
	v_lshl_add_u64 v[46:47], v[2:3], 0, s[6:7]
	s_or_b32 s6, s2, 44
	s_ashr_i32 s7, s6, 31
	s_lshl_b64 s[6:7], s[6:7], 11
	v_lshl_add_u64 v[48:49], v[2:3], 0, s[6:7]
	s_or_b32 s6, s2, 46
	s_ashr_i32 s7, s6, 31
	s_lshl_b64 s[6:7], s[6:7], 11
	v_lshl_add_u64 v[50:51], v[2:3], 0, s[6:7]
	s_or_b32 s6, s2, 48
	s_ashr_i32 s7, s6, 31
	s_lshl_b64 s[6:7], s[6:7], 11
	global_load_dword v34, v[36:37], off offset:-4096 nt
	global_load_dword v35, v[38:39], off offset:-4096 nt
	global_load_dword v32, v[40:41], off offset:-4096 nt
	global_load_dword v33, v[42:43], off offset:-4096 nt
	global_load_dword v30, v[44:45], off offset:-4096 nt
	global_load_dword v31, v[46:47], off offset:-4096 nt
	global_load_dword v28, v[48:49], off offset:-4096 nt
	global_load_dword v29, v[50:51], off offset:-4096 nt
	v_lshl_add_u64 v[44:45], v[2:3], 0, s[6:7]
	s_or_b32 s6, s2, 50
	s_ashr_i32 s7, s6, 31
	s_lshl_b64 s[6:7], s[6:7], 11
	v_lshl_add_u64 v[46:47], v[2:3], 0, s[6:7]
	s_or_b32 s6, s2, 52
	s_ashr_i32 s7, s6, 31
	s_lshl_b64 s[6:7], s[6:7], 11
	v_lshl_add_u64 v[48:49], v[2:3], 0, s[6:7]
	s_or_b32 s6, s2, 54
	s_ashr_i32 s7, s6, 31
	s_lshl_b64 s[6:7], s[6:7], 11
	v_lshl_add_u64 v[50:51], v[2:3], 0, s[6:7]
	s_or_b32 s6, s2, 56
	s_ashr_i32 s7, s6, 31
	s_lshl_b64 s[6:7], s[6:7], 11
	v_lshl_add_u64 v[52:53], v[2:3], 0, s[6:7]
	s_or_b32 s6, s2, 58
	s_ashr_i32 s7, s6, 31
	s_lshl_b64 s[6:7], s[6:7], 11
	v_lshl_add_u64 v[54:55], v[2:3], 0, s[6:7]
	s_or_b32 s6, s2, 60
	s_ashr_i32 s7, s6, 31
	s_lshl_b64 s[6:7], s[6:7], 11
	v_lshl_add_u64 v[56:57], v[2:3], 0, s[6:7]
	s_or_b32 s6, s2, 62
	s_ashr_i32 s7, s6, 31
	s_lshl_b64 s[6:7], s[6:7], 11
	v_lshl_add_u64 v[58:59], v[2:3], 0, s[6:7]
	global_load_dword v42, v[44:45], off offset:-4096 nt
	global_load_dword v43, v[46:47], off offset:-4096 nt
	global_load_dword v40, v[48:49], off offset:-4096 nt
	global_load_dword v41, v[50:51], off offset:-4096 nt
	global_load_dword v38, v[52:53], off offset:-4096 nt
	global_load_dword v39, v[54:55], off offset:-4096 nt
	global_load_dword v36, v[56:57], off offset:-4096 nt
	global_load_dword v37, v[58:59], off offset:-4096 nt
	s_andn2_b64 vcc, exec, s[8:9]
	s_cbranch_vccnz .LBB0_367
	v_lshl_add_u64 v[4:5], v[4:5], 2, s[4:5]
	global_load_dword v10, v[4:5], off offset:256 nt
.LBB0_367:
	s_or_b32 s4, s2, 64
	s_ashr_i32 s5, s4, 31
	s_lshl_b64 s[4:5], s[4:5], 11
	v_lshl_add_u64 v[4:5], v[2:3], 0, s[4:5]
	s_or_b32 s4, s2, 0x42
	s_ashr_i32 s5, s4, 31
	s_lshl_b64 s[4:5], s[4:5], 11
	v_lshl_add_u64 v[44:45], v[2:3], 0, s[4:5]
	s_or_b32 s4, s2, 0x44
	s_ashr_i32 s5, s4, 31
	s_lshl_b64 s[4:5], s[4:5], 11
	v_lshl_add_u64 v[46:47], v[2:3], 0, s[4:5]
	s_or_b32 s4, s2, 0x46
	s_ashr_i32 s5, s4, 31
	s_lshl_b64 s[4:5], s[4:5], 11
	v_lshl_add_u64 v[48:49], v[2:3], 0, s[4:5]
	s_or_b32 s4, s2, 0x48
	s_ashr_i32 s5, s4, 31
	s_lshl_b64 s[4:5], s[4:5], 11
	v_lshl_add_u64 v[50:51], v[2:3], 0, s[4:5]
	s_or_b32 s4, s2, 0x4a
	s_ashr_i32 s5, s4, 31
	s_lshl_b64 s[4:5], s[4:5], 11
	v_lshl_add_u64 v[52:53], v[2:3], 0, s[4:5]
	s_or_b32 s4, s2, 0x4c
	s_ashr_i32 s5, s4, 31
	s_lshl_b64 s[4:5], s[4:5], 11
	v_lshl_add_u64 v[54:55], v[2:3], 0, s[4:5]
	s_or_b32 s4, s2, 0x4e
	s_ashr_i32 s5, s4, 31
	s_lshl_b64 s[4:5], s[4:5], 11
	v_lshl_add_u64 v[56:57], v[2:3], 0, s[4:5]
	s_or_b32 s4, s2, 0x50
	s_ashr_i32 s5, s4, 31
	s_lshl_b64 s[4:5], s[4:5], 11
	global_load_dword v71, v[4:5], off offset:-4096 nt
	global_load_dword v72, v[44:45], off offset:-4096 nt
	global_load_dword v73, v[46:47], off offset:-4096 nt
	global_load_dword v74, v[48:49], off offset:-4096 nt
	global_load_dword v75, v[50:51], off offset:-4096 nt
	global_load_dword v76, v[52:53], off offset:-4096 nt
	global_load_dword v77, v[54:55], off offset:-4096 nt
	global_load_dword v78, v[56:57], off offset:-4096 nt
	v_lshl_add_u64 v[4:5], v[2:3], 0, s[4:5]
	s_or_b32 s4, s2, 0x52
	s_ashr_i32 s5, s4, 31
	s_lshl_b64 s[4:5], s[4:5], 11
	v_lshl_add_u64 v[44:45], v[2:3], 0, s[4:5]
	s_or_b32 s4, s2, 0x54
	s_ashr_i32 s5, s4, 31
	s_lshl_b64 s[4:5], s[4:5], 11
	v_lshl_add_u64 v[46:47], v[2:3], 0, s[4:5]
	s_or_b32 s4, s2, 0x56
	s_ashr_i32 s5, s4, 31
	s_lshl_b64 s[4:5], s[4:5], 11
	v_lshl_add_u64 v[48:49], v[2:3], 0, s[4:5]
	s_or_b32 s4, s2, 0x58
	s_ashr_i32 s5, s4, 31
	s_lshl_b64 s[4:5], s[4:5], 11
	v_lshl_add_u64 v[50:51], v[2:3], 0, s[4:5]
	s_or_b32 s4, s2, 0x5a
	s_ashr_i32 s5, s4, 31
	s_lshl_b64 s[4:5], s[4:5], 11
	v_lshl_add_u64 v[52:53], v[2:3], 0, s[4:5]
	s_or_b32 s4, s2, 0x5c
	s_ashr_i32 s5, s4, 31
	s_lshl_b64 s[4:5], s[4:5], 11
	v_lshl_add_u64 v[54:55], v[2:3], 0, s[4:5]
	s_or_b32 s4, s2, 0x5e
	s_ashr_i32 s5, s4, 31
	s_lshl_b64 s[4:5], s[4:5], 11
	v_lshl_add_u64 v[56:57], v[2:3], 0, s[4:5]
	s_or_b32 s4, s2, 0x60
	s_ashr_i32 s5, s4, 31
	s_lshl_b64 s[4:5], s[4:5], 11
	global_load_dword v79, v[4:5], off offset:-4096 nt
	global_load_dword v80, v[44:45], off offset:-4096 nt
	global_load_dword v81, v[46:47], off offset:-4096 nt
	global_load_dword v82, v[48:49], off offset:-4096 nt
	global_load_dword v83, v[50:51], off offset:-4096 nt
	global_load_dword v84, v[52:53], off offset:-4096 nt
	global_load_dword v85, v[54:55], off offset:-4096 nt
	global_load_dword v86, v[56:57], off offset:-4096 nt
	v_lshl_add_u64 v[4:5], v[2:3], 0, s[4:5]
	s_or_b32 s4, s2, 0x62
	s_ashr_i32 s5, s4, 31
	s_lshl_b64 s[4:5], s[4:5], 11
	v_lshl_add_u64 v[44:45], v[2:3], 0, s[4:5]
	s_or_b32 s4, s2, 0x64
	s_ashr_i32 s5, s4, 31
	s_lshl_b64 s[4:5], s[4:5], 11
	v_lshl_add_u64 v[46:47], v[2:3], 0, s[4:5]
	s_or_b32 s4, s2, 0x66
	s_ashr_i32 s5, s4, 31
	s_lshl_b64 s[4:5], s[4:5], 11
	v_lshl_add_u64 v[48:49], v[2:3], 0, s[4:5]
	s_or_b32 s4, s2, 0x68
	s_ashr_i32 s5, s4, 31
	s_lshl_b64 s[4:5], s[4:5], 11
	v_lshl_add_u64 v[50:51], v[2:3], 0, s[4:5]
	s_or_b32 s4, s2, 0x6a
	s_ashr_i32 s5, s4, 31
	s_lshl_b64 s[4:5], s[4:5], 11
	v_lshl_add_u64 v[52:53], v[2:3], 0, s[4:5]
	s_or_b32 s4, s2, 0x6c
	s_ashr_i32 s5, s4, 31
	s_lshl_b64 s[4:5], s[4:5], 11
	v_lshl_add_u64 v[54:55], v[2:3], 0, s[4:5]
	s_or_b32 s4, s2, 0x6e
	s_ashr_i32 s5, s4, 31
	s_lshl_b64 s[4:5], s[4:5], 11
	v_lshl_add_u64 v[56:57], v[2:3], 0, s[4:5]
	s_or_b32 s4, s2, 0x70
	s_ashr_i32 s5, s4, 31
	s_lshl_b64 s[4:5], s[4:5], 11
	global_load_dword v87, v[4:5], off offset:-4096 nt
	global_load_dword v88, v[44:45], off offset:-4096 nt
	global_load_dword v89, v[46:47], off offset:-4096 nt
	global_load_dword v90, v[48:49], off offset:-4096 nt
	global_load_dword v91, v[50:51], off offset:-4096 nt
	global_load_dword v92, v[52:53], off offset:-4096 nt
	global_load_dword v93, v[54:55], off offset:-4096 nt
	global_load_dword v94, v[56:57], off offset:-4096 nt
	v_lshl_add_u64 v[4:5], v[2:3], 0, s[4:5]
	s_or_b32 s4, s2, 0x72
	s_ashr_i32 s5, s4, 31
	s_lshl_b64 s[4:5], s[4:5], 11
	v_lshl_add_u64 v[44:45], v[2:3], 0, s[4:5]
	s_or_b32 s4, s2, 0x74
	s_ashr_i32 s5, s4, 31
	s_lshl_b64 s[4:5], s[4:5], 11
	v_lshl_add_u64 v[46:47], v[2:3], 0, s[4:5]
	s_or_b32 s4, s2, 0x76
	s_ashr_i32 s5, s4, 31
	s_lshl_b64 s[4:5], s[4:5], 11
	v_lshl_add_u64 v[48:49], v[2:3], 0, s[4:5]
	s_or_b32 s4, s2, 0x78
	s_ashr_i32 s5, s4, 31
	s_lshl_b64 s[4:5], s[4:5], 11
	v_lshl_add_u64 v[50:51], v[2:3], 0, s[4:5]
	s_or_b32 s4, s2, 0x7a
	s_ashr_i32 s5, s4, 31
	s_lshl_b64 s[4:5], s[4:5], 11
	v_lshl_add_u64 v[52:53], v[2:3], 0, s[4:5]
	s_or_b32 s4, s2, 0x7c
	s_ashr_i32 s5, s4, 31
	s_lshl_b64 s[4:5], s[4:5], 11
	v_lshl_add_u64 v[54:55], v[2:3], 0, s[4:5]
	s_or_b32 s4, s2, 0x7e
	s_ashr_i32 s5, s4, 31
	s_lshl_b64 s[4:5], s[4:5], 11
	v_lshlrev_b32_e32 v95, 2, v7
	v_lshl_add_u64 v[2:3], v[2:3], 0, s[4:5]
	s_waitcnt vmcnt(0)
	ds_bpermute_b32 v56, v95, v11
	ds_bpermute_b32 v57, v95, v11 offset:8
	global_load_dword v96, v[4:5], off offset:-4096 nt
	global_load_dword v97, v[44:45], off offset:-4096 nt
	global_load_dword v98, v[46:47], off offset:-4096 nt
	global_load_dword v99, v[48:49], off offset:-4096 nt
	global_load_dword v100, v[50:51], off offset:-4096 nt
	global_load_dword v101, v[52:53], off offset:-4096 nt
	global_load_dword v102, v[54:55], off offset:-4096 nt
	global_load_dword v103, v[2:3], off offset:-4096 nt
	ds_bpermute_b32 v2, v95, v11 offset:16
	ds_bpermute_b32 v3, v95, v11 offset:24
	s_waitcnt lgkmcnt(3)
	v_mul_f32_e32 v45, v18, v56
	s_waitcnt lgkmcnt(2)
	v_mul_f32_e32 v5, v19, v57
	v_max3_f32 v18, |v45|, 0, |v5|
	s_waitcnt lgkmcnt(1)
	v_mul_f32_e32 v4, v16, v2
	s_waitcnt lgkmcnt(0)
	v_mul_f32_e32 v3, v17, v3
	ds_bpermute_b32 v2, v95, v11 offset:32
	v_max3_f32 v17, v18, |v4|, |v3|
	ds_bpermute_b32 v18, v95, v11 offset:48
	ds_bpermute_b32 v19, v95, v11 offset:56
	ds_bpermute_b32 v16, v95, v11 offset:40
	s_waitcnt lgkmcnt(3)
	v_mul_f32_e32 v48, v14, v2
	ds_bpermute_b32 v14, v95, v11 offset:80
	s_waitcnt lgkmcnt(3)
	v_mul_f32_e32 v46, v12, v18
	s_waitcnt lgkmcnt(2)
	v_mul_f32_e32 v44, v13, v19
	ds_bpermute_b32 v12, v95, v11 offset:64
	ds_bpermute_b32 v13, v95, v11 offset:72
	s_waitcnt lgkmcnt(3)
	v_mul_f32_e32 v47, v15, v16
	ds_bpermute_b32 v15, v95, v11 offset:88
	s_waitcnt lgkmcnt(3)
	v_mul_f32_e32 v50, v24, v14
	s_waitcnt lgkmcnt(2)
	v_mul_f32_e32 v52, v26, v12
	s_waitcnt lgkmcnt(1)
	v_mul_f32_e32 v51, v27, v13
	ds_bpermute_b32 v12, v95, v11 offset:96
	ds_bpermute_b32 v13, v95, v11 offset:104
	ds_bpermute_b32 v14, v95, v11 offset:112
	s_waitcnt lgkmcnt(3)
	v_mul_f32_e32 v49, v25, v15
	ds_bpermute_b32 v15, v95, v11 offset:120
	s_waitcnt lgkmcnt(3)
	v_mul_f32_e32 v56, v22, v12
	s_waitcnt lgkmcnt(2)
	v_mul_f32_e32 v55, v23, v13
	s_waitcnt lgkmcnt(1)
	v_mul_f32_e32 v54, v20, v14
	ds_bpermute_b32 v12, v95, v11 offset:128
	ds_bpermute_b32 v13, v95, v11 offset:136
	ds_bpermute_b32 v14, v95, v11 offset:144
	s_waitcnt lgkmcnt(3)
	v_mul_f32_e32 v53, v21, v15
	ds_bpermute_b32 v15, v95, v11 offset:152
	s_waitcnt lgkmcnt(3)
	v_mul_f32_e32 v60, v34, v12
	s_waitcnt lgkmcnt(2)
	v_mul_f32_e32 v59, v35, v13
	s_waitcnt lgkmcnt(1)
	v_mul_f32_e32 v58, v32, v14
	ds_bpermute_b32 v12, v95, v11 offset:160
	ds_bpermute_b32 v13, v95, v11 offset:168
	ds_bpermute_b32 v14, v95, v11 offset:176
	s_waitcnt lgkmcnt(3)
	v_mul_f32_e32 v57, v33, v15
	ds_bpermute_b32 v15, v95, v11 offset:184
	s_waitcnt lgkmcnt(3)
	v_mul_f32_e32 v64, v30, v12
	s_waitcnt lgkmcnt(2)
	v_mul_f32_e32 v63, v31, v13
	s_waitcnt lgkmcnt(1)
	v_mul_f32_e32 v62, v28, v14
	ds_bpermute_b32 v12, v95, v11 offset:192
	ds_bpermute_b32 v13, v95, v11 offset:200
	ds_bpermute_b32 v14, v95, v11 offset:208
	s_waitcnt lgkmcnt(3)
	v_mul_f32_e32 v61, v29, v15
	ds_bpermute_b32 v15, v95, v11 offset:216
	s_waitcnt lgkmcnt(3)
	v_mul_f32_e32 v66, v42, v12
	s_waitcnt lgkmcnt(2)
	v_mul_f32_e32 v65, v43, v13
	s_waitcnt lgkmcnt(1)
	v_mul_f32_e32 v43, v40, v14
	ds_bpermute_b32 v12, v95, v11 offset:224
	ds_bpermute_b32 v13, v95, v11 offset:232
	ds_bpermute_b32 v14, v95, v11 offset:240
	ds_bpermute_b32 v11, v95, v11 offset:248
	s_waitcnt lgkmcnt(4)
	v_mul_f32_e32 v42, v41, v15
	s_waitcnt lgkmcnt(3)
	v_mul_f32_e32 v70, v38, v12
	ds_bpermute_b32 v12, v95, v10 offset:8
	ds_bpermute_b32 v15, v95, v10 offset:16
	s_waitcnt lgkmcnt(2)
	v_mul_f32_e32 v67, v37, v11
	ds_bpermute_b32 v11, v95, v10
	ds_bpermute_b32 v16, v95, v10 offset:24
	v_mul_f32_e32 v69, v39, v13
	v_mul_f32_e32 v68, v36, v14
	s_waitcnt lgkmcnt(3)
	v_mul_f32_e32 v13, v72, v12
	s_waitcnt lgkmcnt(1)
	v_mul_f32_e32 v14, v71, v11
	v_mul_f32_e32 v12, v73, v15
	s_waitcnt lgkmcnt(0)
	v_mul_f32_e32 v11, v74, v16
	ds_bpermute_b32 v15, v95, v10 offset:32
	ds_bpermute_b32 v16, v95, v10 offset:40
	ds_bpermute_b32 v19, v95, v10 offset:48
	ds_bpermute_b32 v20, v95, v10 offset:56
	v_max3_f32 v2, v17, |v48|, |v47|
	s_waitcnt lgkmcnt(3)
	v_mul_f32_e32 v18, v75, v15
	s_waitcnt lgkmcnt(2)
	v_mul_f32_e32 v17, v76, v16
	s_waitcnt lgkmcnt(1)
	v_mul_f32_e32 v16, v77, v19
	s_waitcnt lgkmcnt(0)
	v_mul_f32_e32 v15, v78, v20
	ds_bpermute_b32 v19, v95, v10 offset:64
	ds_bpermute_b32 v20, v95, v10 offset:72
	ds_bpermute_b32 v23, v95, v10 offset:80
	ds_bpermute_b32 v24, v95, v10 offset:88
	v_max3_f32 v2, v2, |v46|, |v44|
	v_max3_f32 v2, v2, |v52|, |v51|
	s_waitcnt lgkmcnt(3)
	v_mul_f32_e32 v22, v79, v19
	s_waitcnt lgkmcnt(2)
	v_mul_f32_e32 v21, v80, v20
	s_waitcnt lgkmcnt(1)
	v_mul_f32_e32 v20, v81, v23
	s_waitcnt lgkmcnt(0)
	v_mul_f32_e32 v19, v82, v24
	ds_bpermute_b32 v23, v95, v10 offset:96
	ds_bpermute_b32 v24, v95, v10 offset:104
	ds_bpermute_b32 v27, v95, v10 offset:112
	ds_bpermute_b32 v28, v95, v10 offset:120
	v_max3_f32 v2, v2, |v50|, |v49|
	v_max3_f32 v2, v2, |v56|, |v55|
	v_max3_f32 v2, v2, |v54|, |v53|
	v_max3_f32 v2, v2, |v60|, |v59|
	v_max3_f32 v2, v2, |v58|, |v57|
	s_waitcnt lgkmcnt(3)
	v_mul_f32_e32 v26, v83, v23
	s_waitcnt lgkmcnt(2)
	v_mul_f32_e32 v25, v84, v24
	s_waitcnt lgkmcnt(1)
	v_mul_f32_e32 v24, v85, v27
	s_waitcnt lgkmcnt(0)
	v_mul_f32_e32 v23, v86, v28
	ds_bpermute_b32 v27, v95, v10 offset:128
	ds_bpermute_b32 v28, v95, v10 offset:136
	ds_bpermute_b32 v31, v95, v10 offset:144
	ds_bpermute_b32 v32, v95, v10 offset:152
	v_max3_f32 v2, v2, |v64|, |v63|
	v_max3_f32 v2, v2, |v62|, |v61|
	v_max3_f32 v2, v2, |v66|, |v65|
	v_max3_f32 v2, v2, |v43|, |v42|
	v_max3_f32 v2, v2, |v70|, |v69|
	s_waitcnt lgkmcnt(3)
	v_mul_f32_e32 v30, v87, v27
	s_waitcnt lgkmcnt(2)
	v_mul_f32_e32 v29, v88, v28
	s_waitcnt lgkmcnt(1)
	v_mul_f32_e32 v28, v89, v31
	s_waitcnt lgkmcnt(0)
	v_mul_f32_e32 v27, v90, v32
	ds_bpermute_b32 v31, v95, v10 offset:160
	ds_bpermute_b32 v32, v95, v10 offset:168
	ds_bpermute_b32 v35, v95, v10 offset:176
	ds_bpermute_b32 v36, v95, v10 offset:184
	v_max3_f32 v2, v2, |v68|, |v67|
	v_max3_f32 v2, v2, |v14|, |v13|
	v_max3_f32 v2, v2, |v12|, |v11|
	v_max3_f32 v2, v2, |v18|, |v17|
	v_max3_f32 v2, v2, |v16|, |v15|
	s_waitcnt lgkmcnt(3)
	v_mul_f32_e32 v34, v91, v31
	s_waitcnt lgkmcnt(2)
	v_mul_f32_e32 v33, v92, v32
	s_waitcnt lgkmcnt(1)
	v_mul_f32_e32 v32, v93, v35
	s_waitcnt lgkmcnt(0)
	v_mul_f32_e32 v31, v94, v36
	ds_bpermute_b32 v35, v95, v10 offset:192
	ds_bpermute_b32 v36, v95, v10 offset:200
	ds_bpermute_b32 v39, v95, v10 offset:208
	ds_bpermute_b32 v40, v95, v10 offset:216
	v_max3_f32 v2, v2, |v22|, |v21|
	v_max3_f32 v2, v2, |v20|, |v19|
	v_max3_f32 v2, v2, |v26|, |v25|
	v_max3_f32 v2, v2, |v24|, |v23|
	v_max3_f32 v2, v2, |v30|, |v29|
	s_waitcnt vmcnt(7) lgkmcnt(3)
	v_mul_f32_e32 v38, v96, v35
	s_waitcnt vmcnt(6) lgkmcnt(2)
	v_mul_f32_e32 v37, v97, v36
	s_waitcnt vmcnt(5) lgkmcnt(1)
	v_mul_f32_e32 v36, v98, v39
	s_waitcnt vmcnt(4) lgkmcnt(0)
	v_mul_f32_e32 v35, v99, v40
	ds_bpermute_b32 v39, v95, v10 offset:224
	ds_bpermute_b32 v40, v95, v10 offset:232
	v_max3_f32 v2, v2, |v28|, |v27|
	ds_bpermute_b32 v71, v95, v10 offset:240
	ds_bpermute_b32 v10, v95, v10 offset:248
	v_max3_f32 v2, v2, |v34|, |v33|
	v_max3_f32 v2, v2, |v32|, |v31|
	v_max3_f32 v2, v2, |v38|, |v37|
	v_max3_f32 v2, v2, |v36|, |v35|
	s_waitcnt vmcnt(3) lgkmcnt(3)
	v_mul_f32_e32 v41, v100, v39
	s_waitcnt vmcnt(2) lgkmcnt(2)
	v_mul_f32_e32 v40, v101, v40
	v_max3_f32 v2, v2, |v41|, |v40|
	s_waitcnt vmcnt(1) lgkmcnt(1)
	v_mul_f32_e32 v39, v102, v71
	s_waitcnt vmcnt(0) lgkmcnt(0)
	v_mul_f32_e32 v10, v103, v10
	v_max3_f32 v2, v2, |v39|, |v10|
	v_mov_b32_e32 v71, v2
	s_lshl_b32 s6, s13, 5
	s_nop 0
	v_permlane32_swap_b32_e32 v2, v71
	v_cmp_gt_u32_e32 vcc, 32, v6
	s_and_saveexec_b64 s[4:5], vcc
	s_cbranch_execz .LBB0_369
	v_max_f32_e32 v2, v2, v2
	v_max_f32_e32 v71, v71, v71
	s_add_i32 s7, s2, 0
	v_max_f32_e32 v2, v2, v71
	v_lshl_add_u32 v71, v6, 2, s7
	v_add_u32_e32 v71, 0x20000, v71
	ds_write_b32 v71, v2

.LBB0_373:
	s_load_dwordx4 s[4:7], s[18:19], 0x60
	s_lshl_b32 s0, s11, 7
	v_or_b32_e32 v4, s0, v6
	v_mov_b32_e32 v10, 1.0
	v_ashrrev_i32_e32 v5, 31, v4
	s_waitcnt lgkmcnt(0)
	s_cmp_lg_u64 s[4:5], 0
	s_cselect_b64 s[2:3], -1, 0
	s_cmp_eq_u64 s[4:5], 0
	v_mov_b32_e32 v11, 1.0
	s_cbranch_scc1 .LBB0_375
	v_lshl_add_u64 v[2:3], v[4:5], 2, s[4:5]
	global_load_dword v11, v[2:3], off nt
.LBB0_375:
	v_and_b32_e32 v9, 31, v144
	s_lshl_b32 s1, s13, 7
	v_lshrrev_b32_e32 v7, 5, v6
	s_add_u32 s6, s6, s1
	v_lshlrev_b32_e32 v8, 2, v9
	s_addc_u32 s7, s7, 0
	v_lshl_or_b32 v2, v7, 12, v8
	v_mov_b32_e32 v3, 0
	s_ashr_i32 s1, s0, 31
	v_lshl_add_u64 v[2:3], s[6:7], 0, v[2:3]
	s_lshl_b64 s[6:7], s[0:1], 12
	v_lshl_add_u64 v[20:21], v[2:3], 0, s[6:7]
	s_or_b32 s6, s0, 2
	s_ashr_i32 s7, s6, 31
	s_lshl_b64 s[6:7], s[6:7], 12
	v_lshl_add_u64 v[22:23], v[2:3], 0, s[6:7]
	s_or_b32 s6, s0, 4
	s_ashr_i32 s7, s6, 31
	s_lshl_b64 s[6:7], s[6:7], 12
	v_lshl_add_u64 v[24:25], v[2:3], 0, s[6:7]
	s_or_b32 s6, s0, 6
	s_ashr_i32 s7, s6, 31
	s_lshl_b64 s[6:7], s[6:7], 12
	v_lshl_add_u64 v[26:27], v[2:3], 0, s[6:7]
	s_or_b32 s6, s0, 8
	s_ashr_i32 s7, s6, 31
	s_lshl_b64 s[6:7], s[6:7], 12
	v_lshl_add_u64 v[28:29], v[2:3], 0, s[6:7]
	s_or_b32 s6, s0, 10
	s_ashr_i32 s7, s6, 31
	s_lshl_b64 s[6:7], s[6:7], 12
	v_lshl_add_u64 v[30:31], v[2:3], 0, s[6:7]
	s_or_b32 s6, s0, 12
	s_ashr_i32 s7, s6, 31
	s_lshl_b64 s[6:7], s[6:7], 12
	v_lshl_add_u64 v[32:33], v[2:3], 0, s[6:7]
	s_or_b32 s6, s0, 14
	s_ashr_i32 s7, s6, 31
	s_lshl_b64 s[6:7], s[6:7], 12
	v_lshl_add_u64 v[34:35], v[2:3], 0, s[6:7]
	s_or_b32 s6, s0, 16
	s_ashr_i32 s7, s6, 31
	s_lshl_b64 s[6:7], s[6:7], 12
	global_load_dword v18, v[20:21], off nt
	global_load_dword v19, v[22:23], off nt
	global_load_dword v16, v[24:25], off nt
	global_load_dword v17, v[26:27], off nt
	global_load_dword v14, v[28:29], off nt
	global_load_dword v15, v[30:31], off nt
	global_load_dword v12, v[32:33], off nt
	global_load_dword v13, v[34:35], off nt
	v_lshl_add_u64 v[28:29], v[2:3], 0, s[6:7]
	s_or_b32 s6, s0, 18
	s_ashr_i32 s7, s6, 31
	s_lshl_b64 s[6:7], s[6:7], 12
	v_lshl_add_u64 v[30:31], v[2:3], 0, s[6:7]
	s_or_b32 s6, s0, 20
	s_ashr_i32 s7, s6, 31
	s_lshl_b64 s[6:7], s[6:7], 12
	v_lshl_add_u64 v[32:33], v[2:3], 0, s[6:7]
	s_or_b32 s6, s0, 22
	s_ashr_i32 s7, s6, 31
	s_lshl_b64 s[6:7], s[6:7], 12
	v_lshl_add_u64 v[34:35], v[2:3], 0, s[6:7]
	s_or_b32 s6, s0, 24
	s_ashr_i32 s7, s6, 31
	s_lshl_b64 s[6:7], s[6:7], 12
	v_lshl_add_u64 v[36:37], v[2:3], 0, s[6:7]
	s_or_b32 s6, s0, 26
	s_ashr_i32 s7, s6, 31
	s_lshl_b64 s[6:7], s[6:7], 12
	v_lshl_add_u64 v[38:39], v[2:3], 0, s[6:7]
	s_or_b32 s6, s0, 28
	s_ashr_i32 s7, s6, 31
	s_lshl_b64 s[6:7], s[6:7], 12
	v_lshl_add_u64 v[40:41], v[2:3], 0, s[6:7]
	s_or_b32 s6, s0, 30
	s_ashr_i32 s7, s6, 31
	s_lshl_b64 s[6:7], s[6:7], 12
	v_lshl_add_u64 v[42:43], v[2:3], 0, s[6:7]
	s_or_b32 s6, s0, 32
	s_ashr_i32 s7, s6, 31
	s_lshl_b64 s[6:7], s[6:7], 12
	global_load_dword v26, v[28:29], off nt
	global_load_dword v27, v[30:31], off nt
	global_load_dword v24, v[32:33], off nt
	global_load_dword v25, v[34:35], off nt
	global_load_dword v22, v[36:37], off nt
	global_load_dword v23, v[38:39], off nt
	global_load_dword v20, v[40:41], off nt
	global_load_dword v21, v[42:43], off nt
	v_lshl_add_u64 v[36:37], v[2:3], 0, s[6:7]
	s_or_b32 s6, s0, 34
	s_ashr_i32 s7, s6, 31
	s_lshl_b64 s[6:7], s[6:7], 12
	v_lshl_add_u64 v[38:39], v[2:3], 0, s[6:7]
	s_or_b32 s6, s0, 36
	s_ashr_i32 s7, s6, 31
	s_lshl_b64 s[6:7], s[6:7], 12
	v_lshl_add_u64 v[40:41], v[2:3], 0, s[6:7]
	s_or_b32 s6, s0, 38
	s_ashr_i32 s7, s6, 31
	s_lshl_b64 s[6:7], s[6:7], 12
	v_lshl_add_u64 v[42:43], v[2:3], 0, s[6:7]
	s_or_b32 s6, s0, 40
	s_ashr_i32 s7, s6, 31
	s_lshl_b64 s[6:7], s[6:7], 12
	v_lshl_add_u64 v[44:45], v[2:3], 0, s[6:7]
	s_or_b32 s6, s0, 42
	s_ashr_i32 s7, s6, 31
	s_lshl_b64 s[6:7], s[6:7], 12
	v_lshl_add_u64 v[46:47], v[2:3], 0, s[6:7]
	s_or_b32 s6, s0, 44
	s_ashr_i32 s7, s6, 31
	s_lshl_b64 s[6:7], s[6:7], 12
	v_lshl_add_u64 v[48:49], v[2:3], 0, s[6:7]
	s_or_b32 s6, s0, 46
	s_ashr_i32 s7, s6, 31
	s_lshl_b64 s[6:7], s[6:7], 12
	v_lshl_add_u64 v[50:51], v[2:3], 0, s[6:7]
	s_or_b32 s6, s0, 48
	s_ashr_i32 s7, s6, 31
	s_lshl_b64 s[6:7], s[6:7], 12
	global_load_dword v34, v[36:37], off nt
	global_load_dword v35, v[38:39], off nt
	global_load_dword v32, v[40:41], off nt
	global_load_dword v33, v[42:43], off nt
	global_load_dword v30, v[44:45], off nt
	global_load_dword v31, v[46:47], off nt
	global_load_dword v28, v[48:49], off nt
	global_load_dword v29, v[50:51], off nt
	v_lshl_add_u64 v[44:45], v[2:3], 0, s[6:7]
	s_or_b32 s6, s0, 50
	s_ashr_i32 s7, s6, 31
	s_lshl_b64 s[6:7], s[6:7], 12
	v_lshl_add_u64 v[46:47], v[2:3], 0, s[6:7]
	s_or_b32 s6, s0, 52
	s_ashr_i32 s7, s6, 31
	s_lshl_b64 s[6:7], s[6:7], 12
	v_lshl_add_u64 v[48:49], v[2:3], 0, s[6:7]
	s_or_b32 s6, s0, 54
	s_ashr_i32 s7, s6, 31
	s_lshl_b64 s[6:7], s[6:7], 12
	v_lshl_add_u64 v[50:51], v[2:3], 0, s[6:7]
	s_or_b32 s6, s0, 56
	s_ashr_i32 s7, s6, 31
	s_lshl_b64 s[6:7], s[6:7], 12
	v_lshl_add_u64 v[52:53], v[2:3], 0, s[6:7]
	s_or_b32 s6, s0, 58
	s_ashr_i32 s7, s6, 31
	s_lshl_b64 s[6:7], s[6:7], 12
	v_lshl_add_u64 v[54:55], v[2:3], 0, s[6:7]
	s_or_b32 s6, s0, 60
	s_ashr_i32 s7, s6, 31
	s_lshl_b64 s[6:7], s[6:7], 12
	v_lshl_add_u64 v[56:57], v[2:3], 0, s[6:7]
	s_or_b32 s6, s0, 62
	s_ashr_i32 s7, s6, 31
	s_lshl_b64 s[6:7], s[6:7], 12
	v_lshl_add_u64 v[58:59], v[2:3], 0, s[6:7]
	global_load_dword v42, v[44:45], off nt
	global_load_dword v43, v[46:47], off nt
	global_load_dword v40, v[48:49], off nt
	global_load_dword v41, v[50:51], off nt
	global_load_dword v38, v[52:53], off nt
	global_load_dword v39, v[54:55], off nt
	global_load_dword v36, v[56:57], off nt
	global_load_dword v37, v[58:59], off nt
	s_andn2_b64 vcc, exec, s[2:3]
	s_cbranch_vccnz .LBB0_377
	v_lshl_add_u64 v[4:5], v[4:5], 2, s[4:5]
	global_load_dword v10, v[4:5], off offset:256 nt
.LBB0_377:
	s_or_b32 s2, s0, 64
	s_ashr_i32 s3, s2, 31
	s_lshl_b64 s[2:3], s[2:3], 12
	v_lshl_add_u64 v[4:5], v[2:3], 0, s[2:3]
	s_or_b32 s2, s0, 0x42
	s_ashr_i32 s3, s2, 31
	s_lshl_b64 s[2:3], s[2:3], 12
	v_lshl_add_u64 v[44:45], v[2:3], 0, s[2:3]
	s_or_b32 s2, s0, 0x44
	s_ashr_i32 s3, s2, 31
	s_lshl_b64 s[2:3], s[2:3], 12
	v_lshl_add_u64 v[46:47], v[2:3], 0, s[2:3]
	s_or_b32 s2, s0, 0x46
	s_ashr_i32 s3, s2, 31
	s_lshl_b64 s[2:3], s[2:3], 12
	v_lshl_add_u64 v[48:49], v[2:3], 0, s[2:3]
	s_or_b32 s2, s0, 0x48
	s_ashr_i32 s3, s2, 31
	s_lshl_b64 s[2:3], s[2:3], 12
	v_lshl_add_u64 v[50:51], v[2:3], 0, s[2:3]
	s_or_b32 s2, s0, 0x4a
	s_ashr_i32 s3, s2, 31
	s_lshl_b64 s[2:3], s[2:3], 12
	v_lshl_add_u64 v[52:53], v[2:3], 0, s[2:3]
	s_or_b32 s2, s0, 0x4c
	s_ashr_i32 s3, s2, 31
	s_lshl_b64 s[2:3], s[2:3], 12
	v_lshl_add_u64 v[54:55], v[2:3], 0, s[2:3]
	s_or_b32 s2, s0, 0x4e
	s_ashr_i32 s3, s2, 31
	s_lshl_b64 s[2:3], s[2:3], 12
	v_lshl_add_u64 v[56:57], v[2:3], 0, s[2:3]
	s_or_b32 s2, s0, 0x50
	s_ashr_i32 s3, s2, 31
	s_lshl_b64 s[2:3], s[2:3], 12
	global_load_dword v71, v[4:5], off nt
	global_load_dword v72, v[44:45], off nt
	global_load_dword v73, v[46:47], off nt
	global_load_dword v74, v[48:49], off nt
	global_load_dword v75, v[50:51], off nt
	global_load_dword v76, v[52:53], off nt
	global_load_dword v77, v[54:55], off nt
	global_load_dword v78, v[56:57], off nt
	v_lshl_add_u64 v[4:5], v[2:3], 0, s[2:3]
	s_or_b32 s2, s0, 0x52
	s_ashr_i32 s3, s2, 31
	s_lshl_b64 s[2:3], s[2:3], 12
	v_lshl_add_u64 v[44:45], v[2:3], 0, s[2:3]
	s_or_b32 s2, s0, 0x54
	s_ashr_i32 s3, s2, 31
	s_lshl_b64 s[2:3], s[2:3], 12
	v_lshl_add_u64 v[46:47], v[2:3], 0, s[2:3]
	s_or_b32 s2, s0, 0x56
	s_ashr_i32 s3, s2, 31
	s_lshl_b64 s[2:3], s[2:3], 12
	v_lshl_add_u64 v[48:49], v[2:3], 0, s[2:3]
	s_or_b32 s2, s0, 0x58
	s_ashr_i32 s3, s2, 31
	s_lshl_b64 s[2:3], s[2:3], 12
	v_lshl_add_u64 v[50:51], v[2:3], 0, s[2:3]
	s_or_b32 s2, s0, 0x5a
	s_ashr_i32 s3, s2, 31
	s_lshl_b64 s[2:3], s[2:3], 12
	v_lshl_add_u64 v[52:53], v[2:3], 0, s[2:3]
	s_or_b32 s2, s0, 0x5c
	s_ashr_i32 s3, s2, 31
	s_lshl_b64 s[2:3], s[2:3], 12
	v_lshl_add_u64 v[54:55], v[2:3], 0, s[2:3]
	s_or_b32 s2, s0, 0x5e
	s_ashr_i32 s3, s2, 31
	s_lshl_b64 s[2:3], s[2:3], 12
	v_lshl_add_u64 v[56:57], v[2:3], 0, s[2:3]
	s_or_b32 s2, s0, 0x60
	s_ashr_i32 s3, s2, 31
	s_lshl_b64 s[2:3], s[2:3], 12
	global_load_dword v79, v[4:5], off nt
	global_load_dword v80, v[44:45], off nt
	global_load_dword v81, v[46:47], off nt
	global_load_dword v82, v[48:49], off nt
	global_load_dword v83, v[50:51], off nt
	global_load_dword v84, v[52:53], off nt
	global_load_dword v85, v[54:55], off nt
	global_load_dword v86, v[56:57], off nt
	v_lshl_add_u64 v[4:5], v[2:3], 0, s[2:3]
	s_or_b32 s2, s0, 0x62
	s_ashr_i32 s3, s2, 31
	s_lshl_b64 s[2:3], s[2:3], 12
	v_lshl_add_u64 v[44:45], v[2:3], 0, s[2:3]
	s_or_b32 s2, s0, 0x64
	s_ashr_i32 s3, s2, 31
	s_lshl_b64 s[2:3], s[2:3], 12
	v_lshl_add_u64 v[46:47], v[2:3], 0, s[2:3]
	s_or_b32 s2, s0, 0x66
	s_ashr_i32 s3, s2, 31
	s_lshl_b64 s[2:3], s[2:3], 12
	v_lshl_add_u64 v[48:49], v[2:3], 0, s[2:3]
	s_or_b32 s2, s0, 0x68
	s_ashr_i32 s3, s2, 31
	s_lshl_b64 s[2:3], s[2:3], 12
	v_lshl_add_u64 v[50:51], v[2:3], 0, s[2:3]
	s_or_b32 s2, s0, 0x6a
	s_ashr_i32 s3, s2, 31
	s_lshl_b64 s[2:3], s[2:3], 12
	v_lshl_add_u64 v[52:53], v[2:3], 0, s[2:3]
	s_or_b32 s2, s0, 0x6c
	s_ashr_i32 s3, s2, 31
	s_lshl_b64 s[2:3], s[2:3], 12
	v_lshl_add_u64 v[54:55], v[2:3], 0, s[2:3]
	s_or_b32 s2, s0, 0x6e
	s_ashr_i32 s3, s2, 31
	s_lshl_b64 s[2:3], s[2:3], 12
	v_lshl_add_u64 v[56:57], v[2:3], 0, s[2:3]
	s_or_b32 s2, s0, 0x70
	s_ashr_i32 s3, s2, 31
	s_lshl_b64 s[2:3], s[2:3], 12
	global_load_dword v87, v[4:5], off nt
	global_load_dword v88, v[44:45], off nt
	global_load_dword v89, v[46:47], off nt
	global_load_dword v90, v[48:49], off nt
	global_load_dword v91, v[50:51], off nt
	global_load_dword v92, v[52:53], off nt
	global_load_dword v93, v[54:55], off nt
	global_load_dword v94, v[56:57], off nt
	v_lshl_add_u64 v[4:5], v[2:3], 0, s[2:3]
	s_or_b32 s2, s0, 0x72
	s_ashr_i32 s3, s2, 31
	s_lshl_b64 s[2:3], s[2:3], 12
	v_lshl_add_u64 v[44:45], v[2:3], 0, s[2:3]
	s_or_b32 s2, s0, 0x74
	s_ashr_i32 s3, s2, 31
	s_lshl_b64 s[2:3], s[2:3], 12
	v_lshl_add_u64 v[46:47], v[2:3], 0, s[2:3]
	s_or_b32 s2, s0, 0x76
	s_ashr_i32 s3, s2, 31
	s_lshl_b64 s[2:3], s[2:3], 12
	v_lshl_add_u64 v[48:49], v[2:3], 0, s[2:3]
	s_or_b32 s2, s0, 0x78
	s_ashr_i32 s3, s2, 31
	s_lshl_b64 s[2:3], s[2:3], 12
	v_lshl_add_u64 v[50:51], v[2:3], 0, s[2:3]
	s_or_b32 s2, s0, 0x7a
	s_ashr_i32 s3, s2, 31
	s_lshl_b64 s[2:3], s[2:3], 12
	v_lshl_add_u64 v[52:53], v[2:3], 0, s[2:3]
	s_or_b32 s2, s0, 0x7c
	s_ashr_i32 s3, s2, 31
	s_lshl_b64 s[2:3], s[2:3], 12
	v_lshl_add_u64 v[54:55], v[2:3], 0, s[2:3]
	s_or_b32 s2, s0, 0x7e
	s_ashr_i32 s3, s2, 31
	s_lshl_b64 s[2:3], s[2:3], 12
	v_lshlrev_b32_e32 v95, 2, v7
	v_lshl_add_u64 v[2:3], v[2:3], 0, s[2:3]
	s_waitcnt vmcnt(0)
	ds_bpermute_b32 v56, v95, v11
	ds_bpermute_b32 v57, v95, v11 offset:8
	global_load_dword v96, v[4:5], off nt
	global_load_dword v97, v[44:45], off nt
	global_load_dword v98, v[46:47], off nt
	global_load_dword v99, v[48:49], off nt
	global_load_dword v100, v[50:51], off nt
	global_load_dword v101, v[52:53], off nt
	global_load_dword v102, v[54:55], off nt
	global_load_dword v103, v[2:3], off nt
	ds_bpermute_b32 v2, v95, v11 offset:16
	ds_bpermute_b32 v3, v95, v11 offset:24
	s_waitcnt lgkmcnt(3)
	v_mul_f32_e32 v45, v18, v56
	s_waitcnt lgkmcnt(2)
	v_mul_f32_e32 v5, v19, v57
	v_max3_f32 v18, |v45|, 0, |v5|
	s_waitcnt lgkmcnt(1)
	v_mul_f32_e32 v4, v16, v2
	s_waitcnt lgkmcnt(0)
	v_mul_f32_e32 v3, v17, v3
	ds_bpermute_b32 v2, v95, v11 offset:32
	v_max3_f32 v17, v18, |v4|, |v3|
	ds_bpermute_b32 v18, v95, v11 offset:48
	ds_bpermute_b32 v19, v95, v11 offset:56
	ds_bpermute_b32 v16, v95, v11 offset:40
	s_waitcnt lgkmcnt(3)
	v_mul_f32_e32 v48, v14, v2
	ds_bpermute_b32 v14, v95, v11 offset:80
	s_waitcnt lgkmcnt(3)
	v_mul_f32_e32 v46, v12, v18
	s_waitcnt lgkmcnt(2)
	v_mul_f32_e32 v44, v13, v19
	ds_bpermute_b32 v12, v95, v11 offset:64
	ds_bpermute_b32 v13, v95, v11 offset:72
	s_waitcnt lgkmcnt(3)
	v_mul_f32_e32 v47, v15, v16
	ds_bpermute_b32 v15, v95, v11 offset:88
	s_waitcnt lgkmcnt(3)
	v_mul_f32_e32 v50, v24, v14
	s_waitcnt lgkmcnt(2)
	v_mul_f32_e32 v52, v26, v12
	s_waitcnt lgkmcnt(1)
	v_mul_f32_e32 v51, v27, v13
	ds_bpermute_b32 v12, v95, v11 offset:96
	ds_bpermute_b32 v13, v95, v11 offset:104
	ds_bpermute_b32 v14, v95, v11 offset:112
	s_waitcnt lgkmcnt(3)
	v_mul_f32_e32 v49, v25, v15
	ds_bpermute_b32 v15, v95, v11 offset:120
	s_waitcnt lgkmcnt(3)
	v_mul_f32_e32 v56, v22, v12
	s_waitcnt lgkmcnt(2)
	v_mul_f32_e32 v55, v23, v13
	s_waitcnt lgkmcnt(1)
	v_mul_f32_e32 v54, v20, v14
	ds_bpermute_b32 v12, v95, v11 offset:128
	ds_bpermute_b32 v13, v95, v11 offset:136
	ds_bpermute_b32 v14, v95, v11 offset:144
	s_waitcnt lgkmcnt(3)
	v_mul_f32_e32 v53, v21, v15
	ds_bpermute_b32 v15, v95, v11 offset:152
	s_waitcnt lgkmcnt(3)
	v_mul_f32_e32 v60, v34, v12
	s_waitcnt lgkmcnt(2)
	v_mul_f32_e32 v59, v35, v13
	s_waitcnt lgkmcnt(1)
	v_mul_f32_e32 v58, v32, v14
	ds_bpermute_b32 v12, v95, v11 offset:160
	ds_bpermute_b32 v13, v95, v11 offset:168
	ds_bpermute_b32 v14, v95, v11 offset:176
	s_waitcnt lgkmcnt(3)
	v_mul_f32_e32 v57, v33, v15
	ds_bpermute_b32 v15, v95, v11 offset:184
	s_waitcnt lgkmcnt(3)
	v_mul_f32_e32 v64, v30, v12
	s_waitcnt lgkmcnt(2)
	v_mul_f32_e32 v63, v31, v13
	s_waitcnt lgkmcnt(1)
	v_mul_f32_e32 v62, v28, v14
	ds_bpermute_b32 v12, v95, v11 offset:192
	ds_bpermute_b32 v13, v95, v11 offset:200
	ds_bpermute_b32 v14, v95, v11 offset:208
	s_waitcnt lgkmcnt(3)
	v_mul_f32_e32 v61, v29, v15
	ds_bpermute_b32 v15, v95, v11 offset:216
	s_waitcnt lgkmcnt(3)
	v_mul_f32_e32 v66, v42, v12
	s_waitcnt lgkmcnt(2)
	v_mul_f32_e32 v65, v43, v13
	s_waitcnt lgkmcnt(1)
	v_mul_f32_e32 v43, v40, v14
	ds_bpermute_b32 v12, v95, v11 offset:224
	ds_bpermute_b32 v13, v95, v11 offset:232
	ds_bpermute_b32 v14, v95, v11 offset:240
	ds_bpermute_b32 v11, v95, v11 offset:248
	s_waitcnt lgkmcnt(4)
	v_mul_f32_e32 v42, v41, v15
	s_waitcnt lgkmcnt(3)
	v_mul_f32_e32 v70, v38, v12
	ds_bpermute_b32 v12, v95, v10 offset:8
	ds_bpermute_b32 v15, v95, v10 offset:16
	s_waitcnt lgkmcnt(2)
	v_mul_f32_e32 v67, v37, v11
	ds_bpermute_b32 v11, v95, v10
	ds_bpermute_b32 v16, v95, v10 offset:24
	v_mul_f32_e32 v69, v39, v13
	v_mul_f32_e32 v68, v36, v14
	s_waitcnt lgkmcnt(3)
	v_mul_f32_e32 v13, v72, v12
	s_waitcnt lgkmcnt(1)
	v_mul_f32_e32 v14, v71, v11
	v_mul_f32_e32 v12, v73, v15
	s_waitcnt lgkmcnt(0)
	v_mul_f32_e32 v11, v74, v16
	ds_bpermute_b32 v15, v95, v10 offset:32
	ds_bpermute_b32 v16, v95, v10 offset:40
	ds_bpermute_b32 v19, v95, v10 offset:48
	ds_bpermute_b32 v20, v95, v10 offset:56
	v_max3_f32 v2, v17, |v48|, |v47|
	s_waitcnt lgkmcnt(3)
	v_mul_f32_e32 v18, v75, v15
	s_waitcnt lgkmcnt(2)
	v_mul_f32_e32 v17, v76, v16
	s_waitcnt lgkmcnt(1)
	v_mul_f32_e32 v16, v77, v19
	s_waitcnt lgkmcnt(0)
	v_mul_f32_e32 v15, v78, v20
	ds_bpermute_b32 v19, v95, v10 offset:64
	ds_bpermute_b32 v20, v95, v10 offset:72
	ds_bpermute_b32 v23, v95, v10 offset:80
	ds_bpermute_b32 v24, v95, v10 offset:88
	v_max3_f32 v2, v2, |v46|, |v44|
	v_max3_f32 v2, v2, |v52|, |v51|
	s_waitcnt lgkmcnt(3)
	v_mul_f32_e32 v22, v79, v19
	s_waitcnt lgkmcnt(2)
	v_mul_f32_e32 v21, v80, v20
	s_waitcnt lgkmcnt(1)
	v_mul_f32_e32 v20, v81, v23
	s_waitcnt lgkmcnt(0)
	v_mul_f32_e32 v19, v82, v24
	ds_bpermute_b32 v23, v95, v10 offset:96
	ds_bpermute_b32 v24, v95, v10 offset:104
	ds_bpermute_b32 v27, v95, v10 offset:112
	ds_bpermute_b32 v28, v95, v10 offset:120
	v_max3_f32 v2, v2, |v50|, |v49|
	v_max3_f32 v2, v2, |v56|, |v55|
	v_max3_f32 v2, v2, |v54|, |v53|
	v_max3_f32 v2, v2, |v60|, |v59|
	v_max3_f32 v2, v2, |v58|, |v57|
	s_waitcnt lgkmcnt(3)
	v_mul_f32_e32 v26, v83, v23
	s_waitcnt lgkmcnt(2)
	v_mul_f32_e32 v25, v84, v24
	s_waitcnt lgkmcnt(1)
	v_mul_f32_e32 v24, v85, v27
	s_waitcnt lgkmcnt(0)
	v_mul_f32_e32 v23, v86, v28
	ds_bpermute_b32 v27, v95, v10 offset:128
	ds_bpermute_b32 v28, v95, v10 offset:136
	ds_bpermute_b32 v31, v95, v10 offset:144
	ds_bpermute_b32 v32, v95, v10 offset:152
	v_max3_f32 v2, v2, |v64|, |v63|
	v_max3_f32 v2, v2, |v62|, |v61|
	v_max3_f32 v2, v2, |v66|, |v65|
	v_max3_f32 v2, v2, |v43|, |v42|
	v_max3_f32 v2, v2, |v70|, |v69|
	s_waitcnt lgkmcnt(3)
	v_mul_f32_e32 v30, v87, v27
	s_waitcnt lgkmcnt(2)
	v_mul_f32_e32 v29, v88, v28
	s_waitcnt lgkmcnt(1)
	v_mul_f32_e32 v28, v89, v31
	s_waitcnt lgkmcnt(0)
	v_mul_f32_e32 v27, v90, v32
	ds_bpermute_b32 v31, v95, v10 offset:160
	ds_bpermute_b32 v32, v95, v10 offset:168
	ds_bpermute_b32 v35, v95, v10 offset:176
	ds_bpermute_b32 v36, v95, v10 offset:184
	v_max3_f32 v2, v2, |v68|, |v67|
	v_max3_f32 v2, v2, |v14|, |v13|
	v_max3_f32 v2, v2, |v12|, |v11|
	v_max3_f32 v2, v2, |v18|, |v17|
	v_max3_f32 v2, v2, |v16|, |v15|
	s_waitcnt lgkmcnt(3)
	v_mul_f32_e32 v34, v91, v31
	s_waitcnt lgkmcnt(2)
	v_mul_f32_e32 v33, v92, v32
	s_waitcnt lgkmcnt(1)
	v_mul_f32_e32 v32, v93, v35
	s_waitcnt lgkmcnt(0)
	v_mul_f32_e32 v31, v94, v36
	ds_bpermute_b32 v35, v95, v10 offset:192
	ds_bpermute_b32 v36, v95, v10 offset:200
	ds_bpermute_b32 v39, v95, v10 offset:208
	ds_bpermute_b32 v40, v95, v10 offset:216
	v_max3_f32 v2, v2, |v22|, |v21|
	v_max3_f32 v2, v2, |v20|, |v19|
	v_max3_f32 v2, v2, |v26|, |v25|
	v_max3_f32 v2, v2, |v24|, |v23|
	v_max3_f32 v2, v2, |v30|, |v29|
	s_waitcnt vmcnt(7) lgkmcnt(3)
	v_mul_f32_e32 v38, v96, v35
	s_waitcnt vmcnt(6) lgkmcnt(2)
	v_mul_f32_e32 v37, v97, v36
	s_waitcnt vmcnt(5) lgkmcnt(1)
	v_mul_f32_e32 v36, v98, v39
	s_waitcnt vmcnt(4) lgkmcnt(0)
	v_mul_f32_e32 v35, v99, v40
	ds_bpermute_b32 v39, v95, v10 offset:224
	ds_bpermute_b32 v40, v95, v10 offset:232
	v_max3_f32 v2, v2, |v28|, |v27|
	ds_bpermute_b32 v71, v95, v10 offset:240
	ds_bpermute_b32 v10, v95, v10 offset:248
	v_max3_f32 v2, v2, |v34|, |v33|
	v_max3_f32 v2, v2, |v32|, |v31|
	v_max3_f32 v2, v2, |v38|, |v37|
	v_max3_f32 v2, v2, |v36|, |v35|
	s_waitcnt vmcnt(3) lgkmcnt(3)
	v_mul_f32_e32 v41, v100, v39
	s_waitcnt vmcnt(2) lgkmcnt(2)
	v_mul_f32_e32 v40, v101, v40
	v_max3_f32 v2, v2, |v41|, |v40|
	s_waitcnt vmcnt(1) lgkmcnt(1)
	v_mul_f32_e32 v39, v102, v71
	s_waitcnt vmcnt(0) lgkmcnt(0)
	v_mul_f32_e32 v10, v103, v10
	v_max3_f32 v2, v2, |v39|, |v10|
	v_mov_b32_e32 v71, v2
	s_lshl_b32 s4, s13, 5
	s_nop 0
	v_permlane32_swap_b32_e32 v2, v71
	v_cmp_gt_u32_e32 vcc, 32, v6
	s_and_saveexec_b64 s[2:3], vcc
	s_cbranch_execz .LBB0_379
	v_max_f32_e32 v2, v2, v2
	v_max_f32_e32 v71, v71, v71
	s_add_i32 s5, s0, 0
	v_max_f32_e32 v2, v2, v71
	v_lshl_add_u32 v71, v6, 2, s5
	v_add_u32_e32 v71, 0x20000, v71
	ds_write_b32 v71, v2

.LBB0_388:
	s_ashr_i32 s4, s0, 31
	s_lshr_b32 s4, s4, 27
	s_add_i32 s4, s0, s4
	s_ashr_i32 s4, s4, 5
	s_lshl_b32 s6, s4, 6
	s_lshl_b32 s7, s4, 10
	s_mul_i32 s4, s4, 0xffd40000
	v_or_b32_e32 v18, s6, v7
	s_sub_i32 s8, s1, s7
	s_ashr_i32 s7, s6, 31
	v_add_u32_e32 v20, s4, v9
	v_or_b32_e32 v22, 2, v18
	v_or_b32_e32 v24, 4, v18
	v_or_b32_e32 v26, 6, v18
	v_or_b32_e32 v28, 8, v18
	v_or_b32_e32 v30, 10, v18
	v_or_b32_e32 v32, 12, v18
	v_or_b32_e32 v34, 14, v18
	v_or_b32_e32 v36, 16, v18
	s_ashr_i32 s9, s8, 31
	v_ashrrev_i32_e32 v19, 31, v18
	v_or_b32_e32 v38, 18, v18
	v_or_b32_e32 v40, 20, v18
	v_or_b32_e32 v42, 22, v18
	v_or_b32_e32 v44, 24, v18
	v_or_b32_e32 v46, 26, v18
	v_or_b32_e32 v48, 28, v18
	v_or_b32_e32 v50, 30, v18
	v_or_b32_e32 v52, 32, v18
	v_or_b32_e32 v54, 34, v18
	v_or_b32_e32 v56, 36, v18
	v_or_b32_e32 v58, 38, v18
	v_or_b32_e32 v60, 40, v18
	v_or_b32_e32 v62, 42, v18
	v_or_b32_e32 v64, 44, v18
	v_or_b32_e32 v66, 46, v18
	v_or_b32_e32 v68, 48, v18
	v_or_b32_e32 v70, 50, v18
	v_or_b32_e32 v72, 52, v18
	v_or_b32_e32 v74, 54, v18
	v_or_b32_e32 v76, 56, v18
	v_or_b32_e32 v78, 58, v18
	v_or_b32_e32 v80, 60, v18
	v_or_b32_e32 v82, 62, v18
	v_lshl_add_u64 v[84:85], s[6:7], 1, v[4:5]
	v_ashrrev_i32_e32 v21, 31, v20
	v_ashrrev_i32_e32 v23, 31, v22
	v_ashrrev_i32_e32 v25, 31, v24
	v_ashrrev_i32_e32 v27, 31, v26
	v_ashrrev_i32_e32 v29, 31, v28
	v_ashrrev_i32_e32 v31, 31, v30
	v_ashrrev_i32_e32 v33, 31, v32
	v_ashrrev_i32_e32 v35, 31, v34
	v_ashrrev_i32_e32 v37, 31, v36
	v_add_u32_e32 v86, 0x5800, v20
	v_add_u32_e32 v88, 0xb000, v20
	v_add_u32_e32 v90, 0x10800, v20
	v_lshl_add_u64 v[92:93], s[8:9], 2, v[2:3]
	v_lshlrev_b64 v[18:19], 12, v[18:19]
	v_ashrrev_i32_e32 v39, 31, v38
	v_ashrrev_i32_e32 v41, 31, v40
	v_ashrrev_i32_e32 v43, 31, v42
	v_ashrrev_i32_e32 v45, 31, v44
	v_ashrrev_i32_e32 v47, 31, v46
	v_ashrrev_i32_e32 v49, 31, v48
	v_ashrrev_i32_e32 v51, 31, v50
	v_ashrrev_i32_e32 v53, 31, v52
	v_ashrrev_i32_e32 v55, 31, v54
	v_ashrrev_i32_e32 v57, 31, v56
	v_ashrrev_i32_e32 v59, 31, v58
	v_ashrrev_i32_e32 v61, 31, v60
	v_ashrrev_i32_e32 v63, 31, v62
	v_ashrrev_i32_e32 v65, 31, v64
	v_ashrrev_i32_e32 v67, 31, v66
	v_ashrrev_i32_e32 v69, 31, v68
	v_ashrrev_i32_e32 v71, 31, v70
	v_ashrrev_i32_e32 v73, 31, v72
	v_ashrrev_i32_e32 v75, 31, v74
	v_ashrrev_i32_e32 v77, 31, v76
	v_ashrrev_i32_e32 v79, 31, v78
	v_ashrrev_i32_e32 v81, 31, v80
	v_ashrrev_i32_e32 v83, 31, v82
	v_lshl_add_u64 v[94:95], v[20:21], 1, v[84:85]
	v_lshlrev_b64 v[20:21], 12, v[22:23]
	v_lshlrev_b64 v[22:23], 12, v[24:25]
	v_lshlrev_b64 v[24:25], 12, v[26:27]
	v_lshlrev_b64 v[26:27], 12, v[28:29]
	v_lshlrev_b64 v[28:29], 12, v[30:31]
	v_lshlrev_b64 v[30:31], 12, v[32:33]
	v_lshlrev_b64 v[32:33], 12, v[34:35]
	v_lshlrev_b64 v[34:35], 12, v[36:37]
	v_ashrrev_i32_e32 v87, 31, v86
	v_ashrrev_i32_e32 v89, 31, v88
	v_ashrrev_i32_e32 v91, 31, v90
	v_lshl_add_u64 v[18:19], v[92:93], 0, v[18:19]
	v_lshlrev_b64 v[36:37], 12, v[38:39]
	v_lshlrev_b64 v[38:39], 12, v[40:41]
	v_lshlrev_b64 v[40:41], 12, v[42:43]
	v_lshlrev_b64 v[42:43], 12, v[44:45]
	v_lshlrev_b64 v[44:45], 12, v[46:47]
	v_lshlrev_b64 v[46:47], 12, v[48:49]
	v_lshlrev_b64 v[48:49], 12, v[50:51]
	v_lshlrev_b64 v[50:51], 12, v[52:53]
	v_lshlrev_b64 v[52:53], 12, v[54:55]
	v_lshlrev_b64 v[54:55], 12, v[56:57]
	v_lshlrev_b64 v[56:57], 12, v[58:59]
	v_lshlrev_b64 v[58:59], 12, v[60:61]
	v_lshlrev_b64 v[60:61], 12, v[62:63]
	v_lshlrev_b64 v[62:63], 12, v[64:65]
	v_lshlrev_b64 v[64:65], 12, v[66:67]
	v_lshlrev_b64 v[66:67], 12, v[68:69]
	v_lshlrev_b64 v[68:69], 12, v[70:71]
	v_lshlrev_b64 v[70:71], 12, v[72:73]
	v_lshlrev_b64 v[72:73], 12, v[74:75]
	v_lshlrev_b64 v[74:75], 12, v[76:77]
	v_lshlrev_b64 v[76:77], 12, v[78:79]
	v_lshlrev_b64 v[78:79], 12, v[80:81]
	v_lshlrev_b64 v[80:81], 12, v[82:83]
	v_lshl_add_u64 v[20:21], v[92:93], 0, v[20:21]
	v_lshl_add_u64 v[22:23], v[92:93], 0, v[22:23]
	v_lshl_add_u64 v[24:25], v[92:93], 0, v[24:25]
	v_lshl_add_u64 v[26:27], v[92:93], 0, v[26:27]
	v_lshl_add_u64 v[28:29], v[92:93], 0, v[28:29]
	v_lshl_add_u64 v[30:31], v[92:93], 0, v[30:31]
	v_lshl_add_u64 v[32:33], v[92:93], 0, v[32:33]
	v_lshl_add_u64 v[34:35], v[92:93], 0, v[34:35]
	v_lshl_add_u64 v[82:83], v[86:87], 1, v[84:85]
	v_lshl_add_u64 v[86:87], v[88:89], 1, v[84:85]
	v_lshl_add_u64 v[84:85], v[90:91], 1, v[84:85]
	v_lshl_add_u64 v[36:37], v[92:93], 0, v[36:37]
	v_lshl_add_u64 v[38:39], v[92:93], 0, v[38:39]
	v_lshl_add_u64 v[40:41], v[92:93], 0, v[40:41]
	v_lshl_add_u64 v[42:43], v[92:93], 0, v[42:43]
	v_lshl_add_u64 v[44:45], v[92:93], 0, v[44:45]
	v_lshl_add_u64 v[46:47], v[92:93], 0, v[46:47]
	v_lshl_add_u64 v[48:49], v[92:93], 0, v[48:49]
	v_lshl_add_u64 v[50:51], v[92:93], 0, v[50:51]
	v_lshl_add_u64 v[52:53], v[92:93], 0, v[52:53]
	v_lshl_add_u64 v[54:55], v[92:93], 0, v[54:55]
	v_lshl_add_u64 v[56:57], v[92:93], 0, v[56:57]
	v_lshl_add_u64 v[58:59], v[92:93], 0, v[58:59]
	v_lshl_add_u64 v[60:61], v[92:93], 0, v[60:61]
	v_lshl_add_u64 v[62:63], v[92:93], 0, v[62:63]
	v_lshl_add_u64 v[64:65], v[92:93], 0, v[64:65]
	v_lshl_add_u64 v[66:67], v[92:93], 0, v[66:67]
	v_lshl_add_u64 v[68:69], v[92:93], 0, v[68:69]
	v_lshl_add_u64 v[70:71], v[92:93], 0, v[70:71]
	v_lshl_add_u64 v[72:73], v[92:93], 0, v[72:73]
	v_lshl_add_u64 v[74:75], v[92:93], 0, v[74:75]
	v_lshl_add_u64 v[76:77], v[92:93], 0, v[76:77]
	v_lshl_add_u64 v[78:79], v[92:93], 0, v[78:79]
	v_lshl_add_u64 v[80:81], v[92:93], 0, v[80:81]
	global_load_dword v88, v[18:19], off nt
	global_load_dword v89, v[20:21], off nt
	global_load_dword v90, v[22:23], off nt
	global_load_dword v91, v[24:25], off nt
	global_load_dword v92, v[26:27], off nt
	global_load_dword v93, v[28:29], off nt
	global_load_dword v96, v[30:31], off nt
	global_load_dword v97, v[32:33], off nt
	global_load_dword v98, v[34:35], off nt
	global_load_dword v99, v[36:37], off nt
	global_load_dword v100, v[38:39], off nt
	global_load_dword v101, v[40:41], off nt
	global_load_dword v102, v[42:43], off nt
	global_load_dword v103, v[44:45], off nt
	global_load_dword v104, v[46:47], off nt
	global_load_dword v18, v[48:49], off nt
	global_load_dword v19, v[50:51], off nt
	global_load_dword v20, v[52:53], off nt
	global_load_dword v21, v[54:55], off nt
	global_load_dword v22, v[56:57], off nt
	global_load_dword v23, v[58:59], off nt
	global_load_dword v24, v[60:61], off nt
	global_load_dword v25, v[62:63], off nt
	global_load_dword v26, v[64:65], off nt
	global_load_dword v27, v[66:67], off nt
	global_load_dword v28, v[68:69], off nt
	global_load_dword v29, v[70:71], off nt
	global_load_dword v30, v[72:73], off nt
	global_load_dword v31, v[74:75], off nt
	global_load_dword v32, v[76:77], off nt
	global_load_dword v33, v[78:79], off nt
	global_load_dword v34, v[80:81], off nt
	s_waitcnt vmcnt(0)
	ds_write2_b32 v10, v88, v89 offset1:66
	ds_write2_b32 v10, v90, v91 offset0:132 offset1:198
	ds_write2_b32 v11, v92, v93 offset0:8 offset1:74
	ds_write2_b32 v11, v96, v97 offset0:140 offset1:206
	ds_write2_b32 v12, v98, v99 offset0:16 offset1:82
	ds_write2_b32 v12, v100, v101 offset0:148 offset1:214
	ds_write2_b32 v13, v102, v103 offset0:24 offset1:90
	ds_write2_b32 v13, v104, v18 offset0:156 offset1:222
	ds_write2_b32 v14, v19, v20 offset0:32 offset1:98
	ds_write2_b32 v14, v21, v22 offset0:164 offset1:230
	ds_write2_b32 v15, v23, v24 offset0:40 offset1:106
	ds_write2_b32 v15, v25, v26 offset0:172 offset1:238
	ds_write2_b32 v16, v27, v28 offset0:48 offset1:114
	ds_write2_b32 v16, v29, v30 offset0:180 offset1:246
	ds_write2_b32 v17, v31, v32 offset0:56 offset1:122
	ds_write2_b32 v17, v33, v34 offset0:188 offset1:254
	s_waitcnt lgkmcnt(0)
	ds_read2_b32 v[18:19], v8 offset1:33
	ds_read2_b32 v[20:21], v8 offset0:66 offset1:99
	ds_read2_b32 v[22:23], v8 offset0:132 offset1:165
	ds_read2_b32 v[24:25], v8 offset0:198 offset1:231
	s_add_i32 s5, s0, 0x200
	s_waitcnt lgkmcnt(3)
	v_bfe_u32 v26, v18, 16, 1
	s_waitcnt lgkmcnt(2)
	v_bfe_u32 v28, v20, 16, 1
	s_waitcnt lgkmcnt(1)
	v_bfe_u32 v30, v22, 16, 1
	s_waitcnt lgkmcnt(0)
	v_bfe_u32 v32, v24, 16, 1
	v_bfe_u32 v27, v19, 16, 1
	v_bfe_u32 v29, v21, 16, 1
	v_bfe_u32 v31, v23, 16, 1
	v_bfe_u32 v33, v25, 16, 1
	v_add3_u32 v18, v18, v26, s2
	v_add3_u32 v20, v20, v28, s2
	v_add3_u32 v22, v22, v30, s2
	v_add3_u32 v24, v24, v32, s2
	v_add3_u32 v19, v19, v27, s2
	v_add3_u32 v21, v21, v29, s2
	v_add3_u32 v23, v23, v31, s2
	v_add3_u32 v25, v25, v33, s2
	v_lshrrev_b32_e32 v18, 16, v18
	v_lshrrev_b32_e32 v20, 16, v20
	v_lshrrev_b32_e32 v22, 16, v22
	v_lshrrev_b32_e32 v24, 16, v24
	v_and_or_b32 v18, v19, s3, v18
	v_and_or_b32 v19, v21, s3, v20
	v_and_or_b32 v20, v23, s3, v22
	v_and_or_b32 v21, v25, s3, v24
	global_store_dwordx4 v[94:95], v[18:21], off sc1
	s_nop 1
	ds_read2_b32 v[18:19], v8 offset0:8 offset1:41
	ds_read2_b32 v[20:21], v8 offset0:74 offset1:107
	ds_read2_b32 v[22:23], v8 offset0:140 offset1:173
	ds_read2_b32 v[24:25], v8 offset0:206 offset1:239
	s_addk_i32 s1, 0x4000
	s_waitcnt lgkmcnt(3)
	v_bfe_u32 v26, v18, 16, 1
	s_waitcnt lgkmcnt(2)
	v_bfe_u32 v28, v20, 16, 1
	s_waitcnt lgkmcnt(1)
	v_bfe_u32 v30, v22, 16, 1
	s_waitcnt lgkmcnt(0)
	v_bfe_u32 v32, v24, 16, 1
	v_bfe_u32 v27, v19, 16, 1
	v_bfe_u32 v29, v21, 16, 1
	v_bfe_u32 v31, v23, 16, 1
	v_bfe_u32 v33, v25, 16, 1
	v_add3_u32 v18, v18, v26, s2
	v_add3_u32 v20, v20, v28, s2
	v_add3_u32 v22, v22, v30, s2
	v_add3_u32 v24, v24, v32, s2
	v_add3_u32 v19, v19, v27, s2
	v_add3_u32 v21, v21, v29, s2
	v_add3_u32 v23, v23, v31, s2
	v_add3_u32 v25, v25, v33, s2
	v_lshrrev_b32_e32 v18, 16, v18
	v_lshrrev_b32_e32 v20, 16, v20
	v_lshrrev_b32_e32 v22, 16, v22
	v_lshrrev_b32_e32 v24, 16, v24
	v_and_or_b32 v18, v19, s3, v18
	v_and_or_b32 v19, v21, s3, v20
	v_and_or_b32 v20, v23, s3, v22
	v_and_or_b32 v21, v25, s3, v24
	global_store_dwordx4 v[82:83], v[18:21], off sc1
	s_nop 1
	ds_read2_b32 v[18:19], v8 offset0:16 offset1:49
	ds_read2_b32 v[20:21], v8 offset0:82 offset1:115
	ds_read2_b32 v[22:23], v8 offset0:148 offset1:181
	ds_read2_b32 v[24:25], v8 offset0:214 offset1:247
	v_add_u32_e32 v9, 0x2c00000, v9
	s_waitcnt lgkmcnt(3)
	v_bfe_u32 v26, v18, 16, 1
	s_waitcnt lgkmcnt(2)
	v_bfe_u32 v28, v20, 16, 1
	s_waitcnt lgkmcnt(1)
	v_bfe_u32 v30, v22, 16, 1
	s_waitcnt lgkmcnt(0)
	v_bfe_u32 v32, v24, 16, 1
	v_bfe_u32 v27, v19, 16, 1
	v_bfe_u32 v29, v21, 16, 1
	v_bfe_u32 v31, v23, 16, 1
	v_bfe_u32 v33, v25, 16, 1
	v_add3_u32 v18, v18, v26, s2
	v_add3_u32 v20, v20, v28, s2
	v_add3_u32 v22, v22, v30, s2
	v_add3_u32 v24, v24, v32, s2
	v_add3_u32 v19, v19, v27, s2
	v_add3_u32 v21, v21, v29, s2
	v_add3_u32 v23, v23, v31, s2
	v_add3_u32 v25, v25, v33, s2
	v_lshrrev_b32_e32 v18, 16, v18
	v_lshrrev_b32_e32 v20, 16, v20
	v_lshrrev_b32_e32 v22, 16, v22
	v_lshrrev_b32_e32 v24, 16, v24
	v_and_or_b32 v18, v19, s3, v18
	v_and_or_b32 v19, v21, s3, v20
	v_and_or_b32 v20, v23, s3, v22
	v_and_or_b32 v21, v25, s3, v24
	global_store_dwordx4 v[86:87], v[18:21], off sc1
	s_nop 1
	ds_read2_b32 v[18:19], v8 offset0:24 offset1:57
	ds_read2_b32 v[20:21], v8 offset0:90 offset1:123
	ds_read2_b32 v[22:23], v8 offset0:156 offset1:189
	ds_read2_b32 v[24:25], v8 offset0:222 offset1:255
	s_cmpk_gt_i32 s0, 0x37f
	s_waitcnt lgkmcnt(3)
	v_bfe_u32 v26, v18, 16, 1
	s_waitcnt lgkmcnt(2)
	v_bfe_u32 v28, v20, 16, 1
	s_waitcnt lgkmcnt(1)
	v_bfe_u32 v30, v22, 16, 1
	s_waitcnt lgkmcnt(0)
	v_bfe_u32 v32, v24, 16, 1
	v_bfe_u32 v27, v19, 16, 1
	v_bfe_u32 v29, v21, 16, 1
	v_bfe_u32 v31, v23, 16, 1
	v_bfe_u32 v33, v25, 16, 1
	v_add3_u32 v18, v18, v26, s2
	v_add3_u32 v20, v20, v28, s2
	v_add3_u32 v22, v22, v30, s2
	v_add3_u32 v24, v24, v32, s2
	v_add3_u32 v19, v19, v27, s2
	v_add3_u32 v21, v21, v29, s2
	v_add3_u32 v23, v23, v31, s2
	v_add3_u32 v25, v25, v33, s2
	v_lshrrev_b32_e32 v18, 16, v18
	v_lshrrev_b32_e32 v20, 16, v20
	v_lshrrev_b32_e32 v22, 16, v22
	v_lshrrev_b32_e32 v24, 16, v24
	v_and_or_b32 v18, v19, s3, v18
	v_and_or_b32 v19, v21, s3, v20
	v_and_or_b32 v20, v23, s3, v22
	v_and_or_b32 v21, v25, s3, v24
	global_store_dwordx4 v[84:85], v[18:21], off sc1
	s_nop 1
	s_waitcnt lgkmcnt(0)
	s_mov_b32 s0, s5
	s_cbranch_scc0 .LBB0_388

.LBB0_392:
	s_ashr_i32 s4, s0, 31
	s_lshr_b32 s4, s4, 27
	s_add_i32 s4, s0, s4
	s_ashr_i32 s4, s4, 5
	s_lshl_b32 s6, s4, 6
	s_lshl_b32 s7, s4, 10
	s_mul_i32 s4, s4, 0xffd40000
	v_or_b32_e32 v18, s6, v7
	s_sub_i32 s8, s1, s7
	s_ashr_i32 s7, s6, 31
	v_add_u32_e32 v20, s4, v8
	v_or_b32_e32 v22, 2, v18
	v_or_b32_e32 v24, 4, v18
	v_or_b32_e32 v26, 6, v18
	v_or_b32_e32 v28, 8, v18
	v_or_b32_e32 v30, 10, v18
	v_or_b32_e32 v32, 12, v18
	v_or_b32_e32 v34, 14, v18
	v_or_b32_e32 v36, 16, v18
	s_ashr_i32 s9, s8, 31
	v_ashrrev_i32_e32 v19, 31, v18
	v_or_b32_e32 v38, 18, v18
	v_or_b32_e32 v40, 20, v18
	v_or_b32_e32 v42, 22, v18
	v_or_b32_e32 v44, 24, v18
	v_or_b32_e32 v46, 26, v18
	v_or_b32_e32 v48, 28, v18
	v_or_b32_e32 v50, 30, v18
	v_or_b32_e32 v52, 32, v18
	v_or_b32_e32 v54, 34, v18
	v_or_b32_e32 v56, 36, v18
	v_or_b32_e32 v58, 38, v18
	v_or_b32_e32 v60, 40, v18
	v_or_b32_e32 v62, 42, v18
	v_or_b32_e32 v64, 44, v18
	v_or_b32_e32 v66, 46, v18
	v_or_b32_e32 v68, 48, v18
	v_or_b32_e32 v70, 50, v18
	v_or_b32_e32 v72, 52, v18
	v_or_b32_e32 v74, 54, v18
	v_or_b32_e32 v76, 56, v18
	v_or_b32_e32 v78, 58, v18
	v_or_b32_e32 v80, 60, v18
	v_or_b32_e32 v82, 62, v18
	v_lshl_add_u64 v[84:85], s[6:7], 1, v[4:5]
	v_ashrrev_i32_e32 v21, 31, v20
	v_ashrrev_i32_e32 v23, 31, v22
	v_ashrrev_i32_e32 v25, 31, v24
	v_ashrrev_i32_e32 v27, 31, v26
	v_ashrrev_i32_e32 v29, 31, v28
	v_ashrrev_i32_e32 v31, 31, v30
	v_ashrrev_i32_e32 v33, 31, v32
	v_ashrrev_i32_e32 v35, 31, v34
	v_ashrrev_i32_e32 v37, 31, v36
	v_add_u32_e32 v86, 0x5800, v20
	v_add_u32_e32 v88, 0xb000, v20
	v_add_u32_e32 v90, 0x10800, v20
	v_lshl_add_u64 v[92:93], s[8:9], 2, v[2:3]
	v_lshlrev_b64 v[18:19], 12, v[18:19]
	v_ashrrev_i32_e32 v39, 31, v38
	v_ashrrev_i32_e32 v41, 31, v40
	v_ashrrev_i32_e32 v43, 31, v42
	v_ashrrev_i32_e32 v45, 31, v44
	v_ashrrev_i32_e32 v47, 31, v46
	v_ashrrev_i32_e32 v49, 31, v48
	v_ashrrev_i32_e32 v51, 31, v50
	v_ashrrev_i32_e32 v53, 31, v52
	v_ashrrev_i32_e32 v55, 31, v54
	v_ashrrev_i32_e32 v57, 31, v56
	v_ashrrev_i32_e32 v59, 31, v58
	v_ashrrev_i32_e32 v61, 31, v60
	v_ashrrev_i32_e32 v63, 31, v62
	v_ashrrev_i32_e32 v65, 31, v64
	v_ashrrev_i32_e32 v67, 31, v66
	v_ashrrev_i32_e32 v69, 31, v68
	v_ashrrev_i32_e32 v71, 31, v70
	v_ashrrev_i32_e32 v73, 31, v72
	v_ashrrev_i32_e32 v75, 31, v74
	v_ashrrev_i32_e32 v77, 31, v76
	v_ashrrev_i32_e32 v79, 31, v78
	v_ashrrev_i32_e32 v81, 31, v80
	v_ashrrev_i32_e32 v83, 31, v82
	v_lshl_add_u64 v[94:95], v[20:21], 1, v[84:85]
	v_lshlrev_b64 v[20:21], 12, v[22:23]
	v_lshlrev_b64 v[22:23], 12, v[24:25]
	v_lshlrev_b64 v[24:25], 12, v[26:27]
	v_lshlrev_b64 v[26:27], 12, v[28:29]
	v_lshlrev_b64 v[28:29], 12, v[30:31]
	v_lshlrev_b64 v[30:31], 12, v[32:33]
	v_lshlrev_b64 v[32:33], 12, v[34:35]
	v_lshlrev_b64 v[34:35], 12, v[36:37]
	v_ashrrev_i32_e32 v87, 31, v86
	v_ashrrev_i32_e32 v89, 31, v88
	v_ashrrev_i32_e32 v91, 31, v90
	v_lshl_add_u64 v[18:19], v[92:93], 0, v[18:19]
	v_lshlrev_b64 v[36:37], 12, v[38:39]
	v_lshlrev_b64 v[38:39], 12, v[40:41]
	v_lshlrev_b64 v[40:41], 12, v[42:43]
	v_lshlrev_b64 v[42:43], 12, v[44:45]
	v_lshlrev_b64 v[44:45], 12, v[46:47]
	v_lshlrev_b64 v[46:47], 12, v[48:49]
	v_lshlrev_b64 v[48:49], 12, v[50:51]
	v_lshlrev_b64 v[50:51], 12, v[52:53]
	v_lshlrev_b64 v[52:53], 12, v[54:55]
	v_lshlrev_b64 v[54:55], 12, v[56:57]
	v_lshlrev_b64 v[56:57], 12, v[58:59]
	v_lshlrev_b64 v[58:59], 12, v[60:61]
	v_lshlrev_b64 v[60:61], 12, v[62:63]
	v_lshlrev_b64 v[62:63], 12, v[64:65]
	v_lshlrev_b64 v[64:65], 12, v[66:67]
	v_lshlrev_b64 v[66:67], 12, v[68:69]
	v_lshlrev_b64 v[68:69], 12, v[70:71]
	v_lshlrev_b64 v[70:71], 12, v[72:73]
	v_lshlrev_b64 v[72:73], 12, v[74:75]
	v_lshlrev_b64 v[74:75], 12, v[76:77]
	v_lshlrev_b64 v[76:77], 12, v[78:79]
	v_lshlrev_b64 v[78:79], 12, v[80:81]
	v_lshlrev_b64 v[80:81], 12, v[82:83]
	v_lshl_add_u64 v[20:21], v[92:93], 0, v[20:21]
	v_lshl_add_u64 v[22:23], v[92:93], 0, v[22:23]
	v_lshl_add_u64 v[24:25], v[92:93], 0, v[24:25]
	v_lshl_add_u64 v[26:27], v[92:93], 0, v[26:27]
	v_lshl_add_u64 v[28:29], v[92:93], 0, v[28:29]
	v_lshl_add_u64 v[30:31], v[92:93], 0, v[30:31]
	v_lshl_add_u64 v[32:33], v[92:93], 0, v[32:33]
	v_lshl_add_u64 v[34:35], v[92:93], 0, v[34:35]
	v_lshl_add_u64 v[82:83], v[86:87], 1, v[84:85]
	v_lshl_add_u64 v[86:87], v[88:89], 1, v[84:85]
	v_lshl_add_u64 v[84:85], v[90:91], 1, v[84:85]
	v_lshl_add_u64 v[36:37], v[92:93], 0, v[36:37]
	v_lshl_add_u64 v[38:39], v[92:93], 0, v[38:39]
	v_lshl_add_u64 v[40:41], v[92:93], 0, v[40:41]
	v_lshl_add_u64 v[42:43], v[92:93], 0, v[42:43]
	v_lshl_add_u64 v[44:45], v[92:93], 0, v[44:45]
	v_lshl_add_u64 v[46:47], v[92:93], 0, v[46:47]
	v_lshl_add_u64 v[48:49], v[92:93], 0, v[48:49]
	v_lshl_add_u64 v[50:51], v[92:93], 0, v[50:51]
	v_lshl_add_u64 v[52:53], v[92:93], 0, v[52:53]
	v_lshl_add_u64 v[54:55], v[92:93], 0, v[54:55]
	v_lshl_add_u64 v[56:57], v[92:93], 0, v[56:57]
	v_lshl_add_u64 v[58:59], v[92:93], 0, v[58:59]
	v_lshl_add_u64 v[60:61], v[92:93], 0, v[60:61]
	v_lshl_add_u64 v[62:63], v[92:93], 0, v[62:63]
	v_lshl_add_u64 v[64:65], v[92:93], 0, v[64:65]
	v_lshl_add_u64 v[66:67], v[92:93], 0, v[66:67]
	v_lshl_add_u64 v[68:69], v[92:93], 0, v[68:69]
	v_lshl_add_u64 v[70:71], v[92:93], 0, v[70:71]
	v_lshl_add_u64 v[72:73], v[92:93], 0, v[72:73]
	v_lshl_add_u64 v[74:75], v[92:93], 0, v[74:75]
	v_lshl_add_u64 v[76:77], v[92:93], 0, v[76:77]
	v_lshl_add_u64 v[78:79], v[92:93], 0, v[78:79]
	v_lshl_add_u64 v[80:81], v[92:93], 0, v[80:81]
	global_load_dword v17, v[18:19], off nt
	global_load_dword v88, v[20:21], off nt
	global_load_dword v89, v[22:23], off nt
	global_load_dword v90, v[24:25], off nt
	global_load_dword v91, v[26:27], off nt
	global_load_dword v92, v[28:29], off nt
	global_load_dword v93, v[30:31], off nt
	global_load_dword v96, v[32:33], off nt
	global_load_dword v97, v[34:35], off nt
	global_load_dword v98, v[36:37], off nt
	global_load_dword v99, v[38:39], off nt
	global_load_dword v100, v[40:41], off nt
	global_load_dword v101, v[42:43], off nt
	global_load_dword v102, v[44:45], off nt
	global_load_dword v103, v[46:47], off nt
	global_load_dword v18, v[48:49], off nt
	global_load_dword v19, v[50:51], off nt
	global_load_dword v20, v[52:53], off nt
	global_load_dword v21, v[54:55], off nt
	global_load_dword v22, v[56:57], off nt
	global_load_dword v23, v[58:59], off nt
	global_load_dword v24, v[60:61], off nt
	global_load_dword v25, v[62:63], off nt
	global_load_dword v26, v[64:65], off nt
	global_load_dword v27, v[66:67], off nt
	global_load_dword v28, v[68:69], off nt
	global_load_dword v29, v[70:71], off nt
	global_load_dword v30, v[72:73], off nt
	global_load_dword v31, v[74:75], off nt
	global_load_dword v32, v[76:77], off nt
	global_load_dword v33, v[78:79], off nt
	global_load_dword v34, v[80:81], off nt
	s_waitcnt vmcnt(0)
	ds_write2_b32 v9, v17, v88 offset1:66
	ds_write2_b32 v9, v89, v90 offset0:132 offset1:198
	ds_write2_b32 v10, v91, v92 offset0:8 offset1:74
	ds_write2_b32 v10, v93, v96 offset0:140 offset1:206
	ds_write2_b32 v11, v97, v98 offset0:16 offset1:82
	ds_write2_b32 v11, v99, v100 offset0:148 offset1:214
	ds_write2_b32 v12, v101, v102 offset0:24 offset1:90
	ds_write2_b32 v12, v103, v18 offset0:156 offset1:222
	ds_write2_b32 v13, v19, v20 offset0:32 offset1:98
	ds_write2_b32 v13, v21, v22 offset0:164 offset1:230
	ds_write2_b32 v14, v23, v24 offset0:40 offset1:106
	ds_write2_b32 v14, v25, v26 offset0:172 offset1:238
	ds_write2_b32 v15, v27, v28 offset0:48 offset1:114
	ds_write2_b32 v15, v29, v30 offset0:180 offset1:246
	ds_write2_b32 v16, v31, v32 offset0:56 offset1:122
	ds_write2_b32 v16, v33, v34 offset0:188 offset1:254
	s_waitcnt lgkmcnt(0)
	ds_read2_b32 v[18:19], v6 offset1:33
	ds_read2_b32 v[20:21], v6 offset0:66 offset1:99
	ds_read2_b32 v[22:23], v6 offset0:132 offset1:165
	ds_read2_b32 v[24:25], v6 offset0:198 offset1:231
	s_add_i32 s5, s0, 0x200
	s_waitcnt lgkmcnt(3)
	v_bfe_u32 v17, v18, 16, 1
	v_bfe_u32 v26, v19, 16, 1
	s_waitcnt lgkmcnt(2)
	v_bfe_u32 v27, v20, 16, 1
	v_bfe_u32 v28, v21, 16, 1
	s_waitcnt lgkmcnt(1)
	v_bfe_u32 v29, v22, 16, 1
	v_bfe_u32 v30, v23, 16, 1
	s_waitcnt lgkmcnt(0)
	v_bfe_u32 v31, v24, 16, 1
	v_bfe_u32 v32, v25, 16, 1
	v_add3_u32 v17, v18, v17, s2
	v_add3_u32 v18, v19, v26, s2
	v_add3_u32 v19, v20, v27, s2
	v_add3_u32 v20, v21, v28, s2
	v_add3_u32 v21, v22, v29, s2
	v_add3_u32 v22, v23, v30, s2
	v_add3_u32 v23, v24, v31, s2
	v_add3_u32 v24, v25, v32, s2
	v_lshrrev_b32_e32 v17, 16, v17
	v_lshrrev_b32_e32 v19, 16, v19
	v_lshrrev_b32_e32 v21, 16, v21
	v_lshrrev_b32_e32 v23, 16, v23
	v_and_or_b32 v18, v18, s3, v17
	v_and_or_b32 v19, v20, s3, v19
	v_and_or_b32 v20, v22, s3, v21
	v_and_or_b32 v21, v24, s3, v23
	global_store_dwordx4 v[94:95], v[18:21], off sc1
	s_nop 1
	ds_read2_b32 v[18:19], v6 offset0:8 offset1:41
	ds_read2_b32 v[20:21], v6 offset0:74 offset1:107
	ds_read2_b32 v[22:23], v6 offset0:140 offset1:173
	ds_read2_b32 v[24:25], v6 offset0:206 offset1:239
	s_addk_i32 s1, 0x4000
	s_waitcnt lgkmcnt(3)
	v_bfe_u32 v17, v18, 16, 1
	v_bfe_u32 v26, v19, 16, 1
	s_waitcnt lgkmcnt(2)
	v_bfe_u32 v27, v20, 16, 1
	v_bfe_u32 v28, v21, 16, 1
	s_waitcnt lgkmcnt(1)
	v_bfe_u32 v29, v22, 16, 1
	v_bfe_u32 v30, v23, 16, 1
	s_waitcnt lgkmcnt(0)
	v_bfe_u32 v31, v24, 16, 1
	v_bfe_u32 v32, v25, 16, 1
	v_add3_u32 v17, v18, v17, s2
	v_add3_u32 v18, v19, v26, s2
	v_add3_u32 v19, v20, v27, s2
	v_add3_u32 v20, v21, v28, s2
	v_add3_u32 v21, v22, v29, s2
	v_add3_u32 v22, v23, v30, s2
	v_add3_u32 v23, v24, v31, s2
	v_add3_u32 v24, v25, v32, s2
	v_lshrrev_b32_e32 v17, 16, v17
	v_lshrrev_b32_e32 v19, 16, v19
	v_lshrrev_b32_e32 v21, 16, v21
	v_lshrrev_b32_e32 v23, 16, v23
	v_and_or_b32 v18, v18, s3, v17
	v_and_or_b32 v19, v20, s3, v19
	v_and_or_b32 v20, v22, s3, v21
	v_and_or_b32 v21, v24, s3, v23
	global_store_dwordx4 v[82:83], v[18:21], off sc1
	s_nop 1
	ds_read2_b32 v[18:19], v6 offset0:16 offset1:49
	ds_read2_b32 v[20:21], v6 offset0:82 offset1:115
	ds_read2_b32 v[22:23], v6 offset0:148 offset1:181
	ds_read2_b32 v[24:25], v6 offset0:214 offset1:247
	v_add_u32_e32 v8, 0x2c00000, v8
	s_waitcnt lgkmcnt(3)
	v_bfe_u32 v17, v18, 16, 1
	v_bfe_u32 v26, v19, 16, 1
	s_waitcnt lgkmcnt(2)
	v_bfe_u32 v27, v20, 16, 1
	v_bfe_u32 v28, v21, 16, 1
	s_waitcnt lgkmcnt(1)
	v_bfe_u32 v29, v22, 16, 1
	v_bfe_u32 v30, v23, 16, 1
	s_waitcnt lgkmcnt(0)
	v_bfe_u32 v31, v24, 16, 1
	v_bfe_u32 v32, v25, 16, 1
	v_add3_u32 v17, v18, v17, s2
	v_add3_u32 v18, v19, v26, s2
	v_add3_u32 v19, v20, v27, s2
	v_add3_u32 v20, v21, v28, s2
	v_add3_u32 v21, v22, v29, s2
	v_add3_u32 v22, v23, v30, s2
	v_add3_u32 v23, v24, v31, s2
	v_add3_u32 v24, v25, v32, s2
	v_lshrrev_b32_e32 v17, 16, v17
	v_lshrrev_b32_e32 v19, 16, v19
	v_lshrrev_b32_e32 v21, 16, v21
	v_lshrrev_b32_e32 v23, 16, v23
	v_and_or_b32 v18, v18, s3, v17
	v_and_or_b32 v19, v20, s3, v19
	v_and_or_b32 v20, v22, s3, v21
	v_and_or_b32 v21, v24, s3, v23
	global_store_dwordx4 v[86:87], v[18:21], off sc1
	s_nop 1
	ds_read2_b32 v[18:19], v6 offset0:24 offset1:57
	ds_read2_b32 v[20:21], v6 offset0:90 offset1:123
	ds_read2_b32 v[22:23], v6 offset0:156 offset1:189
	ds_read2_b32 v[24:25], v6 offset0:222 offset1:255
	s_cmpk_gt_i32 s0, 0x37f
	s_waitcnt lgkmcnt(3)
	v_bfe_u32 v17, v18, 16, 1
	v_bfe_u32 v26, v19, 16, 1
	s_waitcnt lgkmcnt(2)
	v_bfe_u32 v27, v20, 16, 1
	v_bfe_u32 v28, v21, 16, 1
	s_waitcnt lgkmcnt(1)
	v_bfe_u32 v29, v22, 16, 1
	v_bfe_u32 v30, v23, 16, 1
	s_waitcnt lgkmcnt(0)
	v_bfe_u32 v31, v24, 16, 1
	v_bfe_u32 v32, v25, 16, 1
	v_add3_u32 v17, v18, v17, s2
	v_add3_u32 v18, v19, v26, s2
	v_add3_u32 v19, v20, v27, s2
	v_add3_u32 v20, v21, v28, s2
	v_add3_u32 v21, v22, v29, s2
	v_add3_u32 v22, v23, v30, s2
	v_add3_u32 v23, v24, v31, s2
	v_add3_u32 v24, v25, v32, s2
	v_lshrrev_b32_e32 v17, 16, v17
	v_lshrrev_b32_e32 v19, 16, v19
	v_lshrrev_b32_e32 v21, 16, v21
	v_lshrrev_b32_e32 v23, 16, v23
	v_and_or_b32 v18, v18, s3, v17
	v_and_or_b32 v19, v20, s3, v19
	v_and_or_b32 v20, v22, s3, v21
	v_and_or_b32 v21, v24, s3, v23
	global_store_dwordx4 v[84:85], v[18:21], off sc1
	s_nop 1
	s_waitcnt lgkmcnt(0)
	s_mov_b32 s0, s5
	s_cbranch_scc0 .LBB0_392

.LBB0_776:
	v_add_co_u32_e32 v66, vcc, 0xb000, v10
	global_load_dword v55, v[10:11], off nt
	s_nop 0
	v_addc_co_u32_e32 v67, vcc, 0, v11, vcc
	v_add_co_u32_e32 v68, vcc, 0x16000, v10
	s_nop 1
	v_addc_co_u32_e32 v69, vcc, 0, v11, vcc
	v_add_co_u32_e32 v70, vcc, 0x21000, v10
	s_nop 1
	v_addc_co_u32_e32 v71, vcc, 0, v11, vcc
	v_add_co_u32_e32 v72, vcc, 0x2c000, v10
	s_nop 1
	v_addc_co_u32_e32 v73, vcc, 0, v11, vcc
	v_add_co_u32_e32 v74, vcc, 0x37000, v10
	s_nop 1
	v_addc_co_u32_e32 v75, vcc, 0, v11, vcc
	v_add_co_u32_e32 v76, vcc, 0x42000, v10
	s_nop 1
	v_addc_co_u32_e32 v77, vcc, 0, v11, vcc
	v_add_co_u32_e32 v78, vcc, 0x4d000, v10
	s_nop 1
	v_addc_co_u32_e32 v79, vcc, 0, v11, vcc
	v_add_co_u32_e32 v80, vcc, 0x58000, v10
	s_nop 1
	v_addc_co_u32_e32 v81, vcc, 0, v11, vcc
	global_load_dword v64, v[66:67], off nt
	global_load_dword v62, v[68:69], off nt
	global_load_dword v63, v[70:71], off nt
	global_load_dword v60, v[72:73], off nt
	global_load_dword v61, v[74:75], off nt
	global_load_dword v58, v[76:77], off nt
	global_load_dword v59, v[78:79], off nt
	global_load_dword v56, v[80:81], off nt
	v_add_co_u32_e32 v66, vcc, 0x63000, v10
	s_nop 1
	v_addc_co_u32_e32 v67, vcc, 0, v11, vcc
	v_add_co_u32_e32 v68, vcc, 0x6e000, v10
	s_nop 1
	v_addc_co_u32_e32 v69, vcc, 0, v11, vcc
	v_add_co_u32_e32 v70, vcc, 0x79000, v10
	s_nop 1
	v_addc_co_u32_e32 v71, vcc, 0, v11, vcc
	v_add_co_u32_e32 v72, vcc, 0x84000, v10
	s_nop 1
	v_addc_co_u32_e32 v73, vcc, 0, v11, vcc
	v_add_co_u32_e32 v74, vcc, 0x8f000, v10
	s_nop 1
	v_addc_co_u32_e32 v75, vcc, 0, v11, vcc
	v_add_co_u32_e32 v76, vcc, 0x9a000, v10
	s_nop 1
	v_addc_co_u32_e32 v77, vcc, 0, v11, vcc
	v_add_co_u32_e32 v78, vcc, 0xa5000, v10
	s_nop 1
	v_addc_co_u32_e32 v79, vcc, 0, v11, vcc
	v_add_co_u32_e32 v80, vcc, 0xb0000, v10
	s_nop 1
	v_addc_co_u32_e32 v81, vcc, 0, v11, vcc
	global_load_dword v65, v[66:67], off nt
	global_load_dword v82, v[68:69], off nt
	global_load_dword v83, v[70:71], off nt
	global_load_dword v84, v[72:73], off nt
	global_load_dword v85, v[74:75], off nt
	global_load_dword v86, v[76:77], off nt
	global_load_dword v99, v[78:79], off nt
	global_load_dword v103, v[80:81], off nt
	v_add_co_u32_e32 v66, vcc, 0xbb000, v10
	s_nop 1
	v_addc_co_u32_e32 v67, vcc, 0, v11, vcc
	v_add_co_u32_e32 v68, vcc, 0xc6000, v10
	s_nop 1
	v_addc_co_u32_e32 v69, vcc, 0, v11, vcc
	v_add_co_u32_e32 v70, vcc, 0xd1000, v10
	s_nop 1
	v_addc_co_u32_e32 v71, vcc, 0, v11, vcc
	v_add_co_u32_e32 v72, vcc, 0xdc000, v10
	s_nop 1
	v_addc_co_u32_e32 v73, vcc, 0, v11, vcc
	v_add_co_u32_e32 v74, vcc, 0xe7000, v10
	s_nop 1
	v_addc_co_u32_e32 v75, vcc, 0, v11, vcc
	v_add_co_u32_e32 v76, vcc, 0xf2000, v10
	s_nop 1
	v_addc_co_u32_e32 v77, vcc, 0, v11, vcc
	v_add_co_u32_e32 v78, vcc, 0xfd000, v10
	s_nop 1
	v_addc_co_u32_e32 v79, vcc, 0, v11, vcc
	v_add_co_u32_e32 v80, vcc, 0x108000, v10
	s_nop 1
	v_addc_co_u32_e32 v81, vcc, 0, v11, vcc
	global_load_dword v104, v[66:67], off nt
	global_load_dword v107, v[68:69], off nt
	global_load_dword v108, v[70:71], off nt
	global_load_dword v109, v[72:73], off nt
	global_load_dword v111, v[74:75], off nt
	global_load_dword v112, v[76:77], off nt
	global_load_dword v113, v[78:79], off nt
	global_load_dword v114, v[80:81], off nt
	global_load_dword v115, v[2:3], off nt
	global_load_dword v57, v[2:3], off offset:256 nt
	v_add_co_u32_e32 v66, vcc, 0x113000, v10
	s_nop 1
	v_addc_co_u32_e32 v67, vcc, 0, v11, vcc
	v_add_co_u32_e32 v68, vcc, 0x11e000, v10
	s_nop 1
	v_addc_co_u32_e32 v69, vcc, 0, v11, vcc
	v_add_co_u32_e32 v70, vcc, 0x129000, v10
	s_nop 1
	v_addc_co_u32_e32 v71, vcc, 0, v11, vcc
	v_add_co_u32_e32 v72, vcc, 0x134000, v10
	s_nop 1
	v_addc_co_u32_e32 v73, vcc, 0, v11, vcc
	v_add_co_u32_e32 v74, vcc, 0x13f000, v10
	s_nop 1
	v_addc_co_u32_e32 v75, vcc, 0, v11, vcc
	v_add_co_u32_e32 v76, vcc, 0x14a000, v10
	s_nop 1
	v_addc_co_u32_e32 v77, vcc, 0, v11, vcc
	v_add_co_u32_e32 v78, vcc, 0x155000, v10
	s_nop 1
	v_addc_co_u32_e32 v79, vcc, 0, v11, vcc
	v_add_co_u32_e32 v80, vcc, 0x160000, v10
	s_nop 1
	v_addc_co_u32_e32 v81, vcc, 0, v11, vcc
	global_load_dword v116, v[66:67], off nt
	global_load_dword v117, v[68:69], off nt
	global_load_dword v118, v[70:71], off nt
	global_load_dword v119, v[72:73], off nt
	global_load_dword v120, v[74:75], off nt
	global_load_dword v121, v[76:77], off nt
	global_load_dword v122, v[78:79], off nt
	global_load_dword v123, v[80:81], off nt
	v_add_co_u32_e32 v66, vcc, 0x16b000, v10
	s_nop 1
	v_addc_co_u32_e32 v67, vcc, 0, v11, vcc
	v_add_co_u32_e32 v68, vcc, 0x176000, v10
	s_nop 1
	v_addc_co_u32_e32 v69, vcc, 0, v11, vcc
	v_add_co_u32_e32 v70, vcc, 0x181000, v10
	s_nop 1
	v_addc_co_u32_e32 v71, vcc, 0, v11, vcc
	v_add_co_u32_e32 v72, vcc, 0x18c000, v10
	s_nop 1
	v_addc_co_u32_e32 v73, vcc, 0, v11, vcc
	v_add_co_u32_e32 v74, vcc, 0x197000, v10
	s_nop 1
	v_addc_co_u32_e32 v75, vcc, 0, v11, vcc
	v_add_co_u32_e32 v76, vcc, 0x1a2000, v10
	s_nop 1
	v_addc_co_u32_e32 v77, vcc, 0, v11, vcc
	v_add_co_u32_e32 v78, vcc, 0x1ad000, v10
	s_nop 1
	v_addc_co_u32_e32 v79, vcc, 0, v11, vcc
	v_add_co_u32_e32 v80, vcc, 0x1b8000, v10
	s_nop 1
	v_addc_co_u32_e32 v81, vcc, 0, v11, vcc
	global_load_dword v124, v[66:67], off nt
	global_load_dword v125, v[68:69], off nt
	global_load_dword v126, v[70:71], off nt
	global_load_dword v127, v[72:73], off nt
	global_load_dword v128, v[74:75], off nt
	global_load_dword v129, v[76:77], off nt
	global_load_dword v130, v[78:79], off nt
	global_load_dword v131, v[80:81], off nt
	v_add_co_u32_e32 v66, vcc, 0x1c3000, v10
	s_nop 1
	v_addc_co_u32_e32 v67, vcc, 0, v11, vcc
	v_add_co_u32_e32 v68, vcc, 0x1ce000, v10
	s_nop 1
	v_addc_co_u32_e32 v69, vcc, 0, v11, vcc
	v_add_co_u32_e32 v70, vcc, 0x1d9000, v10
	s_nop 1
	v_addc_co_u32_e32 v71, vcc, 0, v11, vcc
	v_add_co_u32_e32 v72, vcc, 0x1e4000, v10
	s_nop 1
	v_addc_co_u32_e32 v73, vcc, 0, v11, vcc
	v_add_co_u32_e32 v74, vcc, 0x1ef000, v10
	s_nop 1
	v_addc_co_u32_e32 v75, vcc, 0, v11, vcc
	v_add_co_u32_e32 v76, vcc, 0x1fa000, v10
	s_nop 1
	v_addc_co_u32_e32 v77, vcc, 0, v11, vcc
	v_add_co_u32_e32 v78, vcc, 0x205000, v10
	s_nop 1
	v_addc_co_u32_e32 v79, vcc, 0, v11, vcc
	v_add_co_u32_e32 v80, vcc, 0x210000, v10
	s_nop 1
	v_addc_co_u32_e32 v81, vcc, 0, v11, vcc
	global_load_dword v132, v[66:67], off nt
	global_load_dword v133, v[68:69], off nt
	global_load_dword v134, v[70:71], off nt
	global_load_dword v135, v[72:73], off nt
	global_load_dword v136, v[74:75], off nt
	global_load_dword v137, v[76:77], off nt
	global_load_dword v138, v[78:79], off nt
	global_load_dword v139, v[80:81], off nt
	v_add_co_u32_e32 v66, vcc, 0x21b000, v10
	s_nop 1
	v_addc_co_u32_e32 v67, vcc, 0, v11, vcc
	v_add_co_u32_e32 v68, vcc, 0x226000, v10
	s_nop 1
	v_addc_co_u32_e32 v69, vcc, 0, v11, vcc
	v_add_co_u32_e32 v70, vcc, 0x231000, v10
	s_nop 1
	v_addc_co_u32_e32 v71, vcc, 0, v11, vcc
	v_add_co_u32_e32 v72, vcc, 0x23c000, v10
	s_nop 1
	v_addc_co_u32_e32 v73, vcc, 0, v11, vcc
	v_add_co_u32_e32 v74, vcc, 0x247000, v10
	s_nop 1
	v_addc_co_u32_e32 v75, vcc, 0, v11, vcc
	v_add_co_u32_e32 v76, vcc, 0x252000, v10
	s_nop 1
	v_addc_co_u32_e32 v77, vcc, 0, v11, vcc
	v_add_co_u32_e32 v78, vcc, 0x25d000, v10
	s_nop 1
	v_addc_co_u32_e32 v79, vcc, 0, v11, vcc
	v_add_co_u32_e32 v80, vcc, 0x268000, v10
	s_nop 1
	v_addc_co_u32_e32 v81, vcc, 0, v11, vcc
	global_load_dword v140, v[66:67], off nt
	global_load_dword v141, v[68:69], off nt
	global_load_dword v142, v[70:71], off nt
	global_load_dword v143, v[72:73], off nt
	global_load_dword v144, v[74:75], off nt
	global_load_dword v145, v[76:77], off nt
	global_load_dword v146, v[78:79], off nt
	global_load_dword v147, v[80:81], off nt
	v_add_co_u32_e32 v66, vcc, 0x273000, v10
	s_waitcnt vmcnt(33)
	ds_bpermute_b32 v81, v19, v115
	v_addc_co_u32_e32 v67, vcc, 0, v11, vcc
	v_add_co_u32_e32 v68, vcc, 0x27e000, v10
	s_waitcnt lgkmcnt(0)
	v_mul_f32_e32 v89, v64, v81
	v_addc_co_u32_e32 v69, vcc, 0, v11, vcc
	v_add_co_u32_e32 v70, vcc, 0x289000, v10
	ds_bpermute_b32 v64, v24, v115
	s_nop 0
	v_addc_co_u32_e32 v71, vcc, 0, v11, vcc
	v_add_co_u32_e32 v72, vcc, 0x294000, v10
	s_waitcnt lgkmcnt(0)
	v_mul_f32_e32 v92, v58, v64
	v_addc_co_u32_e32 v73, vcc, 0, v11, vcc
	v_add_co_u32_e32 v74, vcc, 0x29f000, v10
	ds_bpermute_b32 v58, v26, v115
	s_nop 0
	v_addc_co_u32_e32 v75, vcc, 0, v11, vcc
	v_add_co_u32_e32 v76, vcc, 0x2aa000, v10
	s_waitcnt lgkmcnt(0)
	v_mul_f32_e32 v98, v56, v58
	v_addc_co_u32_e32 v77, vcc, 0, v11, vcc
	v_add_co_u32_e32 v78, vcc, 0x2b5000, v10
	ds_bpermute_b32 v56, v30, v115
	s_nop 0
	v_addc_co_u32_e32 v79, vcc, 0, v11, vcc
	global_load_dword v148, v[66:67], off nt
	global_load_dword v149, v[68:69], off nt
	global_load_dword v150, v[70:71], off nt
	global_load_dword v151, v[72:73], off nt
	global_load_dword v152, v[74:75], off nt
	global_load_dword v153, v[76:77], off nt
	global_load_dword v154, v[78:79], off nt
	ds_bpermute_b32 v66, v20, v115
	ds_bpermute_b32 v58, v31, v115
	ds_bpermute_b32 v67, v21, v115
	s_waitcnt lgkmcnt(3)
	v_mul_f32_e32 v102, v84, v56
	ds_bpermute_b32 v56, v34, v115
	s_waitcnt lgkmcnt(3)
	v_mul_f32_e32 v88, v62, v66
	ds_bpermute_b32 v62, v22, v115
	ds_bpermute_b32 v66, v25, v115
	s_waitcnt lgkmcnt(4)
	v_mul_f32_e32 v101, v85, v58
	ds_bpermute_b32 v58, v35, v115
	ds_bpermute_b32 v80, v18, v115
	s_waitcnt lgkmcnt(3)
	v_mul_f32_e32 v94, v60, v62
	ds_bpermute_b32 v60, v28, v115
	s_waitcnt lgkmcnt(3)
	v_mul_f32_e32 v91, v59, v66
	ds_bpermute_b32 v59, v27, v115
	v_mul_f32_e32 v87, v63, v67
	ds_bpermute_b32 v63, v23, v115
	s_waitcnt lgkmcnt(2)
	v_mul_f32_e32 v96, v82, v60
	ds_bpermute_b32 v60, v33, v115
	s_waitcnt lgkmcnt(2)
	v_mul_f32_e32 v97, v65, v59
	ds_bpermute_b32 v59, v32, v115
	v_mul_f32_e32 v106, v103, v56
	v_mul_f32_e32 v105, v104, v58
	s_waitcnt lgkmcnt(1)
	v_mul_f32_e32 v99, v99, v60
	ds_bpermute_b32 v60, v37, v115
	s_waitcnt lgkmcnt(1)
	v_mul_f32_e32 v100, v86, v59
	ds_bpermute_b32 v59, v36, v115
	ds_bpermute_b32 v56, v38, v115
	ds_bpermute_b32 v58, v39, v115
	s_waitcnt lgkmcnt(3)
	v_mul_f32_e32 v103, v108, v60
	ds_bpermute_b32 v60, v41, v115
	v_mul_f32_e32 v90, v55, v80
	v_mul_f32_e32 v93, v61, v63
	ds_bpermute_b32 v61, v29, v115
	s_waitcnt lgkmcnt(4)
	v_mul_f32_e32 v104, v107, v59
	ds_bpermute_b32 v59, v40, v115
	v_max3_f32 v55, |v90|, 0, |v89|
	s_waitcnt lgkmcnt(4)
	v_mul_f32_e32 v110, v109, v56
	s_waitcnt lgkmcnt(3)
	v_mul_f32_e32 v109, v111, v58
	ds_bpermute_b32 v56, v42, v115
	ds_bpermute_b32 v58, v43, v115
	v_max3_f32 v55, v55, |v88|, |v87|
	s_waitcnt lgkmcnt(4)
	v_mul_f32_e32 v107, v113, v60
	ds_bpermute_b32 v60, v45, v115
	v_max3_f32 v55, v55, |v94|, |v93|
	v_max3_f32 v55, v55, |v92|, |v91|
	v_max3_f32 v55, v55, |v98|, |v97|
	s_waitcnt lgkmcnt(4)
	v_mul_f32_e32 v95, v83, v61
	s_waitcnt lgkmcnt(3)
	v_mul_f32_e32 v108, v112, v59
	ds_bpermute_b32 v59, v44, v115
	v_max3_f32 v55, v55, |v96|, |v95|
	s_waitcnt lgkmcnt(3)
	v_mul_f32_e32 v114, v114, v56
	s_waitcnt vmcnt(38) lgkmcnt(2)
	v_mul_f32_e32 v113, v116, v58
	ds_bpermute_b32 v56, v46, v115
	ds_bpermute_b32 v58, v47, v115
	v_max3_f32 v55, v55, |v102|, |v101|
	s_waitcnt vmcnt(36) lgkmcnt(3)
	v_mul_f32_e32 v111, v118, v60
	ds_bpermute_b32 v60, v49, v115
	v_max3_f32 v55, v55, |v100|, |v99|
	v_max3_f32 v55, v55, |v106|, |v105|
	v_max3_f32 v55, v55, |v104|, |v103|
	s_waitcnt lgkmcnt(3)
	v_mul_f32_e32 v112, v117, v59
	ds_bpermute_b32 v59, v48, v115
	v_max3_f32 v55, v55, |v110|, |v109|
	s_waitcnt vmcnt(35) lgkmcnt(3)
	v_mul_f32_e32 v118, v119, v56
	s_waitcnt vmcnt(34) lgkmcnt(2)
	v_mul_f32_e32 v117, v120, v58
	ds_bpermute_b32 v56, v18, v57
	ds_bpermute_b32 v58, v19, v57
	v_max3_f32 v55, v55, |v108|, |v107|
	s_waitcnt vmcnt(32) lgkmcnt(3)
	v_mul_f32_e32 v115, v122, v60
	ds_bpermute_b32 v60, v20, v57
	ds_bpermute_b32 v61, v21, v57
	v_max3_f32 v55, v55, |v114|, |v113|
	v_max3_f32 v55, v55, |v112|, |v111|
	v_max3_f32 v55, v55, |v118|, |v117|
	s_waitcnt lgkmcnt(4)
	v_mul_f32_e32 v116, v121, v59
	v_max3_f32 v55, v55, |v116|, |v115|
	s_waitcnt vmcnt(31) lgkmcnt(3)
	v_mul_f32_e32 v59, v123, v56
	s_waitcnt vmcnt(30) lgkmcnt(2)
	v_mul_f32_e32 v58, v124, v58
	v_max3_f32 v62, v55, |v59|, |v58|
	s_waitcnt vmcnt(29) lgkmcnt(1)
	v_mul_f32_e32 v56, v125, v60
	s_waitcnt vmcnt(28) lgkmcnt(0)
	v_mul_f32_e32 v55, v126, v61
	ds_bpermute_b32 v60, v22, v57
	ds_bpermute_b32 v61, v23, v57
	ds_bpermute_b32 v65, v24, v57
	ds_bpermute_b32 v66, v25, v57
	v_max3_f32 v64, v62, |v56|, |v55|
	s_waitcnt vmcnt(27) lgkmcnt(3)
	v_mul_f32_e32 v63, v127, v60
	s_waitcnt vmcnt(26) lgkmcnt(2)
	v_mul_f32_e32 v62, v128, v61
	s_waitcnt vmcnt(25) lgkmcnt(1)
	v_mul_f32_e32 v61, v129, v65
	s_waitcnt vmcnt(24) lgkmcnt(0)
	v_mul_f32_e32 v60, v130, v66
	ds_bpermute_b32 v65, v26, v57
	ds_bpermute_b32 v66, v27, v57
	ds_bpermute_b32 v68, v28, v57
	ds_bpermute_b32 v69, v29, v57
	v_max3_f32 v64, v64, |v63|, |v62|
	v_max3_f32 v64, v64, |v61|, |v60|
	s_waitcnt vmcnt(23) lgkmcnt(3)
	v_mul_f32_e32 v67, v131, v65
	s_waitcnt vmcnt(22) lgkmcnt(2)
	v_mul_f32_e32 v66, v132, v66
	v_max3_f32 v70, v64, |v67|, |v66|
	s_waitcnt vmcnt(21) lgkmcnt(1)
	v_mul_f32_e32 v65, v133, v68
	s_waitcnt vmcnt(20) lgkmcnt(0)
	v_mul_f32_e32 v64, v134, v69
	ds_bpermute_b32 v68, v30, v57
	ds_bpermute_b32 v69, v31, v57
	ds_bpermute_b32 v73, v32, v57
	ds_bpermute_b32 v74, v33, v57
	v_max3_f32 v72, v70, |v65|, |v64|
	s_waitcnt vmcnt(19) lgkmcnt(3)
	v_mul_f32_e32 v71, v135, v68
	s_waitcnt vmcnt(18) lgkmcnt(2)
	v_mul_f32_e32 v70, v136, v69
	s_waitcnt vmcnt(17) lgkmcnt(1)
	v_mul_f32_e32 v69, v137, v73
	s_waitcnt vmcnt(16) lgkmcnt(0)
	v_mul_f32_e32 v68, v138, v74
	ds_bpermute_b32 v73, v34, v57
	ds_bpermute_b32 v74, v35, v57
	ds_bpermute_b32 v76, v36, v57
	ds_bpermute_b32 v77, v37, v57
	v_max3_f32 v72, v72, |v71|, |v70|
	v_max3_f32 v72, v72, |v69|, |v68|
	s_waitcnt vmcnt(15) lgkmcnt(3)
	v_mul_f32_e32 v75, v139, v73
	s_waitcnt vmcnt(14) lgkmcnt(2)
	v_mul_f32_e32 v74, v140, v74
	v_max3_f32 v78, v72, |v75|, |v74|
	s_waitcnt vmcnt(13) lgkmcnt(1)
	v_mul_f32_e32 v73, v141, v76
	s_waitcnt vmcnt(12) lgkmcnt(0)
	v_mul_f32_e32 v72, v142, v77
	ds_bpermute_b32 v76, v38, v57
	ds_bpermute_b32 v77, v39, v57
	ds_bpermute_b32 v81, v40, v57
	ds_bpermute_b32 v82, v41, v57
	v_max3_f32 v80, v78, |v73|, |v72|
	s_waitcnt vmcnt(11) lgkmcnt(3)
	v_mul_f32_e32 v79, v143, v76
	s_waitcnt vmcnt(10) lgkmcnt(2)
	v_mul_f32_e32 v78, v144, v77
	s_waitcnt vmcnt(9) lgkmcnt(1)
	v_mul_f32_e32 v77, v145, v81
	s_waitcnt vmcnt(8) lgkmcnt(0)
	v_mul_f32_e32 v76, v146, v82
	ds_bpermute_b32 v81, v42, v57
	ds_bpermute_b32 v82, v43, v57
	ds_bpermute_b32 v84, v44, v57
	ds_bpermute_b32 v85, v45, v57
	v_max3_f32 v80, v80, |v79|, |v78|
	v_max3_f32 v80, v80, |v77|, |v76|
	s_waitcnt vmcnt(7) lgkmcnt(3)
	v_mul_f32_e32 v83, v147, v81
	s_waitcnt vmcnt(6) lgkmcnt(2)
	v_mul_f32_e32 v82, v148, v82
	v_max3_f32 v86, v80, |v83|, |v82|
	s_waitcnt vmcnt(5) lgkmcnt(1)
	v_mul_f32_e32 v81, v149, v84
	s_waitcnt vmcnt(4) lgkmcnt(0)
	v_mul_f32_e32 v80, v150, v85
	ds_bpermute_b32 v84, v46, v57
	ds_bpermute_b32 v85, v47, v57
	ds_bpermute_b32 v120, v48, v57
	ds_bpermute_b32 v57, v49, v57
	v_max3_f32 v119, v86, |v81|, |v80|
	s_waitcnt vmcnt(3) lgkmcnt(3)
	v_mul_f32_e32 v86, v151, v84
	s_waitcnt vmcnt(2) lgkmcnt(2)
	v_mul_f32_e32 v85, v152, v85
	v_max3_f32 v119, v119, |v86|, |v85|
	s_waitcnt vmcnt(1) lgkmcnt(1)
	v_mul_f32_e32 v84, v153, v120
	s_waitcnt vmcnt(0) lgkmcnt(0)
	v_mul_f32_e32 v57, v154, v57
	v_max3_f32 v119, v119, |v84|, |v57|
	v_mov_b32_e32 v120, v119
	s_nop 1
	v_permlane32_swap_b32_e32 v119, v120
	s_and_saveexec_b64 s[8:9], s[4:5]
	v_max_f32_e32 v119, v119, v119
	v_max_f32_e32 v120, v120, v120
	v_max_f32_e32 v119, v119, v120
	ds_write_b32 v53, v119
	s_or_b64 exec, exec, s[8:9]
	s_addk_i32 s15, 0x80
	s_waitcnt lgkmcnt(0)
	s_barrier
	ds_read2_b32 v[120:121], v50 offset1:32
	ds_read2_b32 v[122:123], v50 offset0:64 offset1:96
	ds_read2_b32 v[124:125], v50 offset0:128 offset1:160
	ds_read2_b32 v[126:127], v50 offset0:192 offset1:224
	s_cmpk_gt_i32 s15, 0x57
	s_cselect_b32 s8, 0xfffff500, 0
	s_waitcnt lgkmcnt(3)
	v_max3_f32 v119, v120, 0, v121
	s_cselect_b32 s9, 0x80, 0
	s_add_i32 s8, s8, s2
	s_waitcnt lgkmcnt(2)
	v_max3_f32 v119, v119, v122, v123
	s_lshl_b32 s8, s8, 1
	s_and_b32 s10, s2, 0x60
	s_waitcnt lgkmcnt(1)
	v_max3_f32 v119, v119, v124, v125
	s_and_b32 s8, s8, 0xffffff00
	s_or_b32 s9, s9, s10
	s_waitcnt lgkmcnt(0)
	v_max3_f32 v119, v119, v126, v127
	s_or_b32 s8, s9, s8
	s_and_saveexec_b64 s[10:11], s[0:1]
	s_cbranch_execz .LBB0_775
	s_ashr_i32 s9, s8, 31
	v_lshl_add_u64 v[120:121], s[8:9], 2, v[4:5]
	v_mul_f32_e32 v122, 0x3c010204, v119
	global_store_dword v[120:121], v122, off sc1
	s_branch .LBB0_775
.LBB0_780:
	s_sub_i32 s0, s14, 50
	s_cmp_lt_u32 s0, 32
	s_cbranch_scc0 .LBB0_786
	s_load_dwordx2 s[6:7], s[22:23], 0x78
	s_lshl_b32 s0, s14, 5
	s_addk_i32 s0, 0xf9c0
	s_mov_b32 s1, 0
	s_lshl_b32 s2, s13, 7
	s_lshl_b64 s[4:5], s[0:1], 2
	s_waitcnt lgkmcnt(0)
	s_add_u32 s6, s6, s4
	v_lshlrev_b32_e32 v4, 2, v17
	s_addc_u32 s7, s7, s5
	v_lshl_or_b32 v2, v14, 12, v4
	v_mov_b32_e32 v3, 0
	s_ashr_i32 s3, s2, 31
	v_lshl_add_u64 v[2:3], s[6:7], 0, v[2:3]
	s_lshl_b64 s[6:7], s[2:3], 12
	v_lshl_add_u64 v[20:21], v[2:3], 0, s[6:7]
	s_or_b32 s6, s2, 2
	s_ashr_i32 s7, s6, 31
	s_lshl_b64 s[6:7], s[6:7], 12
	v_lshl_add_u64 v[22:23], v[2:3], 0, s[6:7]
	s_or_b32 s6, s2, 4
	s_ashr_i32 s7, s6, 31
	s_lshl_b64 s[6:7], s[6:7], 12
	v_lshl_add_u64 v[24:25], v[2:3], 0, s[6:7]
	s_or_b32 s6, s2, 6
	s_ashr_i32 s7, s6, 31
	s_lshl_b64 s[6:7], s[6:7], 12
	v_lshl_add_u64 v[26:27], v[2:3], 0, s[6:7]
	s_or_b32 s6, s2, 8
	s_ashr_i32 s7, s6, 31
	s_lshl_b64 s[6:7], s[6:7], 12
	v_lshl_add_u64 v[28:29], v[2:3], 0, s[6:7]
	s_or_b32 s6, s2, 10
	s_ashr_i32 s7, s6, 31
	s_lshl_b64 s[6:7], s[6:7], 12
	v_lshl_add_u64 v[30:31], v[2:3], 0, s[6:7]
	s_or_b32 s6, s2, 12
	s_ashr_i32 s7, s6, 31
	s_lshl_b64 s[6:7], s[6:7], 12
	v_lshl_add_u64 v[32:33], v[2:3], 0, s[6:7]
	s_or_b32 s6, s2, 14
	s_ashr_i32 s7, s6, 31
	s_lshl_b64 s[6:7], s[6:7], 12
	v_lshl_add_u64 v[34:35], v[2:3], 0, s[6:7]
	s_or_b32 s6, s2, 16
	s_ashr_i32 s7, s6, 31
	s_lshl_b64 s[6:7], s[6:7], 12
	global_load_dword v18, v[20:21], off nt
	global_load_dword v11, v[22:23], off nt
	global_load_dword v10, v[24:25], off nt
	global_load_dword v9, v[26:27], off nt
	global_load_dword v8, v[28:29], off nt
	global_load_dword v7, v[30:31], off nt
	global_load_dword v6, v[32:33], off nt
	global_load_dword v5, v[34:35], off nt
	v_lshl_add_u64 v[20:21], v[2:3], 0, s[6:7]
	s_or_b32 s6, s2, 18
	s_ashr_i32 s7, s6, 31
	s_lshl_b64 s[6:7], s[6:7], 12
	v_lshl_add_u64 v[22:23], v[2:3], 0, s[6:7]
	s_or_b32 s6, s2, 20
	s_ashr_i32 s7, s6, 31
	s_lshl_b64 s[6:7], s[6:7], 12
	v_lshl_add_u64 v[24:25], v[2:3], 0, s[6:7]
	s_or_b32 s6, s2, 22
	s_ashr_i32 s7, s6, 31
	s_lshl_b64 s[6:7], s[6:7], 12
	v_lshl_add_u64 v[36:37], v[2:3], 0, s[6:7]
	s_or_b32 s6, s2, 24
	s_ashr_i32 s7, s6, 31
	s_lshl_b64 s[6:7], s[6:7], 12
	v_lshl_add_u64 v[38:39], v[2:3], 0, s[6:7]
	s_or_b32 s6, s2, 26
	s_ashr_i32 s7, s6, 31
	s_lshl_b64 s[6:7], s[6:7], 12
	v_lshl_add_u64 v[40:41], v[2:3], 0, s[6:7]
	s_or_b32 s6, s2, 28
	s_ashr_i32 s7, s6, 31
	s_lshl_b64 s[6:7], s[6:7], 12
	v_lshl_add_u64 v[42:43], v[2:3], 0, s[6:7]
	s_or_b32 s6, s2, 30
	s_ashr_i32 s7, s6, 31
	s_lshl_b64 s[6:7], s[6:7], 12
	v_lshl_add_u64 v[44:45], v[2:3], 0, s[6:7]
	s_or_b32 s6, s2, 32
	s_ashr_i32 s7, s6, 31
	s_lshl_b64 s[6:7], s[6:7], 12
	global_load_dword v34, v[20:21], off nt
	global_load_dword v33, v[22:23], off nt
	global_load_dword v32, v[24:25], off nt
	global_load_dword v31, v[36:37], off nt
	global_load_dword v30, v[38:39], off nt
	global_load_dword v29, v[40:41], off nt
	global_load_dword v28, v[42:43], off nt
	global_load_dword v27, v[44:45], off nt
	v_lshl_add_u64 v[20:21], v[2:3], 0, s[6:7]
	s_or_b32 s6, s2, 34
	s_ashr_i32 s7, s6, 31
	s_lshl_b64 s[6:7], s[6:7], 12
	v_lshl_add_u64 v[22:23], v[2:3], 0, s[6:7]
	s_or_b32 s6, s2, 36
	s_ashr_i32 s7, s6, 31
	s_lshl_b64 s[6:7], s[6:7], 12
	v_lshl_add_u64 v[24:25], v[2:3], 0, s[6:7]
	s_or_b32 s6, s2, 38
	s_ashr_i32 s7, s6, 31
	s_lshl_b64 s[6:7], s[6:7], 12
	v_lshl_add_u64 v[36:37], v[2:3], 0, s[6:7]
	s_or_b32 s6, s2, 40
	s_ashr_i32 s7, s6, 31
	s_lshl_b64 s[6:7], s[6:7], 12
	v_lshl_add_u64 v[38:39], v[2:3], 0, s[6:7]
	s_or_b32 s6, s2, 42
	s_ashr_i32 s7, s6, 31
	s_lshl_b64 s[6:7], s[6:7], 12
	v_lshl_add_u64 v[40:41], v[2:3], 0, s[6:7]
	s_or_b32 s6, s2, 44
	s_ashr_i32 s7, s6, 31
	s_lshl_b64 s[6:7], s[6:7], 12
	s_waitcnt vmcnt(23)
	v_lshl_add_u64 v[52:53], v[2:3], 0, s[6:7]
	s_or_b32 s6, s2, 46
	s_ashr_i32 s7, s6, 31
	s_lshl_b64 s[6:7], s[6:7], 12
	s_waitcnt vmcnt(20)
	v_lshl_add_u64 v[54:55], v[2:3], 0, s[6:7]
	s_or_b32 s6, s2, 48
	s_ashr_i32 s7, s6, 31
	s_lshl_b64 s[6:7], s[6:7], 12
	global_load_dword v50, v[20:21], off nt
	global_load_dword v49, v[22:23], off nt
	global_load_dword v48, v[24:25], off nt
	global_load_dword v47, v[36:37], off nt
	global_load_dword v46, v[38:39], off nt
	global_load_dword v45, v[40:41], off nt
	global_load_dword v44, v[52:53], off nt
	global_load_dword v43, v[54:55], off nt
	v_lshl_add_u64 v[20:21], v[2:3], 0, s[6:7]
	s_or_b32 s6, s2, 50
	s_ashr_i32 s7, s6, 31
	s_lshl_b64 s[6:7], s[6:7], 12
	v_lshl_add_u64 v[22:23], v[2:3], 0, s[6:7]
	s_or_b32 s6, s2, 52
	s_ashr_i32 s7, s6, 31
	s_lshl_b64 s[6:7], s[6:7], 12
	v_lshl_add_u64 v[24:25], v[2:3], 0, s[6:7]
	s_or_b32 s6, s2, 54
	s_ashr_i32 s7, s6, 31
	s_lshl_b64 s[6:7], s[6:7], 12
	v_lshl_add_u64 v[36:37], v[2:3], 0, s[6:7]
	s_or_b32 s6, s2, 56
	s_ashr_i32 s7, s6, 31
	s_lshl_b64 s[6:7], s[6:7], 12
	v_lshl_add_u64 v[38:39], v[2:3], 0, s[6:7]
	s_or_b32 s6, s2, 58
	s_ashr_i32 s7, s6, 31
	s_lshl_b64 s[6:7], s[6:7], 12
	v_lshl_add_u64 v[40:41], v[2:3], 0, s[6:7]
	s_or_b32 s6, s2, 60
	s_ashr_i32 s7, s6, 31
	s_lshl_b64 s[6:7], s[6:7], 12
	v_lshl_add_u64 v[52:53], v[2:3], 0, s[6:7]
	s_or_b32 s6, s2, 62
	s_ashr_i32 s7, s6, 31
	s_lshl_b64 s[6:7], s[6:7], 12
	v_lshl_add_u64 v[54:55], v[2:3], 0, s[6:7]
	s_or_b32 s6, s2, 64
	s_ashr_i32 s7, s6, 31
	s_lshl_b64 s[6:7], s[6:7], 12
	global_load_dword v66, v[20:21], off nt
	global_load_dword v65, v[22:23], off nt
	global_load_dword v64, v[24:25], off nt
	global_load_dword v63, v[36:37], off nt
	global_load_dword v62, v[38:39], off nt
	global_load_dword v61, v[40:41], off nt
	global_load_dword v60, v[52:53], off nt
	global_load_dword v59, v[54:55], off nt
	v_lshl_add_u64 v[36:37], v[2:3], 0, s[6:7]
	s_or_b32 s6, s2, 0x42
	s_ashr_i32 s7, s6, 31
	s_lshl_b64 s[6:7], s[6:7], 12
	v_lshl_add_u64 v[38:39], v[2:3], 0, s[6:7]
	s_or_b32 s6, s2, 0x44
	s_ashr_i32 s7, s6, 31
	s_lshl_b64 s[6:7], s[6:7], 12
	v_lshl_add_u64 v[40:41], v[2:3], 0, s[6:7]
	s_or_b32 s6, s2, 0x46
	s_ashr_i32 s7, s6, 31
	s_lshl_b64 s[6:7], s[6:7], 12
	v_lshl_add_u64 v[52:53], v[2:3], 0, s[6:7]
	s_or_b32 s6, s2, 0x48
	s_ashr_i32 s7, s6, 31
	s_lshl_b64 s[6:7], s[6:7], 12
	v_lshl_add_u64 v[54:55], v[2:3], 0, s[6:7]
	s_or_b32 s6, s2, 0x4a
	s_ashr_i32 s7, s6, 31
	s_lshl_b64 s[6:7], s[6:7], 12
	v_lshl_add_u64 v[56:57], v[2:3], 0, s[6:7]
	s_or_b32 s6, s2, 0x4c
	s_ashr_i32 s7, s6, 31
	s_lshl_b64 s[6:7], s[6:7], 12
	v_lshl_add_u64 v[68:69], v[2:3], 0, s[6:7]
	s_or_b32 s6, s2, 0x4e
	s_ashr_i32 s7, s6, 31
	s_lshl_b64 s[6:7], s[6:7], 12
	v_lshl_add_u64 v[70:71], v[2:3], 0, s[6:7]
	s_or_b32 s6, s2, 0x50
	s_ashr_i32 s7, s6, 31
	s_lshl_b64 s[6:7], s[6:7], 12
	global_load_dword v26, v[36:37], off nt
	global_load_dword v25, v[38:39], off nt
	global_load_dword v24, v[40:41], off nt
	global_load_dword v23, v[52:53], off nt
	global_load_dword v22, v[54:55], off nt
	global_load_dword v21, v[56:57], off nt
	global_load_dword v20, v[68:69], off nt
	global_load_dword v19, v[70:71], off nt
	v_lshl_add_u64 v[52:53], v[2:3], 0, s[6:7]
	s_or_b32 s6, s2, 0x52
	s_ashr_i32 s7, s6, 31
	s_lshl_b64 s[6:7], s[6:7], 12
	v_lshl_add_u64 v[54:55], v[2:3], 0, s[6:7]
	s_or_b32 s6, s2, 0x54
	s_ashr_i32 s7, s6, 31
	s_lshl_b64 s[6:7], s[6:7], 12
	v_lshl_add_u64 v[56:57], v[2:3], 0, s[6:7]
	s_or_b32 s6, s2, 0x56
	s_ashr_i32 s7, s6, 31
	s_lshl_b64 s[6:7], s[6:7], 12
	v_lshl_add_u64 v[68:69], v[2:3], 0, s[6:7]
	s_or_b32 s6, s2, 0x58
	s_ashr_i32 s7, s6, 31
	s_lshl_b64 s[6:7], s[6:7], 12
	v_lshl_add_u64 v[70:71], v[2:3], 0, s[6:7]
	s_or_b32 s6, s2, 0x5a
	s_ashr_i32 s7, s6, 31
	s_lshl_b64 s[6:7], s[6:7], 12
	v_lshl_add_u64 v[72:73], v[2:3], 0, s[6:7]
	s_or_b32 s6, s2, 0x5c
	s_ashr_i32 s7, s6, 31
	s_lshl_b64 s[6:7], s[6:7], 12
	v_lshl_add_u64 v[74:75], v[2:3], 0, s[6:7]
	s_or_b32 s6, s2, 0x5e
	s_ashr_i32 s7, s6, 31
	s_lshl_b64 s[6:7], s[6:7], 12
	v_lshl_add_u64 v[76:77], v[2:3], 0, s[6:7]
	s_or_b32 s6, s2, 0x60
	s_ashr_i32 s7, s6, 31
	s_lshl_b64 s[6:7], s[6:7], 12
	global_load_dword v42, v[52:53], off nt
	global_load_dword v41, v[54:55], off nt
	global_load_dword v40, v[56:57], off nt
	global_load_dword v39, v[68:69], off nt
	global_load_dword v38, v[70:71], off nt
	global_load_dword v37, v[72:73], off nt
	global_load_dword v36, v[74:75], off nt
	global_load_dword v35, v[76:77], off nt
	v_lshl_add_u64 v[68:69], v[2:3], 0, s[6:7]
	s_or_b32 s6, s2, 0x62
	s_ashr_i32 s7, s6, 31
	s_lshl_b64 s[6:7], s[6:7], 12
	v_lshl_add_u64 v[70:71], v[2:3], 0, s[6:7]
	s_or_b32 s6, s2, 0x64
	s_ashr_i32 s7, s6, 31
	s_lshl_b64 s[6:7], s[6:7], 12
	v_lshl_add_u64 v[72:73], v[2:3], 0, s[6:7]
	s_or_b32 s6, s2, 0x66
	s_ashr_i32 s7, s6, 31
	s_lshl_b64 s[6:7], s[6:7], 12
	v_lshl_add_u64 v[74:75], v[2:3], 0, s[6:7]
	s_or_b32 s6, s2, 0x68
	s_ashr_i32 s7, s6, 31
	s_lshl_b64 s[6:7], s[6:7], 12
	v_lshl_add_u64 v[76:77], v[2:3], 0, s[6:7]
	s_or_b32 s6, s2, 0x6a
	s_ashr_i32 s7, s6, 31
	s_lshl_b64 s[6:7], s[6:7], 12
	v_lshl_add_u64 v[78:79], v[2:3], 0, s[6:7]
	s_or_b32 s6, s2, 0x6c
	s_ashr_i32 s7, s6, 31
	s_lshl_b64 s[6:7], s[6:7], 12
	v_lshl_add_u64 v[80:81], v[2:3], 0, s[6:7]
	s_or_b32 s6, s2, 0x6e
	s_ashr_i32 s7, s6, 31
	s_lshl_b64 s[6:7], s[6:7], 12
	v_lshl_add_u64 v[82:83], v[2:3], 0, s[6:7]
	s_or_b32 s6, s2, 0x70
	s_ashr_i32 s7, s6, 31
	s_lshl_b64 s[6:7], s[6:7], 12
	global_load_dword v58, v[68:69], off nt
	global_load_dword v57, v[70:71], off nt
	global_load_dword v56, v[72:73], off nt
	global_load_dword v55, v[74:75], off nt
	global_load_dword v54, v[76:77], off nt
	global_load_dword v53, v[78:79], off nt
	global_load_dword v52, v[80:81], off nt
	global_load_dword v51, v[82:83], off nt
	v_lshl_add_u64 v[76:77], v[2:3], 0, s[6:7]
	s_or_b32 s6, s2, 0x72
	s_ashr_i32 s7, s6, 31
	s_lshl_b64 s[6:7], s[6:7], 12
	v_lshl_add_u64 v[78:79], v[2:3], 0, s[6:7]
	s_or_b32 s6, s2, 0x74
	s_ashr_i32 s7, s6, 31
	s_lshl_b64 s[6:7], s[6:7], 12
	v_lshl_add_u64 v[80:81], v[2:3], 0, s[6:7]
	s_or_b32 s6, s2, 0x76
	s_ashr_i32 s7, s6, 31
	s_lshl_b64 s[6:7], s[6:7], 12
	v_lshl_add_u64 v[82:83], v[2:3], 0, s[6:7]
	s_or_b32 s6, s2, 0x78
	s_ashr_i32 s7, s6, 31
	s_lshl_b64 s[6:7], s[6:7], 12
	v_lshl_add_u64 v[84:85], v[2:3], 0, s[6:7]
	s_or_b32 s6, s2, 0x7a
	s_ashr_i32 s7, s6, 31
	s_lshl_b64 s[6:7], s[6:7], 12
	v_lshl_add_u64 v[86:87], v[2:3], 0, s[6:7]
	s_or_b32 s6, s2, 0x7c
	s_ashr_i32 s7, s6, 31
	s_lshl_b64 s[6:7], s[6:7], 12
	v_lshl_add_u64 v[88:89], v[2:3], 0, s[6:7]
	s_or_b32 s6, s2, 0x7e
	s_ashr_i32 s7, s6, 31
	s_lshl_b64 s[6:7], s[6:7], 12
	v_lshl_add_u64 v[2:3], v[2:3], 0, s[6:7]
	global_load_dword v74, v[76:77], off nt
	global_load_dword v73, v[78:79], off nt
	global_load_dword v72, v[80:81], off nt
	global_load_dword v71, v[82:83], off nt
	global_load_dword v70, v[84:85], off nt
	global_load_dword v69, v[86:87], off nt
	global_load_dword v68, v[88:89], off nt
	global_load_dword v67, v[2:3], off nt
	s_waitcnt vmcnt(62)
	v_max3_f32 v2, |v18|, 0, |v11|
	s_waitcnt vmcnt(60)
	v_max3_f32 v2, v2, |v10|, |v9|
	s_waitcnt vmcnt(58)
	v_max3_f32 v2, v2, |v8|, |v7|
	s_waitcnt vmcnt(56)
	v_max3_f32 v2, v2, |v6|, |v5|
	s_waitcnt vmcnt(54)
	v_max3_f32 v2, v2, |v34|, |v33|
	s_waitcnt vmcnt(52)
	v_max3_f32 v2, v2, |v32|, |v31|
	s_waitcnt vmcnt(50)
	v_max3_f32 v2, v2, |v30|, |v29|
	s_waitcnt vmcnt(48)
	v_max3_f32 v2, v2, |v28|, |v27|
	s_waitcnt vmcnt(46)
	v_max3_f32 v2, v2, |v50|, |v49|
	s_waitcnt vmcnt(44)
	v_max3_f32 v2, v2, |v48|, |v47|
	s_waitcnt vmcnt(42)
	v_max3_f32 v2, v2, |v46|, |v45|
	s_waitcnt vmcnt(40)
	v_max3_f32 v2, v2, |v44|, |v43|
	s_waitcnt vmcnt(38)
	v_max3_f32 v2, v2, |v66|, |v65|
	s_waitcnt vmcnt(36)
	v_max3_f32 v2, v2, |v64|, |v63|
	s_waitcnt vmcnt(34)
	v_max3_f32 v2, v2, |v62|, |v61|
	s_waitcnt vmcnt(32)
	v_max3_f32 v2, v2, |v60|, |v59|
	s_waitcnt vmcnt(30)
	v_max3_f32 v2, v2, |v26|, |v25|
	s_waitcnt vmcnt(28)
	v_max3_f32 v2, v2, |v24|, |v23|
	s_waitcnt vmcnt(26)
	v_max3_f32 v2, v2, |v22|, |v21|
	s_waitcnt vmcnt(24)
	v_max3_f32 v2, v2, |v20|, |v19|
	s_waitcnt vmcnt(22)
	v_max3_f32 v2, v2, |v42|, |v41|
	s_waitcnt vmcnt(20)
	v_max3_f32 v2, v2, |v40|, |v39|
	s_waitcnt vmcnt(18)
	v_max3_f32 v2, v2, |v38|, |v37|
	s_waitcnt vmcnt(16)
	v_max3_f32 v2, v2, |v36|, |v35|
	v_cmp_gt_u32_e32 vcc, 32, v16
	s_waitcnt vmcnt(14)
	v_max3_f32 v2, v2, |v58|, |v57|
	s_waitcnt vmcnt(12)
	v_max3_f32 v2, v2, |v56|, |v55|
	s_waitcnt vmcnt(10)
	v_max3_f32 v2, v2, |v54|, |v53|
	s_waitcnt vmcnt(8)
	v_max3_f32 v2, v2, |v52|, |v51|
	s_waitcnt vmcnt(6)
	v_max3_f32 v2, v2, |v74|, |v73|
	s_waitcnt vmcnt(4)
	v_max3_f32 v2, v2, |v72|, |v71|
	s_waitcnt vmcnt(2)
	v_max3_f32 v2, v2, |v70|, |v69|
	s_waitcnt vmcnt(0)
	v_max3_f32 v2, v2, |v68|, |v67|
	v_mov_b32_e32 v3, v2
	s_nop 1
	v_permlane32_swap_b32_e32 v2, v3
	s_and_saveexec_b64 s[6:7], vcc
	s_cbranch_execz .LBB0_783
	v_max_f32_e32 v2, v2, v2
	v_max_f32_e32 v3, v3, v3
	s_add_i32 s1, s2, 0
	v_max_f32_e32 v2, v2, v3
	v_lshl_add_u32 v3, v16, 2, s1
	v_add_u32_e32 v3, 0x20000, v3
	ds_write_b32 v3, v2
